# opt33: opt26 + nt (streaming) hint on the bf16 epilogue stores of G1, G3/G4, G7 (H, PROJ, K copies, V^T)
# speedup vs baseline: 1.0101x; 1.0009x over previous
; __device__ __forceinline__ unsigned cvt_pk_bf16(float lo, float hi) { f32x2_t v = {lo, hi}; bf16x2_t b = __builtin_convertvector(v, bf16x2_t); return __builtin_bit_cast(unsigned, b); }
; __device__ __forceinline__ float rstd_of(const float* ss, int row) { return __builtin_amdgcn_rsqf(ss[row] * (1.0f / 1024.0f) + RMS_EPS); }
; __device__ __forceinline__ float sigmoidf_(float v) { return __builtin_amdgcn_rcpf(1.0f + __builtin_amdgcn_exp2f(-v * LOG2E)); }
;     __device__ __forceinline__ void operator()(const Acc& acc, const Unit& u, int wr, int wc, int fr, int fq) const {
;         const int row0 = u.pm * BM + wr * 64 + fr, col0 = u.pn * 128 + wc * 32 + 8 * fq;
; #pragma unroll
;         for (int ai = 0; ai < 2; ++ai)
; #pragma unroll
;             for (int m = 0; m < 4; ++m) {
;                 const int row = row0 + ai * HALF + m * 16; const float rs = rstd_of(ss, row);
;                 float o[8];
; #pragma unroll
;                 for (int n = 0; n < 2; ++n)
; #pragma unroll
;                     for (int e = 0; e < 4; ++e) { const float gv = acc[ai][0][m][n][e] * rs, uv = acc[ai][1][m][n][e] * rs; o[4 * n + e] = gv * sigmoidf_(gv) * uv; }
;                 u32x4 w; w.x = cvt_pk_bf16(o[0], o[1]); w.y = cvt_pk_bf16(o[2], o[3]); w.z = cvt_pk_bf16(o[4], o[5]); w.w = cvt_pk_bf16(o[6], o[7]);
;                 *(u32x4*)(H + (size_t)row * FF + col0) = w;
;             }
.LBB0_217:
	v_lshl_add_u32 v144, s46, 8, v152
	v_ashrrev_i32_e32 v145, 31, v144
	v_lshl_add_u64 v[150:151], v[144:145], 2, s[48:49]
	global_load_dword v145, v[150:151], off
	v_lshl_or_b32 v148, s34, 7, v154
	v_mov_b64_e32 v[146:147], s[20:21]
	v_ashrrev_i32_e32 v149, 31, v148
	v_mad_i64_i32 v[164:165], s[6:7], v144, s33, v[146:147]
	v_lshlrev_b64 v[148:149], 1, v[148:149]
	v_lshl_add_u64 v[164:165], v[164:165], 0, v[148:149]
	s_andn2_b64 vcc, exec, s[4:5]
	s_mov_b64 s[4:5], -1
	s_waitcnt vmcnt(0)
	v_fmamk_f32 v145, v145, 0x3a800000, v158
	v_rsq_f32_e32 v162, v145
	s_nop 0
	v_pk_mul_f32 v[124:125], v[124:125], v[162:163] op_sel_hi:[1,0]
	v_pk_mul_f32 v[126:127], v[126:127], v[162:163] op_sel_hi:[1,0]
	v_pk_mul_f32 v[120:121], v[120:121], v[162:163] op_sel_hi:[1,0]
	v_pk_mul_f32 v[122:123], v[122:123], v[162:163] op_sel_hi:[1,0]
	v_pk_mul_f32 v[116:117], v[116:117], v[162:163] op_sel_hi:[1,0]
	v_pk_mul_f32 v[118:119], v[118:119], v[162:163] op_sel_hi:[1,0]
	v_pk_mul_f32 v[112:113], v[112:113], v[162:163] op_sel_hi:[1,0]
	v_pk_mul_f32 v[114:115], v[114:115], v[162:163] op_sel_hi:[1,0]
	v_mul_f32_e32 v145, 0xbfb8aa3b, v124
	v_mul_f32_e32 v159, 0xbfb8aa3b, v125
	v_mul_f32_e32 v162, 0xbfb8aa3b, v126
	v_mul_f32_e32 v163, 0xbfb8aa3b, v127
	v_mul_f32_e32 v166, 0xbfb8aa3b, v120
	v_mul_f32_e32 v167, 0xbfb8aa3b, v121
	v_mul_f32_e32 v168, 0xbfb8aa3b, v122
	v_mul_f32_e32 v169, 0xbfb8aa3b, v123
	v_exp_f32_e32 v145, v145
	v_exp_f32_e32 v159, v159
	v_exp_f32_e32 v162, v162
	v_exp_f32_e32 v163, v163
	v_exp_f32_e32 v166, v166
	v_exp_f32_e32 v167, v167
	v_exp_f32_e32 v168, v168
	v_exp_f32_e32 v169, v169
	v_add_f32_e32 v145, 1.0, v145
	v_add_f32_e32 v159, 1.0, v159
	v_add_f32_e32 v170, 1.0, v162
	v_add_f32_e32 v171, 1.0, v163
	v_add_f32_e32 v173, 1.0, v166
	v_add_f32_e32 v174, 1.0, v167
	v_add_f32_e32 v178, 1.0, v168
	v_add_f32_e32 v179, 1.0, v169
	v_rcp_f32_e32 v162, v145
	v_rcp_f32_e32 v163, v159
	v_rcp_f32_e32 v166, v170
	v_rcp_f32_e32 v167, v171
	v_rcp_f32_e32 v168, v173
	v_rcp_f32_e32 v169, v174
	v_rcp_f32_e32 v170, v178
	v_rcp_f32_e32 v171, v179
	v_pk_mul_f32 v[124:125], v[124:125], v[162:163]
	v_pk_mul_f32 v[126:127], v[126:127], v[166:167]
	v_pk_mul_f32 v[120:121], v[120:121], v[168:169]
	v_pk_mul_f32 v[122:123], v[122:123], v[170:171]
	v_pk_mul_f32 v[116:117], v[116:117], v[124:125]
	v_pk_mul_f32 v[118:119], v[118:119], v[126:127]
	v_pk_mul_f32 v[120:121], v[112:113], v[120:121]
	v_pk_mul_f32 v[122:123], v[114:115], v[122:123]
	v_cvt_pk_bf16_f32 v112, v116, v117
	v_cvt_pk_bf16_f32 v113, v118, v119
	v_cvt_pk_bf16_f32 v114, v120, v121
	v_cvt_pk_bf16_f32 v115, v122, v123
	global_store_dwordx4 v[164:165], v[112:115], off nt
	global_load_dword v112, v[150:151], off offset:64
	s_nop 0
	v_or_b32_e32 v113, 16, v144
	v_mad_i64_i32 v[114:115], s[6:7], v113, s33, v[146:147]
	v_lshl_add_u64 v[114:115], v[114:115], 0, v[148:149]
	s_waitcnt vmcnt(0)
	v_fmamk_f32 v112, v112, 0x3a800000, v158
	v_rsq_f32_e32 v112, v112
	s_nop 0
	v_pk_mul_f32 v[108:109], v[108:109], v[112:113] op_sel_hi:[1,0]
	v_pk_mul_f32 v[110:111], v[110:111], v[112:113] op_sel_hi:[1,0]
	v_pk_mul_f32 v[104:105], v[104:105], v[112:113] op_sel_hi:[1,0]
	v_pk_mul_f32 v[106:107], v[106:107], v[112:113] op_sel_hi:[1,0]
	v_pk_mul_f32 v[100:101], v[100:101], v[112:113] op_sel_hi:[1,0]
	v_pk_mul_f32 v[102:103], v[102:103], v[112:113] op_sel_hi:[1,0]
	v_pk_mul_f32 v[96:97], v[96:97], v[112:113] op_sel_hi:[1,0]
	v_pk_mul_f32 v[98:99], v[98:99], v[112:113] op_sel_hi:[1,0]
	v_mul_f32_e32 v112, 0xbfb8aa3b, v108
	v_mul_f32_e32 v113, 0xbfb8aa3b, v109
	v_mul_f32_e32 v116, 0xbfb8aa3b, v110
	v_mul_f32_e32 v117, 0xbfb8aa3b, v111
	v_mul_f32_e32 v118, 0xbfb8aa3b, v104
	v_mul_f32_e32 v119, 0xbfb8aa3b, v105
	v_mul_f32_e32 v120, 0xbfb8aa3b, v106
	v_mul_f32_e32 v121, 0xbfb8aa3b, v107
	v_exp_f32_e32 v112, v112
	v_exp_f32_e32 v113, v113
	v_exp_f32_e32 v116, v116
	v_exp_f32_e32 v117, v117
	v_exp_f32_e32 v118, v118
	v_exp_f32_e32 v119, v119
	v_exp_f32_e32 v120, v120
	v_exp_f32_e32 v121, v121
	v_add_f32_e32 v112, 1.0, v112
	v_add_f32_e32 v113, 1.0, v113
	v_add_f32_e32 v116, 1.0, v116
	v_add_f32_e32 v117, 1.0, v117
	v_add_f32_e32 v118, 1.0, v118
	v_add_f32_e32 v119, 1.0, v119
	v_add_f32_e32 v120, 1.0, v120
	v_add_f32_e32 v121, 1.0, v121
	v_rcp_f32_e32 v112, v112
	v_rcp_f32_e32 v113, v113
	v_rcp_f32_e32 v116, v116
	v_rcp_f32_e32 v117, v117
	v_rcp_f32_e32 v118, v118
	v_rcp_f32_e32 v119, v119
	v_rcp_f32_e32 v120, v120
	v_rcp_f32_e32 v121, v121
	v_pk_mul_f32 v[108:109], v[108:109], v[112:113]
	v_pk_mul_f32 v[110:111], v[110:111], v[116:117]
	v_pk_mul_f32 v[104:105], v[104:105], v[118:119]
	v_pk_mul_f32 v[106:107], v[106:107], v[120:121]
	v_pk_mul_f32 v[100:101], v[100:101], v[108:109]
	v_pk_mul_f32 v[102:103], v[102:103], v[110:111]
	v_pk_mul_f32 v[104:105], v[96:97], v[104:105]
	v_pk_mul_f32 v[106:107], v[98:99], v[106:107]
	v_cvt_pk_bf16_f32 v96, v100, v101
	v_cvt_pk_bf16_f32 v97, v102, v103
	v_cvt_pk_bf16_f32 v98, v104, v105
	v_cvt_pk_bf16_f32 v99, v106, v107
	global_store_dwordx4 v[114:115], v[96:99], off nt
	global_load_dword v96, v[150:151], off offset:128
	s_nop 0
	v_or_b32_e32 v97, 32, v144
	v_mad_i64_i32 v[98:99], s[6:7], v97, s33, v[146:147]
	v_lshl_add_u64 v[98:99], v[98:99], 0, v[148:149]
	s_waitcnt vmcnt(0)
; __device__ __forceinline__ unsigned cvt_pk_bf16(float lo, float hi) { f32x2_t v = {lo, hi}; bf16x2_t b = __builtin_convertvector(v, bf16x2_t); return __builtin_bit_cast(unsigned, b); }
; __device__ __forceinline__ float rstd_of(const float* ss, int row) { return __builtin_amdgcn_rsqf(ss[row] * (1.0f / 1024.0f) + RMS_EPS); }
; __device__ __forceinline__ float sigmoidf_(float v) { return __builtin_amdgcn_rcpf(1.0f + __builtin_amdgcn_exp2f(-v * LOG2E)); }
;     __device__ __forceinline__ void operator()(const Acc& acc, const Unit& u, int wr, int wc, int fr, int fq) const {
;         const int row0 = u.pm * BM + wr * 64 + fr, col0 = u.pn * 128 + wc * 32 + 8 * fq;
; #pragma unroll
;         for (int ai = 0; ai < 2; ++ai)
; #pragma unroll
;             for (int m = 0; m < 4; ++m) {
;                 const int row = row0 + ai * HALF + m * 16; const float rs = rstd_of(ss, row);
;                 float o[8];
; #pragma unroll
;                 for (int n = 0; n < 2; ++n)
; #pragma unroll
;                     for (int e = 0; e < 4; ++e) { const float gv = acc[ai][0][m][n][e] * rs, uv = acc[ai][1][m][n][e] * rs; o[4 * n + e] = gv * sigmoidf_(gv) * uv; }
;                 u32x4 w; w.x = cvt_pk_bf16(o[0], o[1]); w.y = cvt_pk_bf16(o[2], o[3]); w.z = cvt_pk_bf16(o[4], o[5]); w.w = cvt_pk_bf16(o[6], o[7]);
;                 *(u32x4*)(H + (size_t)row * FF + col0) = w;
;             }
	v_fmamk_f32 v96, v96, 0x3a800000, v158
	v_rsq_f32_e32 v96, v96
	s_nop 0
	v_pk_mul_f32 v[92:93], v[92:93], v[96:97] op_sel_hi:[1,0]
	v_pk_mul_f32 v[94:95], v[94:95], v[96:97] op_sel_hi:[1,0]
	v_pk_mul_f32 v[88:89], v[88:89], v[96:97] op_sel_hi:[1,0]
	v_pk_mul_f32 v[90:91], v[90:91], v[96:97] op_sel_hi:[1,0]
	v_pk_mul_f32 v[84:85], v[84:85], v[96:97] op_sel_hi:[1,0]
	v_pk_mul_f32 v[86:87], v[86:87], v[96:97] op_sel_hi:[1,0]
	v_pk_mul_f32 v[80:81], v[80:81], v[96:97] op_sel_hi:[1,0]
	v_pk_mul_f32 v[82:83], v[82:83], v[96:97] op_sel_hi:[1,0]
	v_mul_f32_e32 v96, 0xbfb8aa3b, v92
	v_mul_f32_e32 v97, 0xbfb8aa3b, v93
	v_mul_f32_e32 v100, 0xbfb8aa3b, v94
	v_mul_f32_e32 v101, 0xbfb8aa3b, v95
	v_mul_f32_e32 v102, 0xbfb8aa3b, v88
	v_mul_f32_e32 v103, 0xbfb8aa3b, v89
	v_mul_f32_e32 v104, 0xbfb8aa3b, v90
	v_mul_f32_e32 v105, 0xbfb8aa3b, v91
	v_exp_f32_e32 v96, v96
	v_exp_f32_e32 v97, v97
	v_exp_f32_e32 v100, v100
	v_exp_f32_e32 v101, v101
	v_exp_f32_e32 v102, v102
	v_exp_f32_e32 v103, v103
	v_exp_f32_e32 v104, v104
	v_exp_f32_e32 v105, v105
	v_add_f32_e32 v96, 1.0, v96
	v_add_f32_e32 v97, 1.0, v97
	v_add_f32_e32 v100, 1.0, v100
	v_add_f32_e32 v101, 1.0, v101
	v_add_f32_e32 v102, 1.0, v102
	v_add_f32_e32 v103, 1.0, v103
	v_add_f32_e32 v104, 1.0, v104
	v_add_f32_e32 v105, 1.0, v105
	v_rcp_f32_e32 v96, v96
	v_rcp_f32_e32 v97, v97
	v_rcp_f32_e32 v100, v100
	v_rcp_f32_e32 v101, v101
	v_rcp_f32_e32 v102, v102
	v_rcp_f32_e32 v103, v103
	v_rcp_f32_e32 v104, v104
	v_rcp_f32_e32 v105, v105
	v_pk_mul_f32 v[92:93], v[92:93], v[96:97]
	v_pk_mul_f32 v[94:95], v[94:95], v[100:101]
	v_pk_mul_f32 v[88:89], v[88:89], v[102:103]
	v_pk_mul_f32 v[90:91], v[90:91], v[104:105]
	v_pk_mul_f32 v[84:85], v[84:85], v[92:93]
	v_pk_mul_f32 v[86:87], v[86:87], v[94:95]
	v_pk_mul_f32 v[88:89], v[80:81], v[88:89]
	v_pk_mul_f32 v[90:91], v[82:83], v[90:91]
	v_cvt_pk_bf16_f32 v80, v84, v85
	v_cvt_pk_bf16_f32 v81, v86, v87
	v_cvt_pk_bf16_f32 v82, v88, v89
	v_cvt_pk_bf16_f32 v83, v90, v91
	global_store_dwordx4 v[98:99], v[80:83], off nt
	global_load_dword v80, v[150:151], off offset:192
	s_nop 0
	v_or_b32_e32 v81, 48, v144
	v_mad_i64_i32 v[82:83], s[6:7], v81, s33, v[146:147]
	v_lshl_add_u64 v[82:83], v[82:83], 0, v[148:149]
	s_waitcnt vmcnt(0)
	v_fmamk_f32 v80, v80, 0x3a800000, v158
	v_rsq_f32_e32 v80, v80
	s_nop 0
	v_pk_mul_f32 v[76:77], v[76:77], v[80:81] op_sel_hi:[1,0]
	v_pk_mul_f32 v[78:79], v[78:79], v[80:81] op_sel_hi:[1,0]
	v_pk_mul_f32 v[72:73], v[72:73], v[80:81] op_sel_hi:[1,0]
	v_pk_mul_f32 v[74:75], v[74:75], v[80:81] op_sel_hi:[1,0]
	v_pk_mul_f32 v[68:69], v[68:69], v[80:81] op_sel_hi:[1,0]
	v_pk_mul_f32 v[70:71], v[70:71], v[80:81] op_sel_hi:[1,0]
	v_pk_mul_f32 v[64:65], v[64:65], v[80:81] op_sel_hi:[1,0]
	v_pk_mul_f32 v[66:67], v[66:67], v[80:81] op_sel_hi:[1,0]
	v_mul_f32_e32 v80, 0xbfb8aa3b, v76
	v_mul_f32_e32 v81, 0xbfb8aa3b, v77
	v_mul_f32_e32 v84, 0xbfb8aa3b, v78
	v_mul_f32_e32 v85, 0xbfb8aa3b, v79
	v_mul_f32_e32 v86, 0xbfb8aa3b, v72
	v_mul_f32_e32 v87, 0xbfb8aa3b, v73
	v_mul_f32_e32 v88, 0xbfb8aa3b, v74
	v_mul_f32_e32 v89, 0xbfb8aa3b, v75
	v_exp_f32_e32 v80, v80
	v_exp_f32_e32 v81, v81
	v_exp_f32_e32 v84, v84
	v_exp_f32_e32 v85, v85
	v_exp_f32_e32 v86, v86
	v_exp_f32_e32 v87, v87
	v_exp_f32_e32 v88, v88
	v_exp_f32_e32 v89, v89
	v_add_f32_e32 v80, 1.0, v80
	v_add_f32_e32 v81, 1.0, v81
	v_add_f32_e32 v84, 1.0, v84
	v_add_f32_e32 v85, 1.0, v85
	v_add_f32_e32 v86, 1.0, v86
	v_add_f32_e32 v87, 1.0, v87
	v_add_f32_e32 v88, 1.0, v88
	v_add_f32_e32 v89, 1.0, v89
	v_rcp_f32_e32 v80, v80
	v_rcp_f32_e32 v81, v81
	v_rcp_f32_e32 v84, v84
	v_rcp_f32_e32 v85, v85
	v_rcp_f32_e32 v86, v86
	v_rcp_f32_e32 v87, v87
	v_rcp_f32_e32 v88, v88
	v_rcp_f32_e32 v89, v89
	v_pk_mul_f32 v[76:77], v[76:77], v[80:81]
	v_pk_mul_f32 v[78:79], v[78:79], v[84:85]
	v_pk_mul_f32 v[72:73], v[72:73], v[86:87]
	v_pk_mul_f32 v[74:75], v[74:75], v[88:89]
	v_pk_mul_f32 v[68:69], v[68:69], v[76:77]
	v_pk_mul_f32 v[70:71], v[70:71], v[78:79]
	v_pk_mul_f32 v[72:73], v[64:65], v[72:73]
	v_pk_mul_f32 v[74:75], v[66:67], v[74:75]
	v_cvt_pk_bf16_f32 v64, v68, v69
	v_cvt_pk_bf16_f32 v65, v70, v71
	v_cvt_pk_bf16_f32 v66, v72, v73
	v_cvt_pk_bf16_f32 v67, v74, v75
	global_store_dwordx4 v[82:83], v[64:67], off nt
	global_load_dword v64, v[150:151], off offset:512
	s_nop 0
	v_add_u32_e32 v65, 0x80, v144
	v_mad_i64_i32 v[66:67], s[6:7], v65, s33, v[146:147]
	v_lshl_add_u64 v[66:67], v[66:67], 0, v[148:149]
	s_waitcnt vmcnt(0)
	v_fmamk_f32 v64, v64, 0x3a800000, v158
	v_rsq_f32_e32 v64, v64
	s_nop 0
	v_pk_mul_f32 v[60:61], v[60:61], v[64:65] op_sel_hi:[1,0]
	v_pk_mul_f32 v[62:63], v[62:63], v[64:65] op_sel_hi:[1,0]
	v_pk_mul_f32 v[56:57], v[56:57], v[64:65] op_sel_hi:[1,0]
	v_pk_mul_f32 v[58:59], v[58:59], v[64:65] op_sel_hi:[1,0]
	v_pk_mul_f32 v[52:53], v[52:53], v[64:65] op_sel_hi:[1,0]
	v_pk_mul_f32 v[54:55], v[54:55], v[64:65] op_sel_hi:[1,0]
	v_pk_mul_f32 v[48:49], v[48:49], v[64:65] op_sel_hi:[1,0]
	v_pk_mul_f32 v[50:51], v[50:51], v[64:65] op_sel_hi:[1,0]
	v_mul_f32_e32 v64, 0xbfb8aa3b, v60
	v_mul_f32_e32 v65, 0xbfb8aa3b, v61
	v_mul_f32_e32 v68, 0xbfb8aa3b, v62
	v_mul_f32_e32 v69, 0xbfb8aa3b, v63
	v_mul_f32_e32 v70, 0xbfb8aa3b, v56
	v_mul_f32_e32 v71, 0xbfb8aa3b, v57
	v_mul_f32_e32 v72, 0xbfb8aa3b, v58
	v_mul_f32_e32 v73, 0xbfb8aa3b, v59
	v_exp_f32_e32 v64, v64
	v_exp_f32_e32 v65, v65
	v_exp_f32_e32 v68, v68
	v_exp_f32_e32 v69, v69
	v_exp_f32_e32 v70, v70
	v_exp_f32_e32 v71, v71
	v_exp_f32_e32 v72, v72
	v_exp_f32_e32 v73, v73
	v_add_f32_e32 v64, 1.0, v64
	v_add_f32_e32 v65, 1.0, v65
	v_add_f32_e32 v68, 1.0, v68
	v_add_f32_e32 v69, 1.0, v69
	v_add_f32_e32 v70, 1.0, v70
	v_add_f32_e32 v71, 1.0, v71
	v_add_f32_e32 v72, 1.0, v72
	v_add_f32_e32 v73, 1.0, v73
	v_rcp_f32_e32 v64, v64
	v_rcp_f32_e32 v65, v65
	v_rcp_f32_e32 v68, v68
	v_rcp_f32_e32 v69, v69
	v_rcp_f32_e32 v70, v70
	v_rcp_f32_e32 v71, v71
	v_rcp_f32_e32 v72, v72
	v_rcp_f32_e32 v73, v73
	v_pk_mul_f32 v[60:61], v[60:61], v[64:65]
	v_pk_mul_f32 v[62:63], v[62:63], v[68:69]
	v_pk_mul_f32 v[56:57], v[56:57], v[70:71]
	v_pk_mul_f32 v[58:59], v[58:59], v[72:73]
	v_pk_mul_f32 v[52:53], v[52:53], v[60:61]
	v_pk_mul_f32 v[54:55], v[54:55], v[62:63]
	v_pk_mul_f32 v[56:57], v[48:49], v[56:57]
	v_pk_mul_f32 v[58:59], v[50:51], v[58:59]
	v_cvt_pk_bf16_f32 v48, v52, v53
	v_cvt_pk_bf16_f32 v49, v54, v55
	v_cvt_pk_bf16_f32 v50, v56, v57
	v_cvt_pk_bf16_f32 v51, v58, v59
	global_store_dwordx4 v[66:67], v[48:51], off nt
	global_load_dword v48, v[150:151], off offset:576
	s_nop 0
	v_add_u32_e32 v49, 0x90, v144
	v_mad_i64_i32 v[50:51], s[6:7], v49, s33, v[146:147]
	v_lshl_add_u64 v[50:51], v[50:51], 0, v[148:149]
	s_waitcnt vmcnt(0)
; __device__ __forceinline__ unsigned cvt_pk_bf16(float lo, float hi) { f32x2_t v = {lo, hi}; bf16x2_t b = __builtin_convertvector(v, bf16x2_t); return __builtin_bit_cast(unsigned, b); }
; __device__ __forceinline__ float rstd_of(const float* ss, int row) { return __builtin_amdgcn_rsqf(ss[row] * (1.0f / 1024.0f) + RMS_EPS); }
; __device__ __forceinline__ float sigmoidf_(float v) { return __builtin_amdgcn_rcpf(1.0f + __builtin_amdgcn_exp2f(-v * LOG2E)); }
;     __device__ __forceinline__ void operator()(const Acc& acc, const Unit& u, int wr, int wc, int fr, int fq) const {
;     ...
;                 const int row = row0 + ai * HALF + m * 16; const float rs = rstd_of(ss, row);
;                 float o[8];
; #pragma unroll
;                 for (int n = 0; n < 2; ++n)
; #pragma unroll
;                     for (int e = 0; e < 4; ++e) { const float gv = acc[ai][0][m][n][e] * rs, uv = acc[ai][1][m][n][e] * rs; o[4 * n + e] = gv * sigmoidf_(gv) * uv; }
;                 u32x4 w; w.x = cvt_pk_bf16(o[0], o[1]); w.y = cvt_pk_bf16(o[2], o[3]); w.z = cvt_pk_bf16(o[4], o[5]); w.w = cvt_pk_bf16(o[6], o[7]);
;                 *(u32x4*)(H + (size_t)row * FF + col0) = w;
	v_fmamk_f32 v48, v48, 0x3a800000, v158
	v_rsq_f32_e32 v48, v48
	s_nop 0
	v_pk_mul_f32 v[44:45], v[44:45], v[48:49] op_sel_hi:[1,0]
	v_pk_mul_f32 v[46:47], v[46:47], v[48:49] op_sel_hi:[1,0]
	v_pk_mul_f32 v[40:41], v[40:41], v[48:49] op_sel_hi:[1,0]
	v_pk_mul_f32 v[42:43], v[42:43], v[48:49] op_sel_hi:[1,0]
	v_pk_mul_f32 v[36:37], v[36:37], v[48:49] op_sel_hi:[1,0]
	v_pk_mul_f32 v[38:39], v[38:39], v[48:49] op_sel_hi:[1,0]
	v_pk_mul_f32 v[32:33], v[32:33], v[48:49] op_sel_hi:[1,0]
	v_pk_mul_f32 v[34:35], v[34:35], v[48:49] op_sel_hi:[1,0]
	v_mul_f32_e32 v48, 0xbfb8aa3b, v44
	v_mul_f32_e32 v49, 0xbfb8aa3b, v45
	v_mul_f32_e32 v52, 0xbfb8aa3b, v46
	v_mul_f32_e32 v53, 0xbfb8aa3b, v47
	v_mul_f32_e32 v54, 0xbfb8aa3b, v40
	v_mul_f32_e32 v55, 0xbfb8aa3b, v41
	v_mul_f32_e32 v56, 0xbfb8aa3b, v42
	v_mul_f32_e32 v57, 0xbfb8aa3b, v43
	v_exp_f32_e32 v48, v48
	v_exp_f32_e32 v49, v49
	v_exp_f32_e32 v52, v52
	v_exp_f32_e32 v53, v53
	v_exp_f32_e32 v54, v54
	v_exp_f32_e32 v55, v55
	v_exp_f32_e32 v56, v56
	v_exp_f32_e32 v57, v57
	v_add_f32_e32 v48, 1.0, v48
	v_add_f32_e32 v49, 1.0, v49
	v_add_f32_e32 v52, 1.0, v52
	v_add_f32_e32 v53, 1.0, v53
	v_add_f32_e32 v54, 1.0, v54
	v_add_f32_e32 v55, 1.0, v55
	v_add_f32_e32 v56, 1.0, v56
	v_add_f32_e32 v57, 1.0, v57
	v_rcp_f32_e32 v48, v48
	v_rcp_f32_e32 v49, v49
	v_rcp_f32_e32 v52, v52
	v_rcp_f32_e32 v53, v53
	v_rcp_f32_e32 v54, v54
	v_rcp_f32_e32 v55, v55
	v_rcp_f32_e32 v56, v56
	v_rcp_f32_e32 v57, v57
	v_pk_mul_f32 v[44:45], v[44:45], v[48:49]
	v_pk_mul_f32 v[46:47], v[46:47], v[52:53]
	v_pk_mul_f32 v[40:41], v[40:41], v[54:55]
	v_pk_mul_f32 v[42:43], v[42:43], v[56:57]
	v_pk_mul_f32 v[36:37], v[36:37], v[44:45]
	v_pk_mul_f32 v[38:39], v[38:39], v[46:47]
	v_pk_mul_f32 v[40:41], v[32:33], v[40:41]
	v_pk_mul_f32 v[42:43], v[34:35], v[42:43]
	v_cvt_pk_bf16_f32 v32, v36, v37
	v_cvt_pk_bf16_f32 v33, v38, v39
	v_cvt_pk_bf16_f32 v34, v40, v41
	v_cvt_pk_bf16_f32 v35, v42, v43
	global_store_dwordx4 v[50:51], v[32:35], off nt
	global_load_dword v32, v[150:151], off offset:640
	s_nop 0
	v_add_u32_e32 v33, 0xa0, v144
	v_mad_i64_i32 v[34:35], s[6:7], v33, s33, v[146:147]
	v_lshl_add_u64 v[34:35], v[34:35], 0, v[148:149]
	s_waitcnt vmcnt(0)
	v_fmamk_f32 v32, v32, 0x3a800000, v158
	v_rsq_f32_e32 v32, v32
	s_nop 0
	v_pk_mul_f32 v[28:29], v[28:29], v[32:33] op_sel_hi:[1,0]
	v_pk_mul_f32 v[30:31], v[30:31], v[32:33] op_sel_hi:[1,0]
	v_pk_mul_f32 v[24:25], v[24:25], v[32:33] op_sel_hi:[1,0]
	v_pk_mul_f32 v[26:27], v[26:27], v[32:33] op_sel_hi:[1,0]
	v_pk_mul_f32 v[20:21], v[20:21], v[32:33] op_sel_hi:[1,0]
	v_pk_mul_f32 v[22:23], v[22:23], v[32:33] op_sel_hi:[1,0]
	v_pk_mul_f32 v[16:17], v[16:17], v[32:33] op_sel_hi:[1,0]
	v_pk_mul_f32 v[18:19], v[18:19], v[32:33] op_sel_hi:[1,0]
	v_mul_f32_e32 v32, 0xbfb8aa3b, v28
	v_mul_f32_e32 v33, 0xbfb8aa3b, v29
	v_mul_f32_e32 v36, 0xbfb8aa3b, v30
	v_mul_f32_e32 v37, 0xbfb8aa3b, v31
	v_mul_f32_e32 v38, 0xbfb8aa3b, v24
	v_mul_f32_e32 v39, 0xbfb8aa3b, v25
	v_mul_f32_e32 v40, 0xbfb8aa3b, v26
	v_mul_f32_e32 v41, 0xbfb8aa3b, v27
	v_exp_f32_e32 v32, v32
	v_exp_f32_e32 v33, v33
	v_exp_f32_e32 v36, v36
	v_exp_f32_e32 v37, v37
	v_exp_f32_e32 v38, v38
	v_exp_f32_e32 v39, v39
	v_exp_f32_e32 v40, v40
	v_exp_f32_e32 v41, v41
	v_add_f32_e32 v32, 1.0, v32
	v_add_f32_e32 v33, 1.0, v33
	v_add_f32_e32 v36, 1.0, v36
	v_add_f32_e32 v37, 1.0, v37
	v_add_f32_e32 v38, 1.0, v38
	v_add_f32_e32 v39, 1.0, v39
	v_add_f32_e32 v40, 1.0, v40
	v_add_f32_e32 v41, 1.0, v41
	v_rcp_f32_e32 v32, v32
	v_rcp_f32_e32 v33, v33
	v_rcp_f32_e32 v36, v36
	v_rcp_f32_e32 v37, v37
	v_rcp_f32_e32 v38, v38
	v_rcp_f32_e32 v39, v39
	v_rcp_f32_e32 v40, v40
	v_rcp_f32_e32 v41, v41
	v_pk_mul_f32 v[28:29], v[28:29], v[32:33]
	v_pk_mul_f32 v[30:31], v[30:31], v[36:37]
	v_pk_mul_f32 v[24:25], v[24:25], v[38:39]
	v_pk_mul_f32 v[26:27], v[26:27], v[40:41]
	v_pk_mul_f32 v[20:21], v[20:21], v[28:29]
	v_pk_mul_f32 v[22:23], v[22:23], v[30:31]
	v_pk_mul_f32 v[24:25], v[16:17], v[24:25]
	v_pk_mul_f32 v[26:27], v[18:19], v[26:27]
	v_cvt_pk_bf16_f32 v16, v20, v21
	v_cvt_pk_bf16_f32 v17, v22, v23
	v_cvt_pk_bf16_f32 v18, v24, v25
	v_cvt_pk_bf16_f32 v19, v26, v27
	global_store_dwordx4 v[34:35], v[16:19], off nt
	global_load_dword v16, v[150:151], off offset:704
	s_nop 0
	v_add_u32_e32 v17, 0xb0, v144
	v_mad_i64_i32 v[18:19], s[6:7], v17, s33, v[146:147]
	v_lshl_add_u64 v[18:19], v[18:19], 0, v[148:149]
	s_waitcnt vmcnt(0)
	v_fmamk_f32 v16, v16, 0x3a800000, v158
	v_rsq_f32_e32 v16, v16
	s_nop 0
	v_pk_mul_f32 v[12:13], v[12:13], v[16:17] op_sel_hi:[1,0]
	v_pk_mul_f32 v[14:15], v[14:15], v[16:17] op_sel_hi:[1,0]
	v_pk_mul_f32 v[8:9], v[8:9], v[16:17] op_sel_hi:[1,0]
	v_pk_mul_f32 v[10:11], v[10:11], v[16:17] op_sel_hi:[1,0]
	v_pk_mul_f32 v[4:5], v[4:5], v[16:17] op_sel_hi:[1,0]
	v_pk_mul_f32 v[6:7], v[6:7], v[16:17] op_sel_hi:[1,0]
	v_pk_mul_f32 v[0:1], v[0:1], v[16:17] op_sel_hi:[1,0]
	v_pk_mul_f32 v[2:3], v[2:3], v[16:17] op_sel_hi:[1,0]
	v_mul_f32_e32 v16, 0xbfb8aa3b, v12
	v_mul_f32_e32 v17, 0xbfb8aa3b, v13
	v_mul_f32_e32 v20, 0xbfb8aa3b, v14
	v_mul_f32_e32 v21, 0xbfb8aa3b, v15
	v_mul_f32_e32 v22, 0xbfb8aa3b, v8
	v_mul_f32_e32 v23, 0xbfb8aa3b, v9
	v_mul_f32_e32 v24, 0xbfb8aa3b, v10
	v_mul_f32_e32 v25, 0xbfb8aa3b, v11
	v_exp_f32_e32 v16, v16
	v_exp_f32_e32 v17, v17
	v_exp_f32_e32 v20, v20
	v_exp_f32_e32 v21, v21
	v_exp_f32_e32 v22, v22
	v_exp_f32_e32 v23, v23
	v_exp_f32_e32 v24, v24
	v_exp_f32_e32 v25, v25
	v_add_f32_e32 v16, 1.0, v16
	v_add_f32_e32 v17, 1.0, v17
	v_add_f32_e32 v20, 1.0, v20
	v_add_f32_e32 v21, 1.0, v21
	v_add_f32_e32 v22, 1.0, v22
	v_add_f32_e32 v23, 1.0, v23
	v_add_f32_e32 v24, 1.0, v24
	v_add_f32_e32 v25, 1.0, v25
	v_rcp_f32_e32 v16, v16
	v_rcp_f32_e32 v17, v17
	v_rcp_f32_e32 v20, v20
	v_rcp_f32_e32 v21, v21
	v_rcp_f32_e32 v22, v22
	v_rcp_f32_e32 v23, v23
	v_rcp_f32_e32 v24, v24
	v_rcp_f32_e32 v25, v25
	v_pk_mul_f32 v[12:13], v[12:13], v[16:17]
	v_pk_mul_f32 v[14:15], v[14:15], v[20:21]
	v_pk_mul_f32 v[8:9], v[8:9], v[22:23]
	v_pk_mul_f32 v[10:11], v[10:11], v[24:25]
	v_pk_mul_f32 v[4:5], v[4:5], v[12:13]
	v_pk_mul_f32 v[6:7], v[6:7], v[14:15]
	v_pk_mul_f32 v[8:9], v[0:1], v[8:9]
	v_pk_mul_f32 v[10:11], v[2:3], v[10:11]
	v_cvt_pk_bf16_f32 v0, v4, v5
	v_cvt_pk_bf16_f32 v1, v6, v7
	v_cvt_pk_bf16_f32 v2, v8, v9
	v_cvt_pk_bf16_f32 v3, v10, v11
	global_store_dwordx4 v[18:19], v[0:3], off nt
	s_cbranch_vccnz .LBB0_210
	s_andn2_b64 vcc, exec, s[0:1]
	s_cbranch_vccnz .LBB0_209
	s_barrier
	s_branch .LBB0_209

; __device__ __forceinline__ unsigned cvt_pk_bf16(float lo, float hi) { f32x2_t v = {lo, hi}; bf16x2_t b = __builtin_convertvector(v, bf16x2_t); return __builtin_bit_cast(unsigned, b); }
; __device__ __forceinline__ float rstd_of(const float* ss, int row) { return __builtin_amdgcn_rsqf(ss[row] * (1.0f / 1024.0f) + RMS_EPS); }
; __device__ __forceinline__ float sigmoidf_(float v) { return __builtin_amdgcn_rcpf(1.0f + __builtin_amdgcn_exp2f(-v * LOG2E)); }
;     __device__ __forceinline__ void operator()(const Acc& acc, const Unit& u, int wr, int wc, int fr, int fq) const {
;     ...
;                 const int row = row0 + ai * HALF + m * 16; const float rs = rstd_of(ss, row) * sc;
;                 const int b = row >> 11, t = row & (SEQ - 1);
; #pragma unroll
;                 for (int bj = 0; bj < 2; ++bj) {
;                     float o[8];
; #pragma unroll
;                     for (int n = 0; n < 2; ++n)
; #pragma unroll
;                         for (int e = 0; e < 4; ++e) { float v = acc[ai][bj][m][n][e] * rs; if (isg) v = sigmoidf_(v + bv[bj][4 * n + e]); o[4 * n + e] = v; }
;                     u32x4 w; w.x = cvt_pk_bf16(o[0], o[1]); w.y = cvt_pk_bf16(o[2], o[3]); w.z = cvt_pk_bf16(o[4], o[5]); w.w = cvt_pk_bf16(o[6], o[7]);
;                     bf16_t* dst;
;                     if (tile < 4) dst = P + (size_t)row * PP + C_DQ + tile * BM + bj * HALF + cc;
;                     else if (tile < 8) dst = KD + ((size_t)((b * 8 + (tile - 4) * 2 + bj) * SEQ + t)) * 128 + cc;
;                     else if (tile < 12) dst = P + (size_t)row * PP + C_SQ + (tile - 8) * BM + bj * HALF + cc;
;                     else if (tile == 12) { const int ccf = bj * HALF + cc; dst = KS + ((size_t)((b * 4 + (ccf >> 6)) * SEQ + t)) * 64 + (ccf & 63); }
;                     else dst = P + (size_t)row * PP + C_GA + (tile - 13) * BM + bj * HALF + cc;
;                     *(u32x4*)dst = w;
.LBB0_450:
	s_and_b32 s6, s14, 0x7ffffffc
	s_waitcnt vmcnt(0)
	v_fmamk_f32 v157, v195, 0x3a800000, v170
	s_cmp_eq_u32 s6, 8
	v_rsq_f32_e32 v157, v157
	s_cselect_b64 s[6:7], -1, 0
	s_or_b64 vcc, s[96:97], s[6:7]
	v_cndmask_b32_e32 v153, 1.0, v173, vcc
	v_mul_f32_e32 v157, v153, v157
	v_mul_f32_e32 v179, v124, v157
	v_fma_f32 v124, v124, v157, v187
	v_mul_f32_e32 v124, 0xbfb8aa3b, v124
	v_exp_f32_e32 v124, v124
	v_readlane_b32 s70, v254, 54
	s_mov_b64 s[6:7], -1
	s_andn2_b64 vcc, exec, s[12:13]
	v_add_f32_e32 v124, 1.0, v124
	v_rcp_f32_e32 v124, v124
	v_readlane_b32 s69, v254, 53
	v_readlane_b32 s71, v254, 55
	v_cndmask_b32_e64 v124, v179, v124, s[10:11]
	v_mul_f32_e32 v179, v125, v157
	v_fma_f32 v125, v125, v157, v186
	v_mul_f32_e32 v125, 0xbfb8aa3b, v125
	v_exp_f32_e32 v125, v125
	s_nop 0
	v_add_f32_e32 v125, 1.0, v125
	v_rcp_f32_e32 v125, v125
	s_nop 0
	v_cndmask_b32_e64 v125, v179, v125, s[10:11]
	v_mul_f32_e32 v179, v126, v157
	v_fma_f32 v126, v126, v157, v191
	v_mul_f32_e32 v126, 0xbfb8aa3b, v126
	v_exp_f32_e32 v126, v126
	s_nop 0
	v_add_f32_e32 v126, 1.0, v126
	v_rcp_f32_e32 v126, v126
	s_nop 0
	v_cndmask_b32_e64 v126, v179, v126, s[10:11]
	v_mul_f32_e32 v179, v127, v157
	v_fma_f32 v127, v127, v157, v188
	v_mul_f32_e32 v127, 0xbfb8aa3b, v127
	v_exp_f32_e32 v127, v127
	s_nop 0
	v_add_f32_e32 v127, 1.0, v127
	v_rcp_f32_e32 v127, v127
	s_nop 0
	v_cndmask_b32_e64 v127, v179, v127, s[10:11]
	v_mul_f32_e32 v179, v120, v157
	v_fma_f32 v120, v120, v157, v192
	v_mul_f32_e32 v120, 0xbfb8aa3b, v120
	v_exp_f32_e32 v120, v120
	s_nop 0
	v_add_f32_e32 v120, 1.0, v120
	v_rcp_f32_e32 v120, v120
	s_nop 0
	v_cndmask_b32_e64 v179, v179, v120, s[10:11]
	v_mul_f32_e32 v120, v121, v157
	v_fma_f32 v121, v121, v157, v189
	v_mul_f32_e32 v121, 0xbfb8aa3b, v121
	v_exp_f32_e32 v121, v121
	s_nop 0
	v_add_f32_e32 v121, 1.0, v121
	v_rcp_f32_e32 v121, v121
	s_nop 0
	v_cndmask_b32_e64 v195, v120, v121, s[10:11]
	v_fma_f32 v121, v122, v157, v193
	v_mul_f32_e32 v121, 0xbfb8aa3b, v121
	v_exp_f32_e32 v121, v121
	v_mul_f32_e32 v120, v122, v157
	v_cvt_pk_bf16_f32 v122, v179, v195
	v_add_f32_e32 v121, 1.0, v121
	v_rcp_f32_e32 v121, v121
	s_nop 0
	v_cndmask_b32_e64 v196, v120, v121, s[10:11]
	v_fma_f32 v121, v123, v157, v190
	v_mul_f32_e32 v121, 0xbfb8aa3b, v121
	v_exp_f32_e32 v121, v121
	v_mul_f32_e32 v120, v123, v157
	v_add_f32_e32 v121, 1.0, v121
	v_rcp_f32_e32 v121, v121
	s_nop 0
	v_cndmask_b32_e64 v123, v120, v121, s[10:11]
	v_cvt_pk_bf16_f32 v120, v124, v125
	v_cvt_pk_bf16_f32 v121, v126, v127
	v_cvt_pk_bf16_f32 v123, v196, v123
	global_store_dwordx4 v[164:165], v[120:123], off nt
	s_nop 1
	v_cndmask_b32_e64 v120, 0, 1, s[12:13]
	v_cmp_ne_u32_e64 s[14:15], 1, v120
	v_cndmask_b32_e64 v120, 0, 1, s[94:95]
	v_cmp_ne_u32_e64 s[12:13], 1, v120
	s_cbranch_vccnz .LBB0_464
	s_and_b64 vcc, exec, s[12:13]
	s_cbranch_vccnz .LBB0_461
	s_andn2_b64 vcc, exec, s[90:91]
	s_cbranch_vccnz .LBB0_458
	s_andn2_b64 vcc, exec, s[88:89]
	s_cbranch_vccnz .LBB0_455
	v_lshl_add_u64 v[120:121], s[0:1], 1, v[162:163]
	v_lshl_add_u64 v[120:121], v[120:121], 0, v[136:137]
	v_lshl_add_u64 v[120:121], v[120:121], 0, s[36:37]
	s_mov_b64 s[6:7], 0

; __device__ __forceinline__ unsigned cvt_pk_bf16(float lo, float hi) { f32x2_t v = {lo, hi}; bf16x2_t b = __builtin_convertvector(v, bf16x2_t); return __builtin_bit_cast(unsigned, b); }
; __device__ __forceinline__ float rstd_of(const float* ss, int row) { return __builtin_amdgcn_rsqf(ss[row] * (1.0f / 1024.0f) + RMS_EPS); }
; __device__ __forceinline__ float sigmoidf_(float v) { return __builtin_amdgcn_rcpf(1.0f + __builtin_amdgcn_exp2f(-v * LOG2E)); }
;     __device__ __forceinline__ void operator()(const Acc& acc, const Unit& u, int wr, int wc, int fr, int fq) const {
;     ...
;                 const int row = row0 + ai * HALF + m * 16; const float rs = rstd_of(ss, row) * sc;
;                 const int b = row >> 11, t = row & (SEQ - 1);
; #pragma unroll
;                 for (int bj = 0; bj < 2; ++bj) {
;                     float o[8];
; #pragma unroll
;                     for (int n = 0; n < 2; ++n)
; #pragma unroll
;                         for (int e = 0; e < 4; ++e) { float v = acc[ai][bj][m][n][e] * rs; if (isg) v = sigmoidf_(v + bv[bj][4 * n + e]); o[4 * n + e] = v; }
;                     u32x4 w; w.x = cvt_pk_bf16(o[0], o[1]); w.y = cvt_pk_bf16(o[2], o[3]); w.z = cvt_pk_bf16(o[4], o[5]); w.w = cvt_pk_bf16(o[6], o[7]);
;                     bf16_t* dst;
;                     if (tile < 4) dst = P + (size_t)row * PP + C_DQ + tile * BM + bj * HALF + cc;
;                     else if (tile < 8) dst = KD + ((size_t)((b * 8 + (tile - 4) * 2 + bj) * SEQ + t)) * 128 + cc;
;                     else if (tile < 12) dst = P + (size_t)row * PP + C_SQ + (tile - 8) * BM + bj * HALF + cc;
;                     else if (tile == 12) { const int ccf = bj * HALF + cc; dst = KS + ((size_t)((b * 4 + (ccf >> 6)) * SEQ + t)) * 64 + (ccf & 63); }
;                     else dst = P + (size_t)row * PP + C_GA + (tile - 13) * BM + bj * HALF + cc;
;                     *(u32x4*)dst = w;
.LBB0_466:
	v_mul_f32_e32 v122, v116, v157
	v_fma_f32 v116, v116, v157, v181
	v_mul_f32_e32 v116, 0xbfb8aa3b, v116
	v_exp_f32_e32 v116, v116
	s_movk_i32 s6, 0x7df
	s_mov_b64 s[94:95], -1
	s_and_b64 vcc, exec, s[14:15]
	v_add_f32_e32 v116, 1.0, v116
	v_rcp_f32_e32 v116, v116
	s_nop 0
	v_cndmask_b32_e64 v116, v122, v116, s[10:11]
	v_mul_f32_e32 v122, v117, v157
	v_fma_f32 v117, v117, v157, v174
	v_mul_f32_e32 v117, 0xbfb8aa3b, v117
	v_exp_f32_e32 v117, v117
	s_nop 0
	v_add_f32_e32 v117, 1.0, v117
	v_rcp_f32_e32 v117, v117
	s_nop 0
	v_cndmask_b32_e64 v117, v122, v117, s[10:11]
	v_mul_f32_e32 v122, v118, v157
	v_fma_f32 v118, v118, v157, v183
	v_mul_f32_e32 v118, 0xbfb8aa3b, v118
	v_exp_f32_e32 v118, v118
	s_nop 0
	v_add_f32_e32 v118, 1.0, v118
	v_rcp_f32_e32 v118, v118
	s_nop 0
	v_cndmask_b32_e64 v118, v122, v118, s[10:11]
	v_mul_f32_e32 v122, v119, v157
	v_fma_f32 v119, v119, v157, v178
	v_mul_f32_e32 v119, 0xbfb8aa3b, v119
	v_exp_f32_e32 v119, v119
	s_nop 0
	v_add_f32_e32 v119, 1.0, v119
	v_rcp_f32_e32 v119, v119
	s_nop 0
	v_cndmask_b32_e64 v119, v122, v119, s[10:11]
	v_mul_f32_e32 v122, v112, v157
	v_fma_f32 v112, v112, v157, v184
	v_mul_f32_e32 v112, 0xbfb8aa3b, v112
	v_exp_f32_e32 v112, v112
	s_nop 0
	v_add_f32_e32 v112, 1.0, v112
	v_rcp_f32_e32 v112, v112
	s_nop 0
	v_cndmask_b32_e64 v122, v122, v112, s[10:11]
	v_mul_f32_e32 v112, v113, v157
	v_fma_f32 v113, v113, v157, v180
	v_mul_f32_e32 v113, 0xbfb8aa3b, v113
	v_exp_f32_e32 v113, v113
	s_nop 0
	v_add_f32_e32 v113, 1.0, v113
	v_rcp_f32_e32 v113, v113
	s_nop 0
	v_cndmask_b32_e64 v123, v112, v113, s[10:11]
	v_fma_f32 v113, v114, v157, v185
	v_mul_f32_e32 v113, 0xbfb8aa3b, v113
	v_exp_f32_e32 v113, v113
	v_mul_f32_e32 v112, v114, v157
	v_cvt_pk_bf16_f32 v114, v122, v123
	v_add_f32_e32 v113, 1.0, v113
	v_rcp_f32_e32 v113, v113
	s_nop 0
	v_cndmask_b32_e64 v124, v112, v113, s[10:11]
	v_fma_f32 v113, v115, v157, v182
	v_mul_f32_e32 v113, 0xbfb8aa3b, v113
	v_exp_f32_e32 v113, v113
	v_mul_f32_e32 v112, v115, v157
	v_add_f32_e32 v113, 1.0, v113
	v_rcp_f32_e32 v113, v113
	s_nop 0
	v_cndmask_b32_e64 v115, v112, v113, s[10:11]
	v_cvt_pk_bf16_f32 v112, v116, v117
	v_cvt_pk_bf16_f32 v113, v118, v119
	v_cvt_pk_bf16_f32 v115, v124, v115
	global_store_dwordx4 v[120:121], v[112:115], off nt
	v_bitop3_b32 v120, v152, s6, 16 bitop3:0xc8
	s_nop 0
	v_or_b32_e32 v112, 16, v152
	v_ashrrev_i32_e32 v113, 31, v112
	v_lshl_add_u64 v[114:115], v[112:113], 2, s[44:45]
	global_load_dword v121, v[114:115], off
	v_lshlrev_b64 v[114:115], 13, v[112:113]
	v_or_b32_e32 v112, s17, v120
	s_cbranch_vccnz .LBB0_480
	s_and_b64 vcc, exec, s[12:13]
	s_mov_b64 s[6:7], -1
	s_cbranch_vccnz .LBB0_477
	s_andn2_b64 vcc, exec, s[90:91]
	s_cbranch_vccnz .LBB0_474
	s_andn2_b64 vcc, exec, s[88:89]
	s_cbranch_vccnz .LBB0_471
	v_lshl_add_u64 v[116:117], s[20:21], 0, v[114:115]
	v_lshl_add_u64 v[116:117], s[0:1], 1, v[116:117]
	v_lshl_add_u64 v[116:117], v[116:117], 0, v[136:137]
	v_lshl_add_u64 v[118:119], v[116:117], 0, s[30:31]
	s_mov_b64 s[6:7], 0

; __device__ __forceinline__ unsigned cvt_pk_bf16(float lo, float hi) { f32x2_t v = {lo, hi}; bf16x2_t b = __builtin_convertvector(v, bf16x2_t); return __builtin_bit_cast(unsigned, b); }
; __device__ __forceinline__ float rstd_of(const float* ss, int row) { return __builtin_amdgcn_rsqf(ss[row] * (1.0f / 1024.0f) + RMS_EPS); }
; __device__ __forceinline__ float sigmoidf_(float v) { return __builtin_amdgcn_rcpf(1.0f + __builtin_amdgcn_exp2f(-v * LOG2E)); }
;     __device__ __forceinline__ void operator()(const Acc& acc, const Unit& u, int wr, int wc, int fr, int fq) const {
;     ...
;                 const int row = row0 + ai * HALF + m * 16; const float rs = rstd_of(ss, row) * sc;
;                 const int b = row >> 11, t = row & (SEQ - 1);
; #pragma unroll
;                 for (int bj = 0; bj < 2; ++bj) {
;                     float o[8];
; #pragma unroll
;                     for (int n = 0; n < 2; ++n)
; #pragma unroll
;                         for (int e = 0; e < 4; ++e) { float v = acc[ai][bj][m][n][e] * rs; if (isg) v = sigmoidf_(v + bv[bj][4 * n + e]); o[4 * n + e] = v; }
;                     u32x4 w; w.x = cvt_pk_bf16(o[0], o[1]); w.y = cvt_pk_bf16(o[2], o[3]); w.z = cvt_pk_bf16(o[4], o[5]); w.w = cvt_pk_bf16(o[6], o[7]);
;                     bf16_t* dst;
;                     if (tile < 4) dst = P + (size_t)row * PP + C_DQ + tile * BM + bj * HALF + cc;
;                     else if (tile < 8) dst = KD + ((size_t)((b * 8 + (tile - 4) * 2 + bj) * SEQ + t)) * 128 + cc;
;                     else if (tile < 12) dst = P + (size_t)row * PP + C_SQ + (tile - 8) * BM + bj * HALF + cc;
;                     else if (tile == 12) { const int ccf = bj * HALF + cc; dst = KS + ((size_t)((b * 4 + (ccf >> 6)) * SEQ + t)) * 64 + (ccf & 63); }
;                     else dst = P + (size_t)row * PP + C_GA + (tile - 13) * BM + bj * HALF + cc;
;                     *(u32x4*)dst = w;
.LBB0_482:
	s_waitcnt vmcnt(0)
	v_fmamk_f32 v113, v121, 0x3a800000, v170
	v_rsq_f32_e32 v113, v113
	s_mov_b64 s[94:95], -1
	s_and_b64 vcc, exec, s[14:15]
	v_mul_f32_e32 v113, v153, v113
	v_mul_f32_e32 v121, v108, v113
	v_fma_f32 v108, v108, v113, v187
	v_mul_f32_e32 v108, 0xbfb8aa3b, v108
	v_exp_f32_e32 v108, v108
	s_nop 0
	v_add_f32_e32 v108, 1.0, v108
	v_rcp_f32_e32 v108, v108
	s_nop 0
	v_cndmask_b32_e64 v108, v121, v108, s[10:11]
	v_mul_f32_e32 v121, v109, v113
	v_fma_f32 v109, v109, v113, v186
	v_mul_f32_e32 v109, 0xbfb8aa3b, v109
	v_exp_f32_e32 v109, v109
	s_nop 0
	v_add_f32_e32 v109, 1.0, v109
	v_rcp_f32_e32 v109, v109
	s_nop 0
	v_cndmask_b32_e64 v109, v121, v109, s[10:11]
	v_mul_f32_e32 v121, v110, v113
	v_fma_f32 v110, v110, v113, v191
	v_mul_f32_e32 v110, 0xbfb8aa3b, v110
	v_exp_f32_e32 v110, v110
	s_nop 0
	v_add_f32_e32 v110, 1.0, v110
	v_rcp_f32_e32 v110, v110
	s_nop 0
	v_cndmask_b32_e64 v110, v121, v110, s[10:11]
	v_mul_f32_e32 v121, v111, v113
	v_fma_f32 v111, v111, v113, v188
	v_mul_f32_e32 v111, 0xbfb8aa3b, v111
	v_exp_f32_e32 v111, v111
	s_nop 0
	v_add_f32_e32 v111, 1.0, v111
	v_rcp_f32_e32 v111, v111
	s_nop 0
	v_cndmask_b32_e64 v111, v121, v111, s[10:11]
	v_mul_f32_e32 v121, v104, v113
	v_fma_f32 v104, v104, v113, v192
	v_mul_f32_e32 v104, 0xbfb8aa3b, v104
	v_exp_f32_e32 v104, v104
	s_nop 0
	v_add_f32_e32 v104, 1.0, v104
	v_rcp_f32_e32 v104, v104
	s_nop 0
	v_cndmask_b32_e64 v121, v121, v104, s[10:11]
	v_mul_f32_e32 v104, v105, v113
	v_fma_f32 v105, v105, v113, v189
	v_mul_f32_e32 v105, 0xbfb8aa3b, v105
	v_exp_f32_e32 v105, v105
	s_nop 0
	v_add_f32_e32 v105, 1.0, v105
	v_rcp_f32_e32 v105, v105
	s_nop 0
	v_cndmask_b32_e64 v122, v104, v105, s[10:11]
	v_fma_f32 v105, v106, v113, v193
	v_mul_f32_e32 v105, 0xbfb8aa3b, v105
	v_exp_f32_e32 v105, v105
	v_mul_f32_e32 v104, v106, v113
	v_cvt_pk_bf16_f32 v106, v121, v122
	v_add_f32_e32 v105, 1.0, v105
	v_rcp_f32_e32 v105, v105
	s_nop 0
	v_cndmask_b32_e64 v123, v104, v105, s[10:11]
	v_fma_f32 v105, v107, v113, v190
	v_mul_f32_e32 v105, 0xbfb8aa3b, v105
	v_exp_f32_e32 v105, v105
	v_mul_f32_e32 v104, v107, v113
	v_add_f32_e32 v105, 1.0, v105
	v_rcp_f32_e32 v105, v105
	s_nop 0
	v_cndmask_b32_e64 v107, v104, v105, s[10:11]
	v_cvt_pk_bf16_f32 v104, v108, v109
	v_cvt_pk_bf16_f32 v105, v110, v111
	v_cvt_pk_bf16_f32 v107, v123, v107
	global_store_dwordx4 v[118:119], v[104:107], off nt
	s_cbranch_vccnz .LBB0_496
	s_and_b64 vcc, exec, s[12:13]
	s_mov_b64 s[6:7], -1
	s_cbranch_vccnz .LBB0_493
	s_andn2_b64 vcc, exec, s[90:91]
	s_cbranch_vccnz .LBB0_490
	s_andn2_b64 vcc, exec, s[88:89]
	s_cbranch_vccnz .LBB0_487
	v_lshl_add_u64 v[104:105], s[0:1], 1, v[116:117]
	v_lshl_add_u64 v[104:105], v[104:105], 0, v[136:137]
	v_lshl_add_u64 v[104:105], v[104:105], 0, s[36:37]
	s_mov_b64 s[6:7], 0

; __device__ __forceinline__ unsigned cvt_pk_bf16(float lo, float hi) { f32x2_t v = {lo, hi}; bf16x2_t b = __builtin_convertvector(v, bf16x2_t); return __builtin_bit_cast(unsigned, b); }
; __device__ __forceinline__ float rstd_of(const float* ss, int row) { return __builtin_amdgcn_rsqf(ss[row] * (1.0f / 1024.0f) + RMS_EPS); }
; __device__ __forceinline__ float sigmoidf_(float v) { return __builtin_amdgcn_rcpf(1.0f + __builtin_amdgcn_exp2f(-v * LOG2E)); }
;     __device__ __forceinline__ void operator()(const Acc& acc, const Unit& u, int wr, int wc, int fr, int fq) const {
;     ...
;                 const int row = row0 + ai * HALF + m * 16; const float rs = rstd_of(ss, row) * sc;
;                 const int b = row >> 11, t = row & (SEQ - 1);
; #pragma unroll
;                 for (int bj = 0; bj < 2; ++bj) {
;                     float o[8];
; #pragma unroll
;                     for (int n = 0; n < 2; ++n)
; #pragma unroll
;                         for (int e = 0; e < 4; ++e) { float v = acc[ai][bj][m][n][e] * rs; if (isg) v = sigmoidf_(v + bv[bj][4 * n + e]); o[4 * n + e] = v; }
;                     u32x4 w; w.x = cvt_pk_bf16(o[0], o[1]); w.y = cvt_pk_bf16(o[2], o[3]); w.z = cvt_pk_bf16(o[4], o[5]); w.w = cvt_pk_bf16(o[6], o[7]);
;                     bf16_t* dst;
;                     if (tile < 4) dst = P + (size_t)row * PP + C_DQ + tile * BM + bj * HALF + cc;
;                     else if (tile < 8) dst = KD + ((size_t)((b * 8 + (tile - 4) * 2 + bj) * SEQ + t)) * 128 + cc;
;                     else if (tile < 12) dst = P + (size_t)row * PP + C_SQ + (tile - 8) * BM + bj * HALF + cc;
;                     else if (tile == 12) { const int ccf = bj * HALF + cc; dst = KS + ((size_t)((b * 4 + (ccf >> 6)) * SEQ + t)) * 64 + (ccf & 63); }
;                     else dst = P + (size_t)row * PP + C_GA + (tile - 13) * BM + bj * HALF + cc;
;                     *(u32x4*)dst = w;
.LBB0_498:
	v_mul_f32_e32 v106, v100, v113
	v_fma_f32 v100, v100, v113, v181
	v_mul_f32_e32 v100, 0xbfb8aa3b, v100
	v_exp_f32_e32 v100, v100
	s_movk_i32 s6, 0x7ef
	s_mov_b64 s[94:95], -1
	s_and_b64 vcc, exec, s[14:15]
	v_add_f32_e32 v100, 1.0, v100
	v_rcp_f32_e32 v100, v100
	s_nop 0
	v_cndmask_b32_e64 v100, v106, v100, s[10:11]
	v_mul_f32_e32 v106, v101, v113
	v_fma_f32 v101, v101, v113, v174
	v_mul_f32_e32 v101, 0xbfb8aa3b, v101
	v_exp_f32_e32 v101, v101
	s_nop 0
	v_add_f32_e32 v101, 1.0, v101
	v_rcp_f32_e32 v101, v101
	s_nop 0
	v_cndmask_b32_e64 v101, v106, v101, s[10:11]
	v_mul_f32_e32 v106, v102, v113
	v_fma_f32 v102, v102, v113, v183
	v_mul_f32_e32 v102, 0xbfb8aa3b, v102
	v_exp_f32_e32 v102, v102
	s_nop 0
	v_add_f32_e32 v102, 1.0, v102
	v_rcp_f32_e32 v102, v102
	s_nop 0
	v_cndmask_b32_e64 v102, v106, v102, s[10:11]
	v_mul_f32_e32 v106, v103, v113
	v_fma_f32 v103, v103, v113, v178
	v_mul_f32_e32 v103, 0xbfb8aa3b, v103
	v_exp_f32_e32 v103, v103
	s_nop 0
	v_add_f32_e32 v103, 1.0, v103
	v_rcp_f32_e32 v103, v103
	s_nop 0
	v_cndmask_b32_e64 v103, v106, v103, s[10:11]
	v_mul_f32_e32 v106, v96, v113
	v_fma_f32 v96, v96, v113, v184
	v_mul_f32_e32 v96, 0xbfb8aa3b, v96
	v_exp_f32_e32 v96, v96
	s_nop 0
	v_add_f32_e32 v96, 1.0, v96
	v_rcp_f32_e32 v96, v96
	s_nop 0
	v_cndmask_b32_e64 v106, v106, v96, s[10:11]
	v_mul_f32_e32 v96, v97, v113
	v_fma_f32 v97, v97, v113, v180
	v_mul_f32_e32 v97, 0xbfb8aa3b, v97
	v_exp_f32_e32 v97, v97
	s_nop 0
	v_add_f32_e32 v97, 1.0, v97
	v_rcp_f32_e32 v97, v97
	s_nop 0
	v_cndmask_b32_e64 v107, v96, v97, s[10:11]
	v_fma_f32 v97, v98, v113, v185
	v_mul_f32_e32 v97, 0xbfb8aa3b, v97
	v_exp_f32_e32 v97, v97
	v_mul_f32_e32 v96, v98, v113
	v_cvt_pk_bf16_f32 v98, v106, v107
	v_add_f32_e32 v97, 1.0, v97
	v_rcp_f32_e32 v97, v97
	s_nop 0
	v_cndmask_b32_e64 v108, v96, v97, s[10:11]
	v_fma_f32 v97, v99, v113, v182
	v_mul_f32_e32 v97, 0xbfb8aa3b, v97
	v_exp_f32_e32 v97, v97
	v_mul_f32_e32 v96, v99, v113
	v_add_f32_e32 v97, 1.0, v97
	v_rcp_f32_e32 v97, v97
	s_nop 0
	v_cndmask_b32_e64 v99, v96, v97, s[10:11]
	v_cvt_pk_bf16_f32 v96, v100, v101
	v_cvt_pk_bf16_f32 v97, v102, v103
	v_cvt_pk_bf16_f32 v99, v108, v99
	global_store_dwordx4 v[104:105], v[96:99], off nt
	v_bitop3_b32 v104, v152, s6, 32 bitop3:0xc8
	s_nop 0
	v_or_b32_e32 v96, 32, v152
	v_ashrrev_i32_e32 v97, 31, v96
	v_lshl_add_u64 v[98:99], v[96:97], 2, s[44:45]
	global_load_dword v105, v[98:99], off
	v_lshlrev_b64 v[98:99], 13, v[96:97]
	v_or_b32_e32 v96, s17, v104
	s_cbranch_vccnz .LBB0_512
	s_and_b64 vcc, exec, s[12:13]
	s_mov_b64 s[6:7], -1
	s_cbranch_vccnz .LBB0_509
	s_andn2_b64 vcc, exec, s[90:91]
	s_cbranch_vccnz .LBB0_506
	s_andn2_b64 vcc, exec, s[88:89]
	s_cbranch_vccnz .LBB0_503
	v_lshl_add_u64 v[100:101], s[20:21], 0, v[98:99]
	v_lshl_add_u64 v[100:101], s[0:1], 1, v[100:101]
	v_lshl_add_u64 v[100:101], v[100:101], 0, v[136:137]
	v_lshl_add_u64 v[102:103], v[100:101], 0, s[30:31]
	s_mov_b64 s[6:7], 0

; __device__ __forceinline__ unsigned cvt_pk_bf16(float lo, float hi) { f32x2_t v = {lo, hi}; bf16x2_t b = __builtin_convertvector(v, bf16x2_t); return __builtin_bit_cast(unsigned, b); }
; __device__ __forceinline__ float rstd_of(const float* ss, int row) { return __builtin_amdgcn_rsqf(ss[row] * (1.0f / 1024.0f) + RMS_EPS); }
; __device__ __forceinline__ float sigmoidf_(float v) { return __builtin_amdgcn_rcpf(1.0f + __builtin_amdgcn_exp2f(-v * LOG2E)); }
;     __device__ __forceinline__ void operator()(const Acc& acc, const Unit& u, int wr, int wc, int fr, int fq) const {
;     ...
;                 const int row = row0 + ai * HALF + m * 16; const float rs = rstd_of(ss, row) * sc;
;                 const int b = row >> 11, t = row & (SEQ - 1);
; #pragma unroll
;                 for (int bj = 0; bj < 2; ++bj) {
;                     float o[8];
; #pragma unroll
;                     for (int n = 0; n < 2; ++n)
; #pragma unroll
;                         for (int e = 0; e < 4; ++e) { float v = acc[ai][bj][m][n][e] * rs; if (isg) v = sigmoidf_(v + bv[bj][4 * n + e]); o[4 * n + e] = v; }
;                     u32x4 w; w.x = cvt_pk_bf16(o[0], o[1]); w.y = cvt_pk_bf16(o[2], o[3]); w.z = cvt_pk_bf16(o[4], o[5]); w.w = cvt_pk_bf16(o[6], o[7]);
;                     bf16_t* dst;
;                     if (tile < 4) dst = P + (size_t)row * PP + C_DQ + tile * BM + bj * HALF + cc;
;                     else if (tile < 8) dst = KD + ((size_t)((b * 8 + (tile - 4) * 2 + bj) * SEQ + t)) * 128 + cc;
;                     else if (tile < 12) dst = P + (size_t)row * PP + C_SQ + (tile - 8) * BM + bj * HALF + cc;
;                     else if (tile == 12) { const int ccf = bj * HALF + cc; dst = KS + ((size_t)((b * 4 + (ccf >> 6)) * SEQ + t)) * 64 + (ccf & 63); }
;                     else dst = P + (size_t)row * PP + C_GA + (tile - 13) * BM + bj * HALF + cc;
;                     *(u32x4*)dst = w;
.LBB0_514:
	s_waitcnt vmcnt(0)
	v_fmamk_f32 v97, v105, 0x3a800000, v170
	v_rsq_f32_e32 v97, v97
	s_mov_b64 s[94:95], -1
	s_and_b64 vcc, exec, s[14:15]
	v_mul_f32_e32 v97, v153, v97
	v_mul_f32_e32 v105, v92, v97
	v_fma_f32 v92, v92, v97, v187
	v_mul_f32_e32 v92, 0xbfb8aa3b, v92
	v_exp_f32_e32 v92, v92
	s_nop 0
	v_add_f32_e32 v92, 1.0, v92
	v_rcp_f32_e32 v92, v92
	s_nop 0
	v_cndmask_b32_e64 v92, v105, v92, s[10:11]
	v_mul_f32_e32 v105, v93, v97
	v_fma_f32 v93, v93, v97, v186
	v_mul_f32_e32 v93, 0xbfb8aa3b, v93
	v_exp_f32_e32 v93, v93
	s_nop 0
	v_add_f32_e32 v93, 1.0, v93
	v_rcp_f32_e32 v93, v93
	s_nop 0
	v_cndmask_b32_e64 v93, v105, v93, s[10:11]
	v_mul_f32_e32 v105, v94, v97
	v_fma_f32 v94, v94, v97, v191
	v_mul_f32_e32 v94, 0xbfb8aa3b, v94
	v_exp_f32_e32 v94, v94
	s_nop 0
	v_add_f32_e32 v94, 1.0, v94
	v_rcp_f32_e32 v94, v94
	s_nop 0
	v_cndmask_b32_e64 v94, v105, v94, s[10:11]
	v_mul_f32_e32 v105, v95, v97
	v_fma_f32 v95, v95, v97, v188
	v_mul_f32_e32 v95, 0xbfb8aa3b, v95
	v_exp_f32_e32 v95, v95
	s_nop 0
	v_add_f32_e32 v95, 1.0, v95
	v_rcp_f32_e32 v95, v95
	s_nop 0
	v_cndmask_b32_e64 v95, v105, v95, s[10:11]
	v_mul_f32_e32 v105, v88, v97
	v_fma_f32 v88, v88, v97, v192
	v_mul_f32_e32 v88, 0xbfb8aa3b, v88
	v_exp_f32_e32 v88, v88
	s_nop 0
	v_add_f32_e32 v88, 1.0, v88
	v_rcp_f32_e32 v88, v88
	s_nop 0
	v_cndmask_b32_e64 v105, v105, v88, s[10:11]
	v_mul_f32_e32 v88, v89, v97
	v_fma_f32 v89, v89, v97, v189
	v_mul_f32_e32 v89, 0xbfb8aa3b, v89
	v_exp_f32_e32 v89, v89
	s_nop 0
	v_add_f32_e32 v89, 1.0, v89
	v_rcp_f32_e32 v89, v89
	s_nop 0
	v_cndmask_b32_e64 v106, v88, v89, s[10:11]
	v_fma_f32 v89, v90, v97, v193
	v_mul_f32_e32 v89, 0xbfb8aa3b, v89
	v_exp_f32_e32 v89, v89
	v_mul_f32_e32 v88, v90, v97
	v_cvt_pk_bf16_f32 v90, v105, v106
	v_add_f32_e32 v89, 1.0, v89
	v_rcp_f32_e32 v89, v89
	s_nop 0
	v_cndmask_b32_e64 v107, v88, v89, s[10:11]
	v_fma_f32 v89, v91, v97, v190
	v_mul_f32_e32 v89, 0xbfb8aa3b, v89
	v_exp_f32_e32 v89, v89
	v_mul_f32_e32 v88, v91, v97
	v_add_f32_e32 v89, 1.0, v89
	v_rcp_f32_e32 v89, v89
	s_nop 0
	v_cndmask_b32_e64 v91, v88, v89, s[10:11]
	v_cvt_pk_bf16_f32 v88, v92, v93
	v_cvt_pk_bf16_f32 v89, v94, v95
	v_cvt_pk_bf16_f32 v91, v107, v91
	global_store_dwordx4 v[102:103], v[88:91], off nt
	s_cbranch_vccnz .LBB0_528
	s_and_b64 vcc, exec, s[12:13]
	s_mov_b64 s[6:7], -1
	s_cbranch_vccnz .LBB0_525
	s_andn2_b64 vcc, exec, s[90:91]
	s_cbranch_vccnz .LBB0_522
	s_andn2_b64 vcc, exec, s[88:89]
	s_cbranch_vccnz .LBB0_519
	v_lshl_add_u64 v[88:89], s[0:1], 1, v[100:101]
	v_lshl_add_u64 v[88:89], v[88:89], 0, v[136:137]
	v_lshl_add_u64 v[88:89], v[88:89], 0, s[36:37]
	s_mov_b64 s[6:7], 0

; __device__ __forceinline__ unsigned cvt_pk_bf16(float lo, float hi) { f32x2_t v = {lo, hi}; bf16x2_t b = __builtin_convertvector(v, bf16x2_t); return __builtin_bit_cast(unsigned, b); }
; __device__ __forceinline__ float rstd_of(const float* ss, int row) { return __builtin_amdgcn_rsqf(ss[row] * (1.0f / 1024.0f) + RMS_EPS); }
; __device__ __forceinline__ float sigmoidf_(float v) { return __builtin_amdgcn_rcpf(1.0f + __builtin_amdgcn_exp2f(-v * LOG2E)); }
;     __device__ __forceinline__ void operator()(const Acc& acc, const Unit& u, int wr, int wc, int fr, int fq) const {
;     ...
;                 const int row = row0 + ai * HALF + m * 16; const float rs = rstd_of(ss, row) * sc;
;                 const int b = row >> 11, t = row & (SEQ - 1);
; #pragma unroll
;                 for (int bj = 0; bj < 2; ++bj) {
;                     float o[8];
; #pragma unroll
;                     for (int n = 0; n < 2; ++n)
; #pragma unroll
;                         for (int e = 0; e < 4; ++e) { float v = acc[ai][bj][m][n][e] * rs; if (isg) v = sigmoidf_(v + bv[bj][4 * n + e]); o[4 * n + e] = v; }
;                     u32x4 w; w.x = cvt_pk_bf16(o[0], o[1]); w.y = cvt_pk_bf16(o[2], o[3]); w.z = cvt_pk_bf16(o[4], o[5]); w.w = cvt_pk_bf16(o[6], o[7]);
;                     bf16_t* dst;
;                     if (tile < 4) dst = P + (size_t)row * PP + C_DQ + tile * BM + bj * HALF + cc;
;                     else if (tile < 8) dst = KD + ((size_t)((b * 8 + (tile - 4) * 2 + bj) * SEQ + t)) * 128 + cc;
;                     else if (tile < 12) dst = P + (size_t)row * PP + C_SQ + (tile - 8) * BM + bj * HALF + cc;
;                     else if (tile == 12) { const int ccf = bj * HALF + cc; dst = KS + ((size_t)((b * 4 + (ccf >> 6)) * SEQ + t)) * 64 + (ccf & 63); }
;                     else dst = P + (size_t)row * PP + C_GA + (tile - 13) * BM + bj * HALF + cc;
;                     *(u32x4*)dst = w;
.LBB0_530:
	v_mul_f32_e32 v90, v84, v97
	v_fma_f32 v84, v84, v97, v181
	v_mul_f32_e32 v84, 0xbfb8aa3b, v84
	v_exp_f32_e32 v84, v84
	s_movk_i32 s6, 0x7ff
	s_mov_b64 s[94:95], -1
	s_and_b64 vcc, exec, s[14:15]
	v_add_f32_e32 v84, 1.0, v84
	v_rcp_f32_e32 v84, v84
	s_nop 0
	v_cndmask_b32_e64 v84, v90, v84, s[10:11]
	v_mul_f32_e32 v90, v85, v97
	v_fma_f32 v85, v85, v97, v174
	v_mul_f32_e32 v85, 0xbfb8aa3b, v85
	v_exp_f32_e32 v85, v85
	s_nop 0
	v_add_f32_e32 v85, 1.0, v85
	v_rcp_f32_e32 v85, v85
	s_nop 0
	v_cndmask_b32_e64 v85, v90, v85, s[10:11]
	v_mul_f32_e32 v90, v86, v97
	v_fma_f32 v86, v86, v97, v183
	v_mul_f32_e32 v86, 0xbfb8aa3b, v86
	v_exp_f32_e32 v86, v86
	s_nop 0
	v_add_f32_e32 v86, 1.0, v86
	v_rcp_f32_e32 v86, v86
	s_nop 0
	v_cndmask_b32_e64 v86, v90, v86, s[10:11]
	v_mul_f32_e32 v90, v87, v97
	v_fma_f32 v87, v87, v97, v178
	v_mul_f32_e32 v87, 0xbfb8aa3b, v87
	v_exp_f32_e32 v87, v87
	s_nop 0
	v_add_f32_e32 v87, 1.0, v87
	v_rcp_f32_e32 v87, v87
	s_nop 0
	v_cndmask_b32_e64 v87, v90, v87, s[10:11]
	v_mul_f32_e32 v90, v80, v97
	v_fma_f32 v80, v80, v97, v184
	v_mul_f32_e32 v80, 0xbfb8aa3b, v80
	v_exp_f32_e32 v80, v80
	s_nop 0
	v_add_f32_e32 v80, 1.0, v80
	v_rcp_f32_e32 v80, v80
	s_nop 0
	v_cndmask_b32_e64 v90, v90, v80, s[10:11]
	v_mul_f32_e32 v80, v81, v97
	v_fma_f32 v81, v81, v97, v180
	v_mul_f32_e32 v81, 0xbfb8aa3b, v81
	v_exp_f32_e32 v81, v81
	s_nop 0
	v_add_f32_e32 v81, 1.0, v81
	v_rcp_f32_e32 v81, v81
	s_nop 0
	v_cndmask_b32_e64 v91, v80, v81, s[10:11]
	v_fma_f32 v81, v82, v97, v185
	v_mul_f32_e32 v81, 0xbfb8aa3b, v81
	v_exp_f32_e32 v81, v81
	v_mul_f32_e32 v80, v82, v97
	v_cvt_pk_bf16_f32 v82, v90, v91
	v_add_f32_e32 v81, 1.0, v81
	v_rcp_f32_e32 v81, v81
	s_nop 0
	v_cndmask_b32_e64 v92, v80, v81, s[10:11]
	v_fma_f32 v81, v83, v97, v182
	v_mul_f32_e32 v81, 0xbfb8aa3b, v81
	v_exp_f32_e32 v81, v81
	v_mul_f32_e32 v80, v83, v97
	v_add_f32_e32 v81, 1.0, v81
	v_rcp_f32_e32 v81, v81
	s_nop 0
	v_cndmask_b32_e64 v83, v80, v81, s[10:11]
	v_cvt_pk_bf16_f32 v80, v84, v85
	v_cvt_pk_bf16_f32 v81, v86, v87
	v_cvt_pk_bf16_f32 v83, v92, v83
	global_store_dwordx4 v[88:89], v[80:83], off nt
	v_bitop3_b32 v88, v152, s6, 48 bitop3:0xc8
	s_nop 0
	v_or_b32_e32 v80, 48, v152
	v_ashrrev_i32_e32 v81, 31, v80
	v_lshl_add_u64 v[82:83], v[80:81], 2, s[44:45]
	global_load_dword v89, v[82:83], off
	v_lshlrev_b64 v[82:83], 13, v[80:81]
	v_or_b32_e32 v80, s17, v88
	s_cbranch_vccnz .LBB0_544
	s_and_b64 vcc, exec, s[12:13]
	s_mov_b64 s[6:7], -1
	s_cbranch_vccnz .LBB0_541
	s_andn2_b64 vcc, exec, s[90:91]
	s_cbranch_vccnz .LBB0_538
	s_andn2_b64 vcc, exec, s[88:89]
	s_cbranch_vccnz .LBB0_535
	v_lshl_add_u64 v[84:85], s[20:21], 0, v[82:83]
	v_lshl_add_u64 v[84:85], s[0:1], 1, v[84:85]
	v_lshl_add_u64 v[84:85], v[84:85], 0, v[136:137]
	v_lshl_add_u64 v[86:87], v[84:85], 0, s[30:31]
	s_mov_b64 s[6:7], 0

; __device__ __forceinline__ unsigned cvt_pk_bf16(float lo, float hi) { f32x2_t v = {lo, hi}; bf16x2_t b = __builtin_convertvector(v, bf16x2_t); return __builtin_bit_cast(unsigned, b); }
; __device__ __forceinline__ float rstd_of(const float* ss, int row) { return __builtin_amdgcn_rsqf(ss[row] * (1.0f / 1024.0f) + RMS_EPS); }
; __device__ __forceinline__ float sigmoidf_(float v) { return __builtin_amdgcn_rcpf(1.0f + __builtin_amdgcn_exp2f(-v * LOG2E)); }
;     __device__ __forceinline__ void operator()(const Acc& acc, const Unit& u, int wr, int wc, int fr, int fq) const {
;     ...
;                 const int row = row0 + ai * HALF + m * 16; const float rs = rstd_of(ss, row) * sc;
;                 const int b = row >> 11, t = row & (SEQ - 1);
; #pragma unroll
;                 for (int bj = 0; bj < 2; ++bj) {
;                     float o[8];
; #pragma unroll
;                     for (int n = 0; n < 2; ++n)
; #pragma unroll
;                         for (int e = 0; e < 4; ++e) { float v = acc[ai][bj][m][n][e] * rs; if (isg) v = sigmoidf_(v + bv[bj][4 * n + e]); o[4 * n + e] = v; }
;                     u32x4 w; w.x = cvt_pk_bf16(o[0], o[1]); w.y = cvt_pk_bf16(o[2], o[3]); w.z = cvt_pk_bf16(o[4], o[5]); w.w = cvt_pk_bf16(o[6], o[7]);
;                     bf16_t* dst;
;                     if (tile < 4) dst = P + (size_t)row * PP + C_DQ + tile * BM + bj * HALF + cc;
;                     else if (tile < 8) dst = KD + ((size_t)((b * 8 + (tile - 4) * 2 + bj) * SEQ + t)) * 128 + cc;
;                     else if (tile < 12) dst = P + (size_t)row * PP + C_SQ + (tile - 8) * BM + bj * HALF + cc;
;                     else if (tile == 12) { const int ccf = bj * HALF + cc; dst = KS + ((size_t)((b * 4 + (ccf >> 6)) * SEQ + t)) * 64 + (ccf & 63); }
;                     else dst = P + (size_t)row * PP + C_GA + (tile - 13) * BM + bj * HALF + cc;
;                     *(u32x4*)dst = w;
.LBB0_546:
	s_waitcnt vmcnt(0)
	v_fmamk_f32 v81, v89, 0x3a800000, v170
	v_rsq_f32_e32 v81, v81
	s_mov_b64 s[94:95], -1
	s_and_b64 vcc, exec, s[14:15]
	v_mul_f32_e32 v81, v153, v81
	v_mul_f32_e32 v89, v76, v81
	v_fma_f32 v76, v76, v81, v187
	v_mul_f32_e32 v76, 0xbfb8aa3b, v76
	v_exp_f32_e32 v76, v76
	s_nop 0
	v_add_f32_e32 v76, 1.0, v76
	v_rcp_f32_e32 v76, v76
	s_nop 0
	v_cndmask_b32_e64 v76, v89, v76, s[10:11]
	v_mul_f32_e32 v89, v77, v81
	v_fma_f32 v77, v77, v81, v186
	v_mul_f32_e32 v77, 0xbfb8aa3b, v77
	v_exp_f32_e32 v77, v77
	s_nop 0
	v_add_f32_e32 v77, 1.0, v77
	v_rcp_f32_e32 v77, v77
	s_nop 0
	v_cndmask_b32_e64 v77, v89, v77, s[10:11]
	v_mul_f32_e32 v89, v78, v81
	v_fma_f32 v78, v78, v81, v191
	v_mul_f32_e32 v78, 0xbfb8aa3b, v78
	v_exp_f32_e32 v78, v78
	s_nop 0
	v_add_f32_e32 v78, 1.0, v78
	v_rcp_f32_e32 v78, v78
	s_nop 0
	v_cndmask_b32_e64 v78, v89, v78, s[10:11]
	v_mul_f32_e32 v89, v79, v81
	v_fma_f32 v79, v79, v81, v188
	v_mul_f32_e32 v79, 0xbfb8aa3b, v79
	v_exp_f32_e32 v79, v79
	s_nop 0
	v_add_f32_e32 v79, 1.0, v79
	v_rcp_f32_e32 v79, v79
	s_nop 0
	v_cndmask_b32_e64 v79, v89, v79, s[10:11]
	v_mul_f32_e32 v89, v72, v81
	v_fma_f32 v72, v72, v81, v192
	v_mul_f32_e32 v72, 0xbfb8aa3b, v72
	v_exp_f32_e32 v72, v72
	s_nop 0
	v_add_f32_e32 v72, 1.0, v72
	v_rcp_f32_e32 v72, v72
	s_nop 0
	v_cndmask_b32_e64 v89, v89, v72, s[10:11]
	v_mul_f32_e32 v72, v73, v81
	v_fma_f32 v73, v73, v81, v189
	v_mul_f32_e32 v73, 0xbfb8aa3b, v73
	v_exp_f32_e32 v73, v73
	s_nop 0
	v_add_f32_e32 v73, 1.0, v73
	v_rcp_f32_e32 v73, v73
	s_nop 0
	v_cndmask_b32_e64 v90, v72, v73, s[10:11]
	v_fma_f32 v73, v74, v81, v193
	v_mul_f32_e32 v73, 0xbfb8aa3b, v73
	v_exp_f32_e32 v73, v73
	v_mul_f32_e32 v72, v74, v81
	v_cvt_pk_bf16_f32 v74, v89, v90
	v_add_f32_e32 v73, 1.0, v73
	v_rcp_f32_e32 v73, v73
	s_nop 0
	v_cndmask_b32_e64 v91, v72, v73, s[10:11]
	v_fma_f32 v73, v75, v81, v190
	v_mul_f32_e32 v73, 0xbfb8aa3b, v73
	v_exp_f32_e32 v73, v73
	v_mul_f32_e32 v72, v75, v81
	v_add_f32_e32 v73, 1.0, v73
	v_rcp_f32_e32 v73, v73
	s_nop 0
	v_cndmask_b32_e64 v75, v72, v73, s[10:11]
	v_cvt_pk_bf16_f32 v72, v76, v77
	v_cvt_pk_bf16_f32 v73, v78, v79
	v_cvt_pk_bf16_f32 v75, v91, v75
	global_store_dwordx4 v[86:87], v[72:75], off nt
	s_cbranch_vccnz .LBB0_560
	s_and_b64 vcc, exec, s[12:13]
	s_mov_b64 s[6:7], -1
	s_cbranch_vccnz .LBB0_557
	s_andn2_b64 vcc, exec, s[90:91]
	s_cbranch_vccnz .LBB0_554
	s_andn2_b64 vcc, exec, s[88:89]
	s_cbranch_vccnz .LBB0_551
	v_lshl_add_u64 v[72:73], s[0:1], 1, v[84:85]
	v_lshl_add_u64 v[72:73], v[72:73], 0, v[136:137]
	v_lshl_add_u64 v[72:73], v[72:73], 0, s[36:37]
	s_mov_b64 s[6:7], 0

; __device__ __forceinline__ unsigned cvt_pk_bf16(float lo, float hi) { f32x2_t v = {lo, hi}; bf16x2_t b = __builtin_convertvector(v, bf16x2_t); return __builtin_bit_cast(unsigned, b); }
; __device__ __forceinline__ float rstd_of(const float* ss, int row) { return __builtin_amdgcn_rsqf(ss[row] * (1.0f / 1024.0f) + RMS_EPS); }
; __device__ __forceinline__ float sigmoidf_(float v) { return __builtin_amdgcn_rcpf(1.0f + __builtin_amdgcn_exp2f(-v * LOG2E)); }
;     __device__ __forceinline__ void operator()(const Acc& acc, const Unit& u, int wr, int wc, int fr, int fq) const {
;     ...
;                 const int row = row0 + ai * HALF + m * 16; const float rs = rstd_of(ss, row) * sc;
;                 const int b = row >> 11, t = row & (SEQ - 1);
; #pragma unroll
;                 for (int bj = 0; bj < 2; ++bj) {
;                     float o[8];
; #pragma unroll
;                     for (int n = 0; n < 2; ++n)
; #pragma unroll
;                         for (int e = 0; e < 4; ++e) { float v = acc[ai][bj][m][n][e] * rs; if (isg) v = sigmoidf_(v + bv[bj][4 * n + e]); o[4 * n + e] = v; }
;                     u32x4 w; w.x = cvt_pk_bf16(o[0], o[1]); w.y = cvt_pk_bf16(o[2], o[3]); w.z = cvt_pk_bf16(o[4], o[5]); w.w = cvt_pk_bf16(o[6], o[7]);
;                     bf16_t* dst;
;                     if (tile < 4) dst = P + (size_t)row * PP + C_DQ + tile * BM + bj * HALF + cc;
;                     else if (tile < 8) dst = KD + ((size_t)((b * 8 + (tile - 4) * 2 + bj) * SEQ + t)) * 128 + cc;
;                     else if (tile < 12) dst = P + (size_t)row * PP + C_SQ + (tile - 8) * BM + bj * HALF + cc;
;                     else if (tile == 12) { const int ccf = bj * HALF + cc; dst = KS + ((size_t)((b * 4 + (ccf >> 6)) * SEQ + t)) * 64 + (ccf & 63); }
;                     else dst = P + (size_t)row * PP + C_GA + (tile - 13) * BM + bj * HALF + cc;
;                     *(u32x4*)dst = w;
.LBB0_562:
	v_mul_f32_e32 v74, v68, v81
	v_fma_f32 v68, v68, v81, v181
	v_mul_f32_e32 v68, 0xbfb8aa3b, v68
	v_exp_f32_e32 v68, v68
	s_mov_b64 s[94:95], -1
	s_and_b64 vcc, exec, s[14:15]
	v_add_f32_e32 v68, 1.0, v68
	v_rcp_f32_e32 v68, v68
	s_nop 0
	v_cndmask_b32_e64 v68, v74, v68, s[10:11]
	v_mul_f32_e32 v74, v69, v81
	v_fma_f32 v69, v69, v81, v174
	v_mul_f32_e32 v69, 0xbfb8aa3b, v69
	v_exp_f32_e32 v69, v69
	s_nop 0
	v_add_f32_e32 v69, 1.0, v69
	v_rcp_f32_e32 v69, v69
	s_nop 0
	v_cndmask_b32_e64 v69, v74, v69, s[10:11]
	v_mul_f32_e32 v74, v70, v81
	v_fma_f32 v70, v70, v81, v183
	v_mul_f32_e32 v70, 0xbfb8aa3b, v70
	v_exp_f32_e32 v70, v70
	s_nop 0
	v_add_f32_e32 v70, 1.0, v70
	v_rcp_f32_e32 v70, v70
	s_nop 0
	v_cndmask_b32_e64 v70, v74, v70, s[10:11]
	v_mul_f32_e32 v74, v71, v81
	v_fma_f32 v71, v71, v81, v178
	v_mul_f32_e32 v71, 0xbfb8aa3b, v71
	v_exp_f32_e32 v71, v71
	s_nop 0
	v_add_f32_e32 v71, 1.0, v71
	v_rcp_f32_e32 v71, v71
	s_nop 0
	v_cndmask_b32_e64 v71, v74, v71, s[10:11]
	v_mul_f32_e32 v74, v64, v81
	v_fma_f32 v64, v64, v81, v184
	v_mul_f32_e32 v64, 0xbfb8aa3b, v64
	v_exp_f32_e32 v64, v64
	s_nop 0
	v_add_f32_e32 v64, 1.0, v64
	v_rcp_f32_e32 v64, v64
	s_nop 0
	v_cndmask_b32_e64 v74, v74, v64, s[10:11]
	v_mul_f32_e32 v64, v65, v81
	v_fma_f32 v65, v65, v81, v180
	v_mul_f32_e32 v65, 0xbfb8aa3b, v65
	v_exp_f32_e32 v65, v65
	s_nop 0
	v_add_f32_e32 v65, 1.0, v65
	v_rcp_f32_e32 v65, v65
	s_nop 0
	v_cndmask_b32_e64 v75, v64, v65, s[10:11]
	v_fma_f32 v65, v66, v81, v185
	v_mul_f32_e32 v65, 0xbfb8aa3b, v65
	v_exp_f32_e32 v65, v65
	v_mul_f32_e32 v64, v66, v81
	v_cvt_pk_bf16_f32 v66, v74, v75
	v_add_f32_e32 v65, 1.0, v65
	v_rcp_f32_e32 v65, v65
	s_nop 0
	v_cndmask_b32_e64 v76, v64, v65, s[10:11]
	v_fma_f32 v65, v67, v81, v182
	v_mul_f32_e32 v65, 0xbfb8aa3b, v65
	v_exp_f32_e32 v65, v65
	v_mul_f32_e32 v64, v67, v81
	v_add_f32_e32 v65, 1.0, v65
	v_rcp_f32_e32 v65, v65
	s_nop 0
	v_cndmask_b32_e64 v67, v64, v65, s[10:11]
	v_cvt_pk_bf16_f32 v64, v68, v69
	v_cvt_pk_bf16_f32 v65, v70, v71
	v_cvt_pk_bf16_f32 v67, v76, v67
	global_store_dwordx4 v[72:73], v[64:67], off nt
	global_load_dword v75, v[154:155], off offset:512
	s_nop 0
	v_add_u32_e32 v64, 0x80, v152
	v_ashrrev_i32_e32 v65, 11, v64
	v_lshl_or_b32 v73, v65, 13, s23
	v_lshl_add_u32 v72, v65, 3, s2
	v_ashrrev_i32_e32 v65, 31, v64
	v_and_b32_e32 v74, 0x7cf, v64
	v_lshlrev_b64 v[66:67], 13, v[64:65]
	v_or_b32_e32 v64, v73, v74
	s_cbranch_vccnz .LBB0_576
	s_and_b64 vcc, exec, s[12:13]
	s_mov_b64 s[6:7], -1
	s_cbranch_vccnz .LBB0_573
	s_andn2_b64 vcc, exec, s[90:91]
	s_cbranch_vccnz .LBB0_570
	s_andn2_b64 vcc, exec, s[88:89]
	s_cbranch_vccnz .LBB0_567
	v_lshl_add_u64 v[68:69], s[20:21], 0, v[66:67]
	v_lshl_add_u64 v[68:69], s[0:1], 1, v[68:69]
	v_lshl_add_u64 v[68:69], v[68:69], 0, v[136:137]
	v_lshl_add_u64 v[70:71], v[68:69], 0, s[30:31]
	s_mov_b64 s[6:7], 0

; __device__ __forceinline__ unsigned cvt_pk_bf16(float lo, float hi) { f32x2_t v = {lo, hi}; bf16x2_t b = __builtin_convertvector(v, bf16x2_t); return __builtin_bit_cast(unsigned, b); }
; __device__ __forceinline__ float rstd_of(const float* ss, int row) { return __builtin_amdgcn_rsqf(ss[row] * (1.0f / 1024.0f) + RMS_EPS); }
; __device__ __forceinline__ float sigmoidf_(float v) { return __builtin_amdgcn_rcpf(1.0f + __builtin_amdgcn_exp2f(-v * LOG2E)); }
;     __device__ __forceinline__ void operator()(const Acc& acc, const Unit& u, int wr, int wc, int fr, int fq) const {
;     ...
;                 const int row = row0 + ai * HALF + m * 16; const float rs = rstd_of(ss, row) * sc;
;                 const int b = row >> 11, t = row & (SEQ - 1);
; #pragma unroll
;                 for (int bj = 0; bj < 2; ++bj) {
;                     float o[8];
; #pragma unroll
;                     for (int n = 0; n < 2; ++n)
; #pragma unroll
;                         for (int e = 0; e < 4; ++e) { float v = acc[ai][bj][m][n][e] * rs; if (isg) v = sigmoidf_(v + bv[bj][4 * n + e]); o[4 * n + e] = v; }
;                     u32x4 w; w.x = cvt_pk_bf16(o[0], o[1]); w.y = cvt_pk_bf16(o[2], o[3]); w.z = cvt_pk_bf16(o[4], o[5]); w.w = cvt_pk_bf16(o[6], o[7]);
;                     bf16_t* dst;
;                     if (tile < 4) dst = P + (size_t)row * PP + C_DQ + tile * BM + bj * HALF + cc;
;                     else if (tile < 8) dst = KD + ((size_t)((b * 8 + (tile - 4) * 2 + bj) * SEQ + t)) * 128 + cc;
;                     else if (tile < 12) dst = P + (size_t)row * PP + C_SQ + (tile - 8) * BM + bj * HALF + cc;
;                     else if (tile == 12) { const int ccf = bj * HALF + cc; dst = KS + ((size_t)((b * 4 + (ccf >> 6)) * SEQ + t)) * 64 + (ccf & 63); }
;                     else dst = P + (size_t)row * PP + C_GA + (tile - 13) * BM + bj * HALF + cc;
;                     *(u32x4*)dst = w;
.LBB0_578:
	s_waitcnt vmcnt(0)
	v_fmamk_f32 v65, v75, 0x3a800000, v170
	v_rsq_f32_e32 v65, v65
	s_mov_b64 s[94:95], -1
	s_and_b64 vcc, exec, s[14:15]
	v_mul_f32_e32 v65, v153, v65
	v_mul_f32_e32 v75, v60, v65
	v_fma_f32 v60, v60, v65, v187
	v_mul_f32_e32 v60, 0xbfb8aa3b, v60
	v_exp_f32_e32 v60, v60
	s_nop 0
	v_add_f32_e32 v60, 1.0, v60
	v_rcp_f32_e32 v60, v60
	s_nop 0
	v_cndmask_b32_e64 v60, v75, v60, s[10:11]
	v_mul_f32_e32 v75, v61, v65
	v_fma_f32 v61, v61, v65, v186
	v_mul_f32_e32 v61, 0xbfb8aa3b, v61
	v_exp_f32_e32 v61, v61
	s_nop 0
	v_add_f32_e32 v61, 1.0, v61
	v_rcp_f32_e32 v61, v61
	s_nop 0
	v_cndmask_b32_e64 v61, v75, v61, s[10:11]
	v_mul_f32_e32 v75, v62, v65
	v_fma_f32 v62, v62, v65, v191
	v_mul_f32_e32 v62, 0xbfb8aa3b, v62
	v_exp_f32_e32 v62, v62
	s_nop 0
	v_add_f32_e32 v62, 1.0, v62
	v_rcp_f32_e32 v62, v62
	s_nop 0
	v_cndmask_b32_e64 v62, v75, v62, s[10:11]
	v_mul_f32_e32 v75, v63, v65
	v_fma_f32 v63, v63, v65, v188
	v_mul_f32_e32 v63, 0xbfb8aa3b, v63
	v_exp_f32_e32 v63, v63
	s_nop 0
	v_add_f32_e32 v63, 1.0, v63
	v_rcp_f32_e32 v63, v63
	s_nop 0
	v_cndmask_b32_e64 v63, v75, v63, s[10:11]
	v_mul_f32_e32 v75, v56, v65
	v_fma_f32 v56, v56, v65, v192
	v_mul_f32_e32 v56, 0xbfb8aa3b, v56
	v_exp_f32_e32 v56, v56
	s_nop 0
	v_add_f32_e32 v56, 1.0, v56
	v_rcp_f32_e32 v56, v56
	s_nop 0
	v_cndmask_b32_e64 v75, v75, v56, s[10:11]
	v_mul_f32_e32 v56, v57, v65
	v_fma_f32 v57, v57, v65, v189
	v_mul_f32_e32 v57, 0xbfb8aa3b, v57
	v_exp_f32_e32 v57, v57
	s_nop 0
	v_add_f32_e32 v57, 1.0, v57
	v_rcp_f32_e32 v57, v57
	s_nop 0
	v_cndmask_b32_e64 v76, v56, v57, s[10:11]
	v_fma_f32 v57, v58, v65, v193
	v_mul_f32_e32 v57, 0xbfb8aa3b, v57
	v_exp_f32_e32 v57, v57
	v_mul_f32_e32 v56, v58, v65
	v_cvt_pk_bf16_f32 v58, v75, v76
	v_add_f32_e32 v57, 1.0, v57
	v_rcp_f32_e32 v57, v57
	s_nop 0
	v_cndmask_b32_e64 v77, v56, v57, s[10:11]
	v_fma_f32 v57, v59, v65, v190
	v_mul_f32_e32 v57, 0xbfb8aa3b, v57
	v_exp_f32_e32 v57, v57
	v_mul_f32_e32 v56, v59, v65
	v_add_f32_e32 v57, 1.0, v57
	v_rcp_f32_e32 v57, v57
	s_nop 0
	v_cndmask_b32_e64 v59, v56, v57, s[10:11]
	v_cvt_pk_bf16_f32 v56, v60, v61
	v_cvt_pk_bf16_f32 v57, v62, v63
	v_cvt_pk_bf16_f32 v59, v77, v59
	global_store_dwordx4 v[70:71], v[56:59], off nt
	s_cbranch_vccnz .LBB0_592
	s_and_b64 vcc, exec, s[12:13]
	s_mov_b64 s[6:7], -1
	s_cbranch_vccnz .LBB0_589
	s_andn2_b64 vcc, exec, s[90:91]
	s_cbranch_vccnz .LBB0_586
	s_andn2_b64 vcc, exec, s[88:89]
	s_cbranch_vccnz .LBB0_583
	v_lshl_add_u64 v[56:57], s[0:1], 1, v[68:69]
	v_lshl_add_u64 v[56:57], v[56:57], 0, v[136:137]
	v_lshl_add_u64 v[56:57], v[56:57], 0, s[36:37]
	s_mov_b64 s[6:7], 0

; __device__ __forceinline__ unsigned cvt_pk_bf16(float lo, float hi) { f32x2_t v = {lo, hi}; bf16x2_t b = __builtin_convertvector(v, bf16x2_t); return __builtin_bit_cast(unsigned, b); }
; __device__ __forceinline__ float rstd_of(const float* ss, int row) { return __builtin_amdgcn_rsqf(ss[row] * (1.0f / 1024.0f) + RMS_EPS); }
; __device__ __forceinline__ float sigmoidf_(float v) { return __builtin_amdgcn_rcpf(1.0f + __builtin_amdgcn_exp2f(-v * LOG2E)); }
;     __device__ __forceinline__ void operator()(const Acc& acc, const Unit& u, int wr, int wc, int fr, int fq) const {
;     ...
;                 const int row = row0 + ai * HALF + m * 16; const float rs = rstd_of(ss, row) * sc;
;                 const int b = row >> 11, t = row & (SEQ - 1);
; #pragma unroll
;                 for (int bj = 0; bj < 2; ++bj) {
;                     float o[8];
; #pragma unroll
;                     for (int n = 0; n < 2; ++n)
; #pragma unroll
;                         for (int e = 0; e < 4; ++e) { float v = acc[ai][bj][m][n][e] * rs; if (isg) v = sigmoidf_(v + bv[bj][4 * n + e]); o[4 * n + e] = v; }
;                     u32x4 w; w.x = cvt_pk_bf16(o[0], o[1]); w.y = cvt_pk_bf16(o[2], o[3]); w.z = cvt_pk_bf16(o[4], o[5]); w.w = cvt_pk_bf16(o[6], o[7]);
;                     bf16_t* dst;
;                     if (tile < 4) dst = P + (size_t)row * PP + C_DQ + tile * BM + bj * HALF + cc;
;                     else if (tile < 8) dst = KD + ((size_t)((b * 8 + (tile - 4) * 2 + bj) * SEQ + t)) * 128 + cc;
;                     else if (tile < 12) dst = P + (size_t)row * PP + C_SQ + (tile - 8) * BM + bj * HALF + cc;
;                     else if (tile == 12) { const int ccf = bj * HALF + cc; dst = KS + ((size_t)((b * 4 + (ccf >> 6)) * SEQ + t)) * 64 + (ccf & 63); }
;                     else dst = P + (size_t)row * PP + C_GA + (tile - 13) * BM + bj * HALF + cc;
;                     *(u32x4*)dst = w;
.LBB0_594:
	v_mul_f32_e32 v58, v52, v65
	v_fma_f32 v52, v52, v65, v181
	v_mul_f32_e32 v52, 0xbfb8aa3b, v52
	v_exp_f32_e32 v52, v52
	s_mov_b64 s[94:95], -1
	s_and_b64 vcc, exec, s[14:15]
	v_add_f32_e32 v52, 1.0, v52
	v_rcp_f32_e32 v52, v52
	s_nop 0
	v_cndmask_b32_e64 v52, v58, v52, s[10:11]
	v_mul_f32_e32 v58, v53, v65
	v_fma_f32 v53, v53, v65, v174
	v_mul_f32_e32 v53, 0xbfb8aa3b, v53
	v_exp_f32_e32 v53, v53
	s_nop 0
	v_add_f32_e32 v53, 1.0, v53
	v_rcp_f32_e32 v53, v53
	s_nop 0
	v_cndmask_b32_e64 v53, v58, v53, s[10:11]
	v_mul_f32_e32 v58, v54, v65
	v_fma_f32 v54, v54, v65, v183
	v_mul_f32_e32 v54, 0xbfb8aa3b, v54
	v_exp_f32_e32 v54, v54
	s_nop 0
	v_add_f32_e32 v54, 1.0, v54
	v_rcp_f32_e32 v54, v54
	s_nop 0
	v_cndmask_b32_e64 v54, v58, v54, s[10:11]
	v_mul_f32_e32 v58, v55, v65
	v_fma_f32 v55, v55, v65, v178
	v_mul_f32_e32 v55, 0xbfb8aa3b, v55
	v_exp_f32_e32 v55, v55
	s_nop 0
	v_add_f32_e32 v55, 1.0, v55
	v_rcp_f32_e32 v55, v55
	s_nop 0
	v_cndmask_b32_e64 v55, v58, v55, s[10:11]
	v_mul_f32_e32 v58, v48, v65
	v_fma_f32 v48, v48, v65, v184
	v_mul_f32_e32 v48, 0xbfb8aa3b, v48
	v_exp_f32_e32 v48, v48
	s_nop 0
	v_add_f32_e32 v48, 1.0, v48
	v_rcp_f32_e32 v48, v48
	s_nop 0
	v_cndmask_b32_e64 v58, v58, v48, s[10:11]
	v_mul_f32_e32 v48, v49, v65
	v_fma_f32 v49, v49, v65, v180
	v_mul_f32_e32 v49, 0xbfb8aa3b, v49
	v_exp_f32_e32 v49, v49
	s_nop 0
	v_add_f32_e32 v49, 1.0, v49
	v_rcp_f32_e32 v49, v49
	s_nop 0
	v_cndmask_b32_e64 v59, v48, v49, s[10:11]
	v_fma_f32 v49, v50, v65, v185
	v_mul_f32_e32 v49, 0xbfb8aa3b, v49
	v_exp_f32_e32 v49, v49
	v_mul_f32_e32 v48, v50, v65
	v_cvt_pk_bf16_f32 v50, v58, v59
	v_add_f32_e32 v49, 1.0, v49
	v_rcp_f32_e32 v49, v49
	s_nop 0
	v_cndmask_b32_e64 v60, v48, v49, s[10:11]
	v_fma_f32 v49, v51, v65, v182
	v_mul_f32_e32 v49, 0xbfb8aa3b, v49
	v_exp_f32_e32 v49, v49
	v_mul_f32_e32 v48, v51, v65
	v_add_f32_e32 v49, 1.0, v49
	v_rcp_f32_e32 v49, v49
	s_nop 0
	v_cndmask_b32_e64 v51, v48, v49, s[10:11]
	v_cvt_pk_bf16_f32 v48, v52, v53
	v_cvt_pk_bf16_f32 v49, v54, v55
	v_cvt_pk_bf16_f32 v51, v60, v51
	global_store_dwordx4 v[56:57], v[48:51], off nt
	global_load_dword v57, v[154:155], off offset:576
	s_nop 0
	v_add_u32_e32 v48, 0x90, v152
	v_ashrrev_i32_e32 v49, 31, v48
	v_and_b32_e32 v56, 0x7df, v48
	v_lshlrev_b64 v[50:51], 13, v[48:49]
	v_or_b32_e32 v48, v73, v56
	s_cbranch_vccnz .LBB0_608
	s_and_b64 vcc, exec, s[12:13]
	s_mov_b64 s[6:7], -1
	s_cbranch_vccnz .LBB0_605
	s_andn2_b64 vcc, exec, s[90:91]
	s_cbranch_vccnz .LBB0_602
	s_andn2_b64 vcc, exec, s[88:89]
	s_cbranch_vccnz .LBB0_599
	v_lshl_add_u64 v[52:53], s[20:21], 0, v[50:51]
	v_lshl_add_u64 v[52:53], s[0:1], 1, v[52:53]
	v_lshl_add_u64 v[52:53], v[52:53], 0, v[136:137]
	v_lshl_add_u64 v[54:55], v[52:53], 0, s[30:31]
	s_mov_b64 s[6:7], 0

; __device__ __forceinline__ unsigned cvt_pk_bf16(float lo, float hi) { f32x2_t v = {lo, hi}; bf16x2_t b = __builtin_convertvector(v, bf16x2_t); return __builtin_bit_cast(unsigned, b); }
; __device__ __forceinline__ float rstd_of(const float* ss, int row) { return __builtin_amdgcn_rsqf(ss[row] * (1.0f / 1024.0f) + RMS_EPS); }
; __device__ __forceinline__ float sigmoidf_(float v) { return __builtin_amdgcn_rcpf(1.0f + __builtin_amdgcn_exp2f(-v * LOG2E)); }
;     __device__ __forceinline__ void operator()(const Acc& acc, const Unit& u, int wr, int wc, int fr, int fq) const {
;     ...
;                 const int row = row0 + ai * HALF + m * 16; const float rs = rstd_of(ss, row) * sc;
;                 const int b = row >> 11, t = row & (SEQ - 1);
; #pragma unroll
;                 for (int bj = 0; bj < 2; ++bj) {
;                     float o[8];
; #pragma unroll
;                     for (int n = 0; n < 2; ++n)
; #pragma unroll
;                         for (int e = 0; e < 4; ++e) { float v = acc[ai][bj][m][n][e] * rs; if (isg) v = sigmoidf_(v + bv[bj][4 * n + e]); o[4 * n + e] = v; }
;                     u32x4 w; w.x = cvt_pk_bf16(o[0], o[1]); w.y = cvt_pk_bf16(o[2], o[3]); w.z = cvt_pk_bf16(o[4], o[5]); w.w = cvt_pk_bf16(o[6], o[7]);
;                     bf16_t* dst;
;                     if (tile < 4) dst = P + (size_t)row * PP + C_DQ + tile * BM + bj * HALF + cc;
;                     else if (tile < 8) dst = KD + ((size_t)((b * 8 + (tile - 4) * 2 + bj) * SEQ + t)) * 128 + cc;
;                     else if (tile < 12) dst = P + (size_t)row * PP + C_SQ + (tile - 8) * BM + bj * HALF + cc;
;                     else if (tile == 12) { const int ccf = bj * HALF + cc; dst = KS + ((size_t)((b * 4 + (ccf >> 6)) * SEQ + t)) * 64 + (ccf & 63); }
;                     else dst = P + (size_t)row * PP + C_GA + (tile - 13) * BM + bj * HALF + cc;
;                     *(u32x4*)dst = w;
.LBB0_610:
	s_waitcnt vmcnt(0)
	v_fmamk_f32 v49, v57, 0x3a800000, v170
	v_rsq_f32_e32 v49, v49
	s_mov_b64 s[94:95], -1
	s_and_b64 vcc, exec, s[14:15]
	v_mul_f32_e32 v49, v153, v49
	v_mul_f32_e32 v57, v44, v49
	v_fma_f32 v44, v44, v49, v187
	v_mul_f32_e32 v44, 0xbfb8aa3b, v44
	v_exp_f32_e32 v44, v44
	s_nop 0
	v_add_f32_e32 v44, 1.0, v44
	v_rcp_f32_e32 v44, v44
	s_nop 0
	v_cndmask_b32_e64 v44, v57, v44, s[10:11]
	v_mul_f32_e32 v57, v45, v49
	v_fma_f32 v45, v45, v49, v186
	v_mul_f32_e32 v45, 0xbfb8aa3b, v45
	v_exp_f32_e32 v45, v45
	s_nop 0
	v_add_f32_e32 v45, 1.0, v45
	v_rcp_f32_e32 v45, v45
	s_nop 0
	v_cndmask_b32_e64 v45, v57, v45, s[10:11]
	v_mul_f32_e32 v57, v46, v49
	v_fma_f32 v46, v46, v49, v191
	v_mul_f32_e32 v46, 0xbfb8aa3b, v46
	v_exp_f32_e32 v46, v46
	s_nop 0
	v_add_f32_e32 v46, 1.0, v46
	v_rcp_f32_e32 v46, v46
	s_nop 0
	v_cndmask_b32_e64 v46, v57, v46, s[10:11]
	v_mul_f32_e32 v57, v47, v49
	v_fma_f32 v47, v47, v49, v188
	v_mul_f32_e32 v47, 0xbfb8aa3b, v47
	v_exp_f32_e32 v47, v47
	s_nop 0
	v_add_f32_e32 v47, 1.0, v47
	v_rcp_f32_e32 v47, v47
	s_nop 0
	v_cndmask_b32_e64 v47, v57, v47, s[10:11]
	v_mul_f32_e32 v57, v40, v49
	v_fma_f32 v40, v40, v49, v192
	v_mul_f32_e32 v40, 0xbfb8aa3b, v40
	v_exp_f32_e32 v40, v40
	s_nop 0
	v_add_f32_e32 v40, 1.0, v40
	v_rcp_f32_e32 v40, v40
	s_nop 0
	v_cndmask_b32_e64 v57, v57, v40, s[10:11]
	v_mul_f32_e32 v40, v41, v49
	v_fma_f32 v41, v41, v49, v189
	v_mul_f32_e32 v41, 0xbfb8aa3b, v41
	v_exp_f32_e32 v41, v41
	s_nop 0
	v_add_f32_e32 v41, 1.0, v41
	v_rcp_f32_e32 v41, v41
	s_nop 0
	v_cndmask_b32_e64 v58, v40, v41, s[10:11]
	v_fma_f32 v41, v42, v49, v193
	v_mul_f32_e32 v41, 0xbfb8aa3b, v41
	v_exp_f32_e32 v41, v41
	v_mul_f32_e32 v40, v42, v49
	v_cvt_pk_bf16_f32 v42, v57, v58
	v_add_f32_e32 v41, 1.0, v41
	v_rcp_f32_e32 v41, v41
	s_nop 0
	v_cndmask_b32_e64 v59, v40, v41, s[10:11]
	v_fma_f32 v41, v43, v49, v190
	v_mul_f32_e32 v41, 0xbfb8aa3b, v41
	v_exp_f32_e32 v41, v41
	v_mul_f32_e32 v40, v43, v49
	v_add_f32_e32 v41, 1.0, v41
	v_rcp_f32_e32 v41, v41
	s_nop 0
	v_cndmask_b32_e64 v43, v40, v41, s[10:11]
	v_cvt_pk_bf16_f32 v40, v44, v45
	v_cvt_pk_bf16_f32 v41, v46, v47
	v_cvt_pk_bf16_f32 v43, v59, v43
	global_store_dwordx4 v[54:55], v[40:43], off nt
	s_cbranch_vccnz .LBB0_624
	s_and_b64 vcc, exec, s[12:13]
	s_mov_b64 s[6:7], -1
	s_cbranch_vccnz .LBB0_621
	s_andn2_b64 vcc, exec, s[90:91]
	s_cbranch_vccnz .LBB0_618
	s_andn2_b64 vcc, exec, s[88:89]
	s_cbranch_vccnz .LBB0_615
	v_lshl_add_u64 v[40:41], s[0:1], 1, v[52:53]
	v_lshl_add_u64 v[40:41], v[40:41], 0, v[136:137]
	v_lshl_add_u64 v[40:41], v[40:41], 0, s[36:37]
	s_mov_b64 s[6:7], 0

; __device__ __forceinline__ unsigned cvt_pk_bf16(float lo, float hi) { f32x2_t v = {lo, hi}; bf16x2_t b = __builtin_convertvector(v, bf16x2_t); return __builtin_bit_cast(unsigned, b); }
; __device__ __forceinline__ float rstd_of(const float* ss, int row) { return __builtin_amdgcn_rsqf(ss[row] * (1.0f / 1024.0f) + RMS_EPS); }
; __device__ __forceinline__ float sigmoidf_(float v) { return __builtin_amdgcn_rcpf(1.0f + __builtin_amdgcn_exp2f(-v * LOG2E)); }
;     __device__ __forceinline__ void operator()(const Acc& acc, const Unit& u, int wr, int wc, int fr, int fq) const {
;     ...
;                 const int row = row0 + ai * HALF + m * 16; const float rs = rstd_of(ss, row) * sc;
;                 const int b = row >> 11, t = row & (SEQ - 1);
; #pragma unroll
;                 for (int bj = 0; bj < 2; ++bj) {
;                     float o[8];
; #pragma unroll
;                     for (int n = 0; n < 2; ++n)
; #pragma unroll
;                         for (int e = 0; e < 4; ++e) { float v = acc[ai][bj][m][n][e] * rs; if (isg) v = sigmoidf_(v + bv[bj][4 * n + e]); o[4 * n + e] = v; }
;                     u32x4 w; w.x = cvt_pk_bf16(o[0], o[1]); w.y = cvt_pk_bf16(o[2], o[3]); w.z = cvt_pk_bf16(o[4], o[5]); w.w = cvt_pk_bf16(o[6], o[7]);
;                     bf16_t* dst;
;                     if (tile < 4) dst = P + (size_t)row * PP + C_DQ + tile * BM + bj * HALF + cc;
;                     else if (tile < 8) dst = KD + ((size_t)((b * 8 + (tile - 4) * 2 + bj) * SEQ + t)) * 128 + cc;
;                     else if (tile < 12) dst = P + (size_t)row * PP + C_SQ + (tile - 8) * BM + bj * HALF + cc;
;                     else if (tile == 12) { const int ccf = bj * HALF + cc; dst = KS + ((size_t)((b * 4 + (ccf >> 6)) * SEQ + t)) * 64 + (ccf & 63); }
;                     else dst = P + (size_t)row * PP + C_GA + (tile - 13) * BM + bj * HALF + cc;
;                     *(u32x4*)dst = w;
.LBB0_626:
	v_mul_f32_e32 v42, v36, v49
	v_fma_f32 v36, v36, v49, v181
	v_mul_f32_e32 v36, 0xbfb8aa3b, v36
	v_exp_f32_e32 v36, v36
	s_mov_b64 s[94:95], -1
	s_and_b64 vcc, exec, s[14:15]
	v_add_f32_e32 v36, 1.0, v36
	v_rcp_f32_e32 v36, v36
	s_nop 0
	v_cndmask_b32_e64 v36, v42, v36, s[10:11]
	v_mul_f32_e32 v42, v37, v49
	v_fma_f32 v37, v37, v49, v174
	v_mul_f32_e32 v37, 0xbfb8aa3b, v37
	v_exp_f32_e32 v37, v37
	s_nop 0
	v_add_f32_e32 v37, 1.0, v37
	v_rcp_f32_e32 v37, v37
	s_nop 0
	v_cndmask_b32_e64 v37, v42, v37, s[10:11]
	v_mul_f32_e32 v42, v38, v49
	v_fma_f32 v38, v38, v49, v183
	v_mul_f32_e32 v38, 0xbfb8aa3b, v38
	v_exp_f32_e32 v38, v38
	s_nop 0
	v_add_f32_e32 v38, 1.0, v38
	v_rcp_f32_e32 v38, v38
	s_nop 0
	v_cndmask_b32_e64 v38, v42, v38, s[10:11]
	v_mul_f32_e32 v42, v39, v49
	v_fma_f32 v39, v39, v49, v178
	v_mul_f32_e32 v39, 0xbfb8aa3b, v39
	v_exp_f32_e32 v39, v39
	s_nop 0
	v_add_f32_e32 v39, 1.0, v39
	v_rcp_f32_e32 v39, v39
	s_nop 0
	v_cndmask_b32_e64 v39, v42, v39, s[10:11]
	v_mul_f32_e32 v42, v32, v49
	v_fma_f32 v32, v32, v49, v184
	v_mul_f32_e32 v32, 0xbfb8aa3b, v32
	v_exp_f32_e32 v32, v32
	s_nop 0
	v_add_f32_e32 v32, 1.0, v32
	v_rcp_f32_e32 v32, v32
	s_nop 0
	v_cndmask_b32_e64 v42, v42, v32, s[10:11]
	v_mul_f32_e32 v32, v33, v49
	v_fma_f32 v33, v33, v49, v180
	v_mul_f32_e32 v33, 0xbfb8aa3b, v33
	v_exp_f32_e32 v33, v33
	s_nop 0
	v_add_f32_e32 v33, 1.0, v33
	v_rcp_f32_e32 v33, v33
	s_nop 0
	v_cndmask_b32_e64 v43, v32, v33, s[10:11]
	v_fma_f32 v33, v34, v49, v185
	v_mul_f32_e32 v33, 0xbfb8aa3b, v33
	v_exp_f32_e32 v33, v33
	v_mul_f32_e32 v32, v34, v49
	v_cvt_pk_bf16_f32 v34, v42, v43
	v_add_f32_e32 v33, 1.0, v33
	v_rcp_f32_e32 v33, v33
	s_nop 0
	v_cndmask_b32_e64 v44, v32, v33, s[10:11]
	v_fma_f32 v33, v35, v49, v182
	v_mul_f32_e32 v33, 0xbfb8aa3b, v33
	v_exp_f32_e32 v33, v33
	v_mul_f32_e32 v32, v35, v49
	v_add_f32_e32 v33, 1.0, v33
	v_rcp_f32_e32 v33, v33
	s_nop 0
	v_cndmask_b32_e64 v35, v32, v33, s[10:11]
	v_cvt_pk_bf16_f32 v32, v36, v37
	v_cvt_pk_bf16_f32 v33, v38, v39
	v_cvt_pk_bf16_f32 v35, v44, v35
	global_store_dwordx4 v[40:41], v[32:35], off nt
	global_load_dword v41, v[154:155], off offset:640
	s_nop 0
	v_add_u32_e32 v32, 0xa0, v152
	v_ashrrev_i32_e32 v33, 31, v32
	v_and_b32_e32 v40, 0x7ef, v32
	v_lshlrev_b64 v[34:35], 13, v[32:33]
	v_or_b32_e32 v32, v73, v40
	s_cbranch_vccnz .LBB0_640
	s_and_b64 vcc, exec, s[12:13]
	s_mov_b64 s[6:7], -1
	s_cbranch_vccnz .LBB0_637
	s_andn2_b64 vcc, exec, s[90:91]
	s_cbranch_vccnz .LBB0_634
	s_andn2_b64 vcc, exec, s[88:89]
	s_cbranch_vccnz .LBB0_631
	v_lshl_add_u64 v[36:37], s[20:21], 0, v[34:35]
	v_lshl_add_u64 v[36:37], s[0:1], 1, v[36:37]
	v_lshl_add_u64 v[36:37], v[36:37], 0, v[136:137]
	v_lshl_add_u64 v[38:39], v[36:37], 0, s[30:31]
	s_mov_b64 s[6:7], 0

; __device__ __forceinline__ unsigned cvt_pk_bf16(float lo, float hi) { f32x2_t v = {lo, hi}; bf16x2_t b = __builtin_convertvector(v, bf16x2_t); return __builtin_bit_cast(unsigned, b); }
; __device__ __forceinline__ float rstd_of(const float* ss, int row) { return __builtin_amdgcn_rsqf(ss[row] * (1.0f / 1024.0f) + RMS_EPS); }
; __device__ __forceinline__ float sigmoidf_(float v) { return __builtin_amdgcn_rcpf(1.0f + __builtin_amdgcn_exp2f(-v * LOG2E)); }
;     __device__ __forceinline__ void operator()(const Acc& acc, const Unit& u, int wr, int wc, int fr, int fq) const {
;     ...
;                 const int row = row0 + ai * HALF + m * 16; const float rs = rstd_of(ss, row) * sc;
;                 const int b = row >> 11, t = row & (SEQ - 1);
; #pragma unroll
;                 for (int bj = 0; bj < 2; ++bj) {
;                     float o[8];
; #pragma unroll
;                     for (int n = 0; n < 2; ++n)
; #pragma unroll
;                         for (int e = 0; e < 4; ++e) { float v = acc[ai][bj][m][n][e] * rs; if (isg) v = sigmoidf_(v + bv[bj][4 * n + e]); o[4 * n + e] = v; }
;                     u32x4 w; w.x = cvt_pk_bf16(o[0], o[1]); w.y = cvt_pk_bf16(o[2], o[3]); w.z = cvt_pk_bf16(o[4], o[5]); w.w = cvt_pk_bf16(o[6], o[7]);
;                     bf16_t* dst;
;                     if (tile < 4) dst = P + (size_t)row * PP + C_DQ + tile * BM + bj * HALF + cc;
;                     else if (tile < 8) dst = KD + ((size_t)((b * 8 + (tile - 4) * 2 + bj) * SEQ + t)) * 128 + cc;
;                     else if (tile < 12) dst = P + (size_t)row * PP + C_SQ + (tile - 8) * BM + bj * HALF + cc;
;                     else if (tile == 12) { const int ccf = bj * HALF + cc; dst = KS + ((size_t)((b * 4 + (ccf >> 6)) * SEQ + t)) * 64 + (ccf & 63); }
;                     else dst = P + (size_t)row * PP + C_GA + (tile - 13) * BM + bj * HALF + cc;
;                     *(u32x4*)dst = w;
.LBB0_642:
	s_waitcnt vmcnt(0)
	v_fmamk_f32 v33, v41, 0x3a800000, v170
	v_rsq_f32_e32 v33, v33
	s_mov_b64 s[94:95], -1
	s_and_b64 vcc, exec, s[14:15]
	v_mul_f32_e32 v33, v153, v33
	v_mul_f32_e32 v41, v28, v33
	v_fma_f32 v28, v28, v33, v187
	v_mul_f32_e32 v28, 0xbfb8aa3b, v28
	v_exp_f32_e32 v28, v28
	s_nop 0
	v_add_f32_e32 v28, 1.0, v28
	v_rcp_f32_e32 v28, v28
	s_nop 0
	v_cndmask_b32_e64 v28, v41, v28, s[10:11]
	v_mul_f32_e32 v41, v29, v33
	v_fma_f32 v29, v29, v33, v186
	v_mul_f32_e32 v29, 0xbfb8aa3b, v29
	v_exp_f32_e32 v29, v29
	s_nop 0
	v_add_f32_e32 v29, 1.0, v29
	v_rcp_f32_e32 v29, v29
	s_nop 0
	v_cndmask_b32_e64 v29, v41, v29, s[10:11]
	v_mul_f32_e32 v41, v30, v33
	v_fma_f32 v30, v30, v33, v191
	v_mul_f32_e32 v30, 0xbfb8aa3b, v30
	v_exp_f32_e32 v30, v30
	s_nop 0
	v_add_f32_e32 v30, 1.0, v30
	v_rcp_f32_e32 v30, v30
	s_nop 0
	v_cndmask_b32_e64 v30, v41, v30, s[10:11]
	v_mul_f32_e32 v41, v31, v33
	v_fma_f32 v31, v31, v33, v188
	v_mul_f32_e32 v31, 0xbfb8aa3b, v31
	v_exp_f32_e32 v31, v31
	s_nop 0
	v_add_f32_e32 v31, 1.0, v31
	v_rcp_f32_e32 v31, v31
	s_nop 0
	v_cndmask_b32_e64 v31, v41, v31, s[10:11]
	v_mul_f32_e32 v41, v24, v33
	v_fma_f32 v24, v24, v33, v192
	v_mul_f32_e32 v24, 0xbfb8aa3b, v24
	v_exp_f32_e32 v24, v24
	s_nop 0
	v_add_f32_e32 v24, 1.0, v24
	v_rcp_f32_e32 v24, v24
	s_nop 0
	v_cndmask_b32_e64 v41, v41, v24, s[10:11]
	v_mul_f32_e32 v24, v25, v33
	v_fma_f32 v25, v25, v33, v189
	v_mul_f32_e32 v25, 0xbfb8aa3b, v25
	v_exp_f32_e32 v25, v25
	s_nop 0
	v_add_f32_e32 v25, 1.0, v25
	v_rcp_f32_e32 v25, v25
	s_nop 0
	v_cndmask_b32_e64 v42, v24, v25, s[10:11]
	v_fma_f32 v25, v26, v33, v193
	v_mul_f32_e32 v25, 0xbfb8aa3b, v25
	v_exp_f32_e32 v25, v25
	v_mul_f32_e32 v24, v26, v33
	v_cvt_pk_bf16_f32 v26, v41, v42
	v_add_f32_e32 v25, 1.0, v25
	v_rcp_f32_e32 v25, v25
	s_nop 0
	v_cndmask_b32_e64 v43, v24, v25, s[10:11]
	v_fma_f32 v25, v27, v33, v190
	v_mul_f32_e32 v25, 0xbfb8aa3b, v25
	v_exp_f32_e32 v25, v25
	v_mul_f32_e32 v24, v27, v33
	v_add_f32_e32 v25, 1.0, v25
	v_rcp_f32_e32 v25, v25
	s_nop 0
	v_cndmask_b32_e64 v27, v24, v25, s[10:11]
	v_cvt_pk_bf16_f32 v24, v28, v29
	v_cvt_pk_bf16_f32 v25, v30, v31
	v_cvt_pk_bf16_f32 v27, v43, v27
	global_store_dwordx4 v[38:39], v[24:27], off nt
	s_cbranch_vccnz .LBB0_656
	s_and_b64 vcc, exec, s[12:13]
	s_mov_b64 s[6:7], -1
	s_cbranch_vccnz .LBB0_653
	s_andn2_b64 vcc, exec, s[90:91]
	s_cbranch_vccnz .LBB0_650
	s_andn2_b64 vcc, exec, s[88:89]
	s_cbranch_vccnz .LBB0_647
	v_lshl_add_u64 v[24:25], s[0:1], 1, v[36:37]
	v_lshl_add_u64 v[24:25], v[24:25], 0, v[136:137]
	v_lshl_add_u64 v[24:25], v[24:25], 0, s[36:37]
	s_mov_b64 s[6:7], 0

; __device__ __forceinline__ unsigned cvt_pk_bf16(float lo, float hi) { f32x2_t v = {lo, hi}; bf16x2_t b = __builtin_convertvector(v, bf16x2_t); return __builtin_bit_cast(unsigned, b); }
; __device__ __forceinline__ float rstd_of(const float* ss, int row) { return __builtin_amdgcn_rsqf(ss[row] * (1.0f / 1024.0f) + RMS_EPS); }
; __device__ __forceinline__ float sigmoidf_(float v) { return __builtin_amdgcn_rcpf(1.0f + __builtin_amdgcn_exp2f(-v * LOG2E)); }
;     __device__ __forceinline__ void operator()(const Acc& acc, const Unit& u, int wr, int wc, int fr, int fq) const {
;     ...
;                 const int row = row0 + ai * HALF + m * 16; const float rs = rstd_of(ss, row) * sc;
;                 const int b = row >> 11, t = row & (SEQ - 1);
; #pragma unroll
;                 for (int bj = 0; bj < 2; ++bj) {
;                     float o[8];
; #pragma unroll
;                     for (int n = 0; n < 2; ++n)
; #pragma unroll
;                         for (int e = 0; e < 4; ++e) { float v = acc[ai][bj][m][n][e] * rs; if (isg) v = sigmoidf_(v + bv[bj][4 * n + e]); o[4 * n + e] = v; }
;                     u32x4 w; w.x = cvt_pk_bf16(o[0], o[1]); w.y = cvt_pk_bf16(o[2], o[3]); w.z = cvt_pk_bf16(o[4], o[5]); w.w = cvt_pk_bf16(o[6], o[7]);
;                     bf16_t* dst;
;                     if (tile < 4) dst = P + (size_t)row * PP + C_DQ + tile * BM + bj * HALF + cc;
;                     else if (tile < 8) dst = KD + ((size_t)((b * 8 + (tile - 4) * 2 + bj) * SEQ + t)) * 128 + cc;
;                     else if (tile < 12) dst = P + (size_t)row * PP + C_SQ + (tile - 8) * BM + bj * HALF + cc;
;                     else if (tile == 12) { const int ccf = bj * HALF + cc; dst = KS + ((size_t)((b * 4 + (ccf >> 6)) * SEQ + t)) * 64 + (ccf & 63); }
;                     else dst = P + (size_t)row * PP + C_GA + (tile - 13) * BM + bj * HALF + cc;
;                     *(u32x4*)dst = w;
.LBB0_658:
	v_mul_f32_e32 v26, v20, v33
	v_fma_f32 v20, v20, v33, v181
	v_mul_f32_e32 v20, 0xbfb8aa3b, v20
	v_exp_f32_e32 v20, v20
	s_mov_b64 s[94:95], -1
	s_and_b64 vcc, exec, s[14:15]
	v_add_f32_e32 v20, 1.0, v20
	v_rcp_f32_e32 v20, v20
	s_nop 0
	v_cndmask_b32_e64 v20, v26, v20, s[10:11]
	v_mul_f32_e32 v26, v21, v33
	v_fma_f32 v21, v21, v33, v174
	v_mul_f32_e32 v21, 0xbfb8aa3b, v21
	v_exp_f32_e32 v21, v21
	s_nop 0
	v_add_f32_e32 v21, 1.0, v21
	v_rcp_f32_e32 v21, v21
	s_nop 0
	v_cndmask_b32_e64 v21, v26, v21, s[10:11]
	v_mul_f32_e32 v26, v22, v33
	v_fma_f32 v22, v22, v33, v183
	v_mul_f32_e32 v22, 0xbfb8aa3b, v22
	v_exp_f32_e32 v22, v22
	s_nop 0
	v_add_f32_e32 v22, 1.0, v22
	v_rcp_f32_e32 v22, v22
	s_nop 0
	v_cndmask_b32_e64 v22, v26, v22, s[10:11]
	v_mul_f32_e32 v26, v23, v33
	v_fma_f32 v23, v23, v33, v178
	v_mul_f32_e32 v23, 0xbfb8aa3b, v23
	v_exp_f32_e32 v23, v23
	s_nop 0
	v_add_f32_e32 v23, 1.0, v23
	v_rcp_f32_e32 v23, v23
	s_nop 0
	v_cndmask_b32_e64 v23, v26, v23, s[10:11]
	v_mul_f32_e32 v26, v16, v33
	v_fma_f32 v16, v16, v33, v184
	v_mul_f32_e32 v16, 0xbfb8aa3b, v16
	v_exp_f32_e32 v16, v16
	s_nop 0
	v_add_f32_e32 v16, 1.0, v16
	v_rcp_f32_e32 v16, v16
	s_nop 0
	v_cndmask_b32_e64 v26, v26, v16, s[10:11]
	v_mul_f32_e32 v16, v17, v33
	v_fma_f32 v17, v17, v33, v180
	v_mul_f32_e32 v17, 0xbfb8aa3b, v17
	v_exp_f32_e32 v17, v17
	s_nop 0
	v_add_f32_e32 v17, 1.0, v17
	v_rcp_f32_e32 v17, v17
	s_nop 0
	v_cndmask_b32_e64 v27, v16, v17, s[10:11]
	v_fma_f32 v17, v18, v33, v185
	v_mul_f32_e32 v17, 0xbfb8aa3b, v17
	v_exp_f32_e32 v17, v17
	v_mul_f32_e32 v16, v18, v33
	v_cvt_pk_bf16_f32 v18, v26, v27
	v_add_f32_e32 v17, 1.0, v17
	v_rcp_f32_e32 v17, v17
	s_nop 0
	v_cndmask_b32_e64 v28, v16, v17, s[10:11]
	v_fma_f32 v17, v19, v33, v182
	v_mul_f32_e32 v17, 0xbfb8aa3b, v17
	v_exp_f32_e32 v17, v17
	v_mul_f32_e32 v16, v19, v33
	v_add_f32_e32 v17, 1.0, v17
	v_rcp_f32_e32 v17, v17
	s_nop 0
	v_cndmask_b32_e64 v19, v16, v17, s[10:11]
	v_cvt_pk_bf16_f32 v16, v20, v21
	v_cvt_pk_bf16_f32 v17, v22, v23
	v_cvt_pk_bf16_f32 v19, v28, v19
	global_store_dwordx4 v[24:25], v[16:19], off nt
	global_load_dword v25, v[154:155], off offset:704
	s_nop 0
	v_add_u32_e32 v16, 0xb0, v152
	v_ashrrev_i32_e32 v17, 31, v16
	v_and_b32_e32 v24, 0x7ff, v16
	v_lshlrev_b64 v[18:19], 13, v[16:17]
	v_or_b32_e32 v16, v73, v24
	s_cbranch_vccnz .LBB0_672
	s_and_b64 vcc, exec, s[12:13]
	s_mov_b64 s[6:7], -1
	s_cbranch_vccnz .LBB0_669
	s_andn2_b64 vcc, exec, s[90:91]
	s_cbranch_vccnz .LBB0_666
	s_andn2_b64 vcc, exec, s[88:89]
	s_cbranch_vccnz .LBB0_663
	v_lshl_add_u64 v[20:21], s[20:21], 0, v[18:19]
	v_lshl_add_u64 v[20:21], s[0:1], 1, v[20:21]
	v_lshl_add_u64 v[20:21], v[20:21], 0, v[136:137]
	v_lshl_add_u64 v[22:23], v[20:21], 0, s[30:31]
	s_mov_b64 s[6:7], 0

; __device__ __forceinline__ unsigned cvt_pk_bf16(float lo, float hi) { f32x2_t v = {lo, hi}; bf16x2_t b = __builtin_convertvector(v, bf16x2_t); return __builtin_bit_cast(unsigned, b); }
; __device__ __forceinline__ float rstd_of(const float* ss, int row) { return __builtin_amdgcn_rsqf(ss[row] * (1.0f / 1024.0f) + RMS_EPS); }
; __device__ __forceinline__ float sigmoidf_(float v) { return __builtin_amdgcn_rcpf(1.0f + __builtin_amdgcn_exp2f(-v * LOG2E)); }
;     __device__ __forceinline__ void operator()(const Acc& acc, const Unit& u, int wr, int wc, int fr, int fq) const {
;     ...
;                 const int row = row0 + ai * HALF + m * 16; const float rs = rstd_of(ss, row) * sc;
;                 const int b = row >> 11, t = row & (SEQ - 1);
; #pragma unroll
;                 for (int bj = 0; bj < 2; ++bj) {
;                     float o[8];
; #pragma unroll
;                     for (int n = 0; n < 2; ++n)
; #pragma unroll
;                         for (int e = 0; e < 4; ++e) { float v = acc[ai][bj][m][n][e] * rs; if (isg) v = sigmoidf_(v + bv[bj][4 * n + e]); o[4 * n + e] = v; }
;                     u32x4 w; w.x = cvt_pk_bf16(o[0], o[1]); w.y = cvt_pk_bf16(o[2], o[3]); w.z = cvt_pk_bf16(o[4], o[5]); w.w = cvt_pk_bf16(o[6], o[7]);
;                     bf16_t* dst;
;                     if (tile < 4) dst = P + (size_t)row * PP + C_DQ + tile * BM + bj * HALF + cc;
;                     else if (tile < 8) dst = KD + ((size_t)((b * 8 + (tile - 4) * 2 + bj) * SEQ + t)) * 128 + cc;
;                     else if (tile < 12) dst = P + (size_t)row * PP + C_SQ + (tile - 8) * BM + bj * HALF + cc;
;                     else if (tile == 12) { const int ccf = bj * HALF + cc; dst = KS + ((size_t)((b * 4 + (ccf >> 6)) * SEQ + t)) * 64 + (ccf & 63); }
;                     else dst = P + (size_t)row * PP + C_GA + (tile - 13) * BM + bj * HALF + cc;
;                     *(u32x4*)dst = w;
.LBB0_674:
	s_waitcnt vmcnt(0)
	v_fmamk_f32 v17, v25, 0x3a800000, v170
	v_rsq_f32_e32 v17, v17
	s_and_b64 vcc, exec, s[14:15]
	s_mov_b64 s[6:7], -1
	v_mul_f32_e32 v17, v153, v17
	v_fmac_f32_e32 v187, v12, v17
	v_fmac_f32_e32 v186, v13, v17
	v_mul_f32_e32 v25, 0xbfb8aa3b, v187
	v_mul_f32_e32 v26, 0xbfb8aa3b, v186
	v_exp_f32_e32 v25, v25
	v_exp_f32_e32 v26, v26
	v_mul_f32_e32 v12, v12, v17
	v_mul_f32_e32 v13, v13, v17
	v_add_f32_e32 v25, 1.0, v25
	v_add_f32_e32 v26, 1.0, v26
	v_rcp_f32_e32 v25, v25
	v_rcp_f32_e32 v26, v26
	v_fmac_f32_e32 v191, v14, v17
	v_fmac_f32_e32 v188, v15, v17
	v_cndmask_b32_e64 v12, v12, v25, s[10:11]
	v_cndmask_b32_e64 v13, v13, v26, s[10:11]
	v_mul_f32_e32 v25, 0xbfb8aa3b, v191
	v_mul_f32_e32 v26, 0xbfb8aa3b, v188
	v_exp_f32_e32 v25, v25
	v_exp_f32_e32 v26, v26
	v_fmac_f32_e32 v192, v8, v17
	v_mul_f32_e32 v27, 0xbfb8aa3b, v192
	v_add_f32_e32 v25, 1.0, v25
	v_add_f32_e32 v26, 1.0, v26
	v_rcp_f32_e32 v25, v25
	v_rcp_f32_e32 v26, v26
	v_exp_f32_e32 v27, v27
	v_mul_f32_e32 v14, v14, v17
	v_mul_f32_e32 v15, v15, v17
	v_fmac_f32_e32 v189, v9, v17
	v_cndmask_b32_e64 v14, v14, v25, s[10:11]
	v_cndmask_b32_e64 v15, v15, v26, s[10:11]
	v_add_f32_e32 v25, 1.0, v27
	v_mul_f32_e32 v26, 0xbfb8aa3b, v189
	v_rcp_f32_e32 v25, v25
	v_exp_f32_e32 v26, v26
	v_mul_f32_e32 v8, v8, v17
	v_fmac_f32_e32 v193, v10, v17
	v_cndmask_b32_e64 v25, v8, v25, s[10:11]
	v_mul_f32_e32 v8, v9, v17
	v_add_f32_e32 v9, 1.0, v26
	v_mul_f32_e32 v26, 0xbfb8aa3b, v193
	v_fmac_f32_e32 v190, v11, v17
	v_rcp_f32_e32 v9, v9
	v_exp_f32_e32 v26, v26
	v_mul_f32_e32 v27, 0xbfb8aa3b, v190
	v_exp_f32_e32 v27, v27
	v_cndmask_b32_e64 v28, v8, v9, s[10:11]
	v_add_f32_e32 v8, 1.0, v26
	v_rcp_f32_e32 v8, v8
	v_add_f32_e32 v9, 1.0, v27
	v_rcp_f32_e32 v9, v9
	v_mul_f32_e32 v10, v10, v17
	v_cndmask_b32_e64 v26, v10, v8, s[10:11]
	v_mul_f32_e32 v8, v11, v17
	v_cndmask_b32_e64 v11, v8, v9, s[10:11]
	v_cvt_pk_bf16_f32 v8, v12, v13
	v_cvt_pk_bf16_f32 v9, v14, v15
	v_cvt_pk_bf16_f32 v10, v25, v28
	v_cvt_pk_bf16_f32 v11, v26, v11
	global_store_dwordx4 v[22:23], v[8:11], off nt
	s_cbranch_vccnz .LBB0_688
	s_and_b64 vcc, exec, s[12:13]
	s_cbranch_vccnz .LBB0_685
	s_andn2_b64 vcc, exec, s[90:91]
	s_cbranch_vccnz .LBB0_682
	s_andn2_b64 vcc, exec, s[88:89]
	s_cbranch_vccnz .LBB0_679
	v_lshl_add_u64 v[8:9], s[0:1], 1, v[20:21]
	v_lshl_add_u64 v[8:9], v[8:9], 0, v[136:137]
	v_lshl_add_u64 v[8:9], v[8:9], 0, s[36:37]
	s_mov_b64 s[6:7], 0

; __device__ __forceinline__ unsigned cvt_pk_bf16(float lo, float hi) { f32x2_t v = {lo, hi}; bf16x2_t b = __builtin_convertvector(v, bf16x2_t); return __builtin_bit_cast(unsigned, b); }
; __device__ __forceinline__ float rstd_of(const float* ss, int row) { return __builtin_amdgcn_rsqf(ss[row] * (1.0f / 1024.0f) + RMS_EPS); }
; __device__ __forceinline__ float sigmoidf_(float v) { return __builtin_amdgcn_rcpf(1.0f + __builtin_amdgcn_exp2f(-v * LOG2E)); }
; #define PG8_BAR __builtin_amdgcn_s_barrier()
; template <class Epi>
; __device__ __forceinline__ void gemm_phase(LAS unsigned char* lds, const Gemm g, const StaticOrder& S, const Epi& E) {
;     ...
;         if (wr == 0) PG8_BAR;
;         E(acc, cur, wr, wc, fr, fq);
;     __device__ __forceinline__ void operator()(const Acc& acc, const Unit& u, int wr, int wc, int fr, int fq) const {
;     ...
;                 const int row = row0 + ai * HALF + m * 16; const float rs = rstd_of(ss, row) * sc;
;                 const int b = row >> 11, t = row & (SEQ - 1);
; #pragma unroll
;                 for (int bj = 0; bj < 2; ++bj) {
;                     float o[8];
; #pragma unroll
;                     for (int n = 0; n < 2; ++n)
; #pragma unroll
;                         for (int e = 0; e < 4; ++e) { float v = acc[ai][bj][m][n][e] * rs; if (isg) v = sigmoidf_(v + bv[bj][4 * n + e]); o[4 * n + e] = v; }
;                     u32x4 w; w.x = cvt_pk_bf16(o[0], o[1]); w.y = cvt_pk_bf16(o[2], o[3]); w.z = cvt_pk_bf16(o[4], o[5]); w.w = cvt_pk_bf16(o[6], o[7]);
;                     bf16_t* dst;
;                     if (tile < 4) dst = P + (size_t)row * PP + C_DQ + tile * BM + bj * HALF + cc;
;                     else if (tile < 8) dst = KD + ((size_t)((b * 8 + (tile - 4) * 2 + bj) * SEQ + t)) * 128 + cc;
;                     else if (tile < 12) dst = P + (size_t)row * PP + C_SQ + (tile - 8) * BM + bj * HALF + cc;
;                     else if (tile == 12) { const int ccf = bj * HALF + cc; dst = KS + ((size_t)((b * 4 + (ccf >> 6)) * SEQ + t)) * 64 + (ccf & 63); }
;                     else dst = P + (size_t)row * PP + C_GA + (tile - 13) * BM + bj * HALF + cc;
;                     *(u32x4*)dst = w;
.LBB0_690:
	v_fmac_f32_e32 v181, v4, v17
	v_fmac_f32_e32 v174, v5, v17
	v_mul_f32_e32 v10, 0xbfb8aa3b, v181
	v_mul_f32_e32 v11, 0xbfb8aa3b, v174
	v_exp_f32_e32 v10, v10
	v_exp_f32_e32 v11, v11
	v_mul_f32_e32 v4, v4, v17
	v_mul_f32_e32 v5, v5, v17
	v_add_f32_e32 v10, 1.0, v10
	v_add_f32_e32 v11, 1.0, v11
	v_rcp_f32_e32 v10, v10
	v_rcp_f32_e32 v11, v11
	v_fmac_f32_e32 v183, v6, v17
	v_fmac_f32_e32 v178, v7, v17
	v_cndmask_b32_e64 v4, v4, v10, s[10:11]
	v_cndmask_b32_e64 v5, v5, v11, s[10:11]
	v_mul_f32_e32 v10, 0xbfb8aa3b, v183
	v_mul_f32_e32 v11, 0xbfb8aa3b, v178
	v_exp_f32_e32 v10, v10
	v_exp_f32_e32 v11, v11
	v_fmac_f32_e32 v184, v0, v17
	v_mul_f32_e32 v12, 0xbfb8aa3b, v184
	v_add_f32_e32 v10, 1.0, v10
	v_add_f32_e32 v11, 1.0, v11
	v_rcp_f32_e32 v10, v10
	v_rcp_f32_e32 v11, v11
	v_exp_f32_e32 v12, v12
	v_mul_f32_e32 v6, v6, v17
	v_mul_f32_e32 v7, v7, v17
	v_fmac_f32_e32 v180, v1, v17
	v_cndmask_b32_e64 v6, v6, v10, s[10:11]
	v_cndmask_b32_e64 v7, v7, v11, s[10:11]
	v_add_f32_e32 v10, 1.0, v12
	v_mul_f32_e32 v11, 0xbfb8aa3b, v180
	v_rcp_f32_e32 v10, v10
	v_exp_f32_e32 v11, v11
	v_mul_f32_e32 v0, v0, v17
	v_fmac_f32_e32 v185, v2, v17
	v_cndmask_b32_e64 v10, v0, v10, s[10:11]
	v_mul_f32_e32 v0, v1, v17
	v_add_f32_e32 v1, 1.0, v11
	v_mul_f32_e32 v11, 0xbfb8aa3b, v185
	v_fmac_f32_e32 v182, v3, v17
	v_rcp_f32_e32 v1, v1
	v_exp_f32_e32 v11, v11
	v_mul_f32_e32 v12, 0xbfb8aa3b, v182
	v_exp_f32_e32 v12, v12
	v_cndmask_b32_e64 v13, v0, v1, s[10:11]
	v_add_f32_e32 v0, 1.0, v11
	v_rcp_f32_e32 v0, v0
	v_add_f32_e32 v1, 1.0, v12
	v_rcp_f32_e32 v1, v1
	v_mul_f32_e32 v2, v2, v17
	v_cndmask_b32_e64 v11, v2, v0, s[10:11]
	v_mul_f32_e32 v0, v3, v17
	v_cndmask_b32_e64 v3, v0, v1, s[10:11]
	v_cvt_pk_bf16_f32 v0, v4, v5
	v_cvt_pk_bf16_f32 v1, v6, v7
	v_cvt_pk_bf16_f32 v2, v10, v13
	v_cvt_pk_bf16_f32 v3, v11, v3
	s_andn2_b64 vcc, exec, s[8:9]
	s_mov_b64 s[6:7], -1
	global_store_dwordx4 v[8:9], v[0:3], off nt
	s_cbranch_vccnz .LBB0_410
	s_andn2_b64 vcc, exec, s[46:47]
	s_cbranch_vccnz .LBB0_409
	s_barrier
	s_branch .LBB0_409

; __device__ __forceinline__ unsigned cvt_pk_bf16(float lo, float hi) { f32x2_t v = {lo, hi}; bf16x2_t b = __builtin_convertvector(v, bf16x2_t); return __builtin_bit_cast(unsigned, b); }
; __device__ __forceinline__ float rstd_of(const float* ss, int row) { return __builtin_amdgcn_rsqf(ss[row] * (1.0f / 1024.0f) + RMS_EPS); }
;     __device__ __forceinline__ void operator()(const Acc& acc, const Unit& u, int wr, int wc, int fr, int fq) const {
;         const int row0 = u.pm * BM + wr * 64 + fr, col0 = u.pn * BM + wc * 32 + 8 * fq;
;         float rs[2][8];
; #pragma unroll
;         for (int bj = 0; bj < 2; ++bj)
; #pragma unroll
;             for (int e = 0; e < 8; ++e) rs[bj][e] = rstd_of(ss, col0 + bj * HALF + e);
; #pragma unroll
;         for (int ai = 0; ai < 2; ++ai)
; #pragma unroll
;             for (int m = 0; m < 4; ++m) {
;                 const int row = row0 + ai * HALF + m * 16;
; #pragma unroll
;                 for (int bj = 0; bj < 2; ++bj) {
;                     float o[8];
; #pragma unroll
;                     for (int n = 0; n < 2; ++n)
; #pragma unroll
;                         for (int e = 0; e < 4; ++e) o[4 * n + e] = acc[ai][bj][m][n][e] * rs[bj][4 * n + e];
;                     u32x4 w; w.x = cvt_pk_bf16(o[0], o[1]); w.y = cvt_pk_bf16(o[2], o[3]); w.z = cvt_pk_bf16(o[4], o[5]); w.w = cvt_pk_bf16(o[6], o[7]);
;                     const int tok = col0 + bj * HALF, b = tok >> 11, t = tok & (SEQ - 1);
;                     bf16_t* dst;
;                     if (row < 1024) dst = VT + ((size_t)(((b * 8 + (row >> 7)) * 32 + (t >> 6)) * 128 + (row & 127))) * 64 + (t & 63);
;                     else { const int f = row - 1024; dst = VTS + ((size_t)(((b * 4 + (f >> 6)) * 32 + (t >> 6)) * 64 + (f & 63))) * 64 + (t & 63); }
;                     *(u32x4*)dst = w;
.LBB0_723:
	s_lshl_b32 s35, s58, 8
	v_or_b32_e32 v166, s35, v174
	v_ashrrev_i32_e32 v167, 31, v166
	v_lshl_add_u64 v[132:133], v[166:167], 2, s[44:45]
	global_load_dwordx4 v[136:139], v[132:133], off offset:16
	global_load_dwordx4 v[140:143], v[132:133], off
	global_load_dwordx4 v[128:131], v[132:133], off offset:528
	s_nop 0
	global_load_dwordx4 v[132:135], v[132:133], off offset:512
	s_lshl_b32 s38, s60, 8
	s_lshl_b32 s6, s58, 10
	s_add_i32 s38, s38, s19
	s_and_b32 s15, s6, 0xffffe000
	s_addk_i32 s15, 0x8000
	s_lshl_b32 s36, s38, 5
	v_or_b32_e32 v167, s38, v155
	s_add_i32 s36, s36, s15
	v_cmp_lt_i32_e32 vcc, s29, v167
	v_or_b32_e32 v190, s36, v155
	s_and_saveexec_b64 s[6:7], vcc
	s_xor_b64 s[6:7], exec, s[6:7]
	v_and_or_b32 v168, v166, s30, v190
	s_or_saveexec_b64 s[60:61], s[6:7]
	v_bitop3_b32 v189, s35, v186, v174 bitop3:0xc8
	s_and_b32 s35, s58, 0xffff8
	s_lshr_b32 s6, s38, 7
	s_add_i32 s6, s6, s35
	s_lshl_b32 s37, s6, 12
	v_bitop3_b32 v191, s38, v187, v155 bitop3:0xc8
	v_or_b32_e32 v192, s37, v191
	v_mov_b64_e32 v[170:171], 0x9600000
	v_lshlrev_b32_e32 v188, 1, v189
	s_xor_b64 exec, exec, s[60:61]
	v_and_or_b32 v168, v188, s31, v192
	v_mov_b64_e32 v[170:171], 0x5600000
	s_or_b64 exec, exec, s[60:61]
	s_waitcnt vmcnt(0)
	v_fmamk_f32 v140, v140, 0x3a800000, v185
	v_fmamk_f32 v141, v141, 0x3a800000, v185
	v_fmamk_f32 v142, v142, 0x3a800000, v185
	v_fmamk_f32 v143, v143, 0x3a800000, v185
	v_rsq_f32_e32 v140, v140
	v_rsq_f32_e32 v141, v141
	v_rsq_f32_e32 v142, v142
	v_rsq_f32_e32 v143, v143
	v_fmamk_f32 v136, v136, 0x3a800000, v185
	v_fmamk_f32 v137, v137, 0x3a800000, v185
	v_rsq_f32_e32 v136, v136
	v_rsq_f32_e32 v137, v137
	v_fmamk_f32 v138, v138, 0x3a800000, v185
	v_fmamk_f32 v139, v139, 0x3a800000, v185
	v_rsq_f32_e32 v138, v138
	v_rsq_f32_e32 v139, v139
	v_pk_mul_f32 v[124:125], v[124:125], v[140:141]
	v_pk_mul_f32 v[126:127], v[126:127], v[142:143]
	v_ashrrev_i32_e32 v169, 31, v168
	v_pk_mul_f32 v[194:195], v[120:121], v[136:137]
	v_cvt_pk_bf16_f32 v120, v124, v125
	v_cvt_pk_bf16_f32 v121, v126, v127
	v_lshl_add_u64 v[124:125], s[48:49], 0, v[170:171]
	v_lshlrev_b64 v[126:127], 7, v[168:169]
	v_pk_mul_f32 v[196:197], v[122:123], v[138:139]
	v_lshl_add_u64 v[124:125], v[124:125], 0, v[126:127]
	v_lshlrev_b32_e32 v152, 1, v154
	v_cvt_pk_bf16_f32 v122, v194, v195
	v_cvt_pk_bf16_f32 v123, v196, v197
	v_lshl_add_u64 v[124:125], v[124:125], 0, v[152:153]
	v_or_b32_e32 v189, 0x80, v189
	global_store_dwordx4 v[124:125], v[120:123], off nt
	s_and_saveexec_b64 s[6:7], vcc
	s_xor_b64 s[6:7], exec, s[6:7]
	v_and_or_b32 v168, v189, s33, v190
	s_or_saveexec_b64 s[6:7], s[6:7]
	v_mov_b64_e32 v[170:171], 0x9600000
	v_lshlrev_b32_e32 v190, 1, v189
	s_xor_b64 exec, exec, s[6:7]
	v_and_or_b32 v168, v190, s34, v192
	v_mov_b64_e32 v[170:171], 0x5600000
	s_or_b64 exec, exec, s[6:7]
	v_fmamk_f32 v120, v132, 0x3a800000, v185
	v_rsq_f32_e32 v122, v120
	v_fmamk_f32 v120, v133, 0x3a800000, v185
	v_rsq_f32_e32 v123, v120
	v_fmamk_f32 v120, v134, 0x3a800000, v185
	v_fmamk_f32 v121, v135, 0x3a800000, v185
	v_fmamk_f32 v124, v128, 0x3a800000, v185
	v_rsq_f32_e32 v120, v120
	v_rsq_f32_e32 v121, v121
	v_rsq_f32_e32 v126, v124
	v_fmamk_f32 v124, v129, 0x3a800000, v185
	v_rsq_f32_e32 v127, v124
	v_fmamk_f32 v124, v130, 0x3a800000, v185
	v_fmamk_f32 v125, v131, 0x3a800000, v185
	v_rsq_f32_e32 v124, v124
	v_rsq_f32_e32 v125, v125
	v_pk_mul_f32 v[116:117], v[116:117], v[122:123]
	v_pk_mul_f32 v[118:119], v[118:119], v[120:121]
	v_ashrrev_i32_e32 v169, 31, v168
	v_pk_mul_f32 v[128:129], v[112:113], v[126:127]
	v_cvt_pk_bf16_f32 v112, v116, v117
	v_cvt_pk_bf16_f32 v113, v118, v119
	v_lshl_add_u64 v[116:117], s[48:49], 0, v[170:171]
	v_lshlrev_b64 v[118:119], 7, v[168:169]
	v_pk_mul_f32 v[130:131], v[114:115], v[124:125]
	v_lshl_add_u64 v[116:117], v[116:117], 0, v[118:119]
	v_cvt_pk_bf16_f32 v114, v128, v129
	v_cvt_pk_bf16_f32 v115, v130, v131
	v_lshl_add_u64 v[116:117], v[116:117], 0, v[152:153]
	global_store_dwordx4 v[116:117], v[112:115], off nt
	v_or_b32_e32 v116, s36, v178
	s_nop 0
	v_or_b32_e32 v112, 16, v167
	v_cmp_lt_i32_e32 vcc, s29, v112
	s_and_saveexec_b64 s[6:7], vcc
	s_xor_b64 s[6:7], exec, s[6:7]
	v_and_or_b32 v112, v166, s30, v116
	s_or_saveexec_b64 s[6:7], s[6:7]
	s_movk_i32 s38, 0x5f
	v_bitop3_b32 v113, v167, s38, 16 bitop3:0xc8
	v_or_b32_e32 v117, s37, v113
	v_mov_b64_e32 v[114:115], 0x9600000
	s_xor_b64 exec, exec, s[6:7]
	v_and_or_b32 v112, v188, s31, v117
	v_mov_b64_e32 v[114:115], 0x5600000
	s_or_b64 exec, exec, s[6:7]
	v_pk_mul_f32 v[108:109], v[108:109], v[140:141]
	v_pk_mul_f32 v[110:111], v[110:111], v[142:143]
	v_ashrrev_i32_e32 v113, 31, v112
	v_pk_mul_f32 v[118:119], v[104:105], v[136:137]
	v_cvt_pk_bf16_f32 v104, v108, v109
	v_cvt_pk_bf16_f32 v105, v110, v111
	v_lshl_add_u64 v[108:109], s[48:49], 0, v[114:115]
	v_lshlrev_b64 v[110:111], 7, v[112:113]
	v_pk_mul_f32 v[128:129], v[106:107], v[138:139]
	v_lshl_add_u64 v[108:109], v[108:109], 0, v[110:111]
	v_cvt_pk_bf16_f32 v106, v118, v119
	v_cvt_pk_bf16_f32 v107, v128, v129
	v_lshl_add_u64 v[108:109], v[108:109], 0, v[152:153]
	global_store_dwordx4 v[108:109], v[104:107], off nt
	s_and_saveexec_b64 s[6:7], vcc
	s_xor_b64 s[6:7], exec, s[6:7]
	v_and_or_b32 v104, v189, s33, v116
	s_or_saveexec_b64 s[6:7], s[6:7]
	v_mov_b64_e32 v[106:107], 0x9600000
	s_xor_b64 exec, exec, s[6:7]
	v_and_or_b32 v104, v190, s34, v117
	v_mov_b64_e32 v[106:107], 0x5600000
	s_or_b64 exec, exec, s[6:7]
	v_pk_mul_f32 v[100:101], v[100:101], v[122:123]
	v_pk_mul_f32 v[102:103], v[102:103], v[120:121]
	v_ashrrev_i32_e32 v105, 31, v104
	v_pk_mul_f32 v[108:109], v[96:97], v[126:127]
	v_cvt_pk_bf16_f32 v96, v100, v101
; __device__ __forceinline__ unsigned cvt_pk_bf16(float lo, float hi) { f32x2_t v = {lo, hi}; bf16x2_t b = __builtin_convertvector(v, bf16x2_t); return __builtin_bit_cast(unsigned, b); }
;     __device__ __forceinline__ void operator()(const Acc& acc, const Unit& u, int wr, int wc, int fr, int fq) const {
;     ...
;             for (int m = 0; m < 4; ++m) {
;                 const int row = row0 + ai * HALF + m * 16;
; #pragma unroll
;                 for (int bj = 0; bj < 2; ++bj) {
;                     float o[8];
; #pragma unroll
;                     for (int n = 0; n < 2; ++n)
; #pragma unroll
;                         for (int e = 0; e < 4; ++e) o[4 * n + e] = acc[ai][bj][m][n][e] * rs[bj][4 * n + e];
;                     u32x4 w; w.x = cvt_pk_bf16(o[0], o[1]); w.y = cvt_pk_bf16(o[2], o[3]); w.z = cvt_pk_bf16(o[4], o[5]); w.w = cvt_pk_bf16(o[6], o[7]);
;                     const int tok = col0 + bj * HALF, b = tok >> 11, t = tok & (SEQ - 1);
;                     bf16_t* dst;
;                     if (row < 1024) dst = VT + ((size_t)(((b * 8 + (row >> 7)) * 32 + (t >> 6)) * 128 + (row & 127))) * 64 + (t & 63);
;                     else { const int f = row - 1024; dst = VTS + ((size_t)(((b * 4 + (f >> 6)) * 32 + (t >> 6)) * 64 + (f & 63))) * 64 + (t & 63); }
;                     *(u32x4*)dst = w;
	v_cvt_pk_bf16_f32 v97, v102, v103
	v_lshl_add_u64 v[100:101], s[48:49], 0, v[106:107]
	v_lshlrev_b64 v[102:103], 7, v[104:105]
	v_pk_mul_f32 v[110:111], v[98:99], v[124:125]
	v_lshl_add_u64 v[100:101], v[100:101], 0, v[102:103]
	v_cvt_pk_bf16_f32 v98, v108, v109
	v_cvt_pk_bf16_f32 v99, v110, v111
	v_lshl_add_u64 v[100:101], v[100:101], 0, v[152:153]
	global_store_dwordx4 v[100:101], v[96:99], off nt
	v_or_b32_e32 v100, s36, v180
	s_nop 0
	v_or_b32_e32 v96, 32, v167
	v_cmp_lt_i32_e32 vcc, s29, v96
	s_and_saveexec_b64 s[6:7], vcc
	s_xor_b64 s[6:7], exec, s[6:7]
	v_and_or_b32 v96, v166, s30, v100
	s_or_saveexec_b64 s[6:7], s[6:7]
	s_movk_i32 s38, 0x6f
	v_bitop3_b32 v97, v167, s38, 32 bitop3:0xc8
	v_or_b32_e32 v101, s37, v97
	v_mov_b64_e32 v[98:99], 0x9600000
	s_xor_b64 exec, exec, s[6:7]
	v_and_or_b32 v96, v188, s31, v101
	v_mov_b64_e32 v[98:99], 0x5600000
	s_or_b64 exec, exec, s[6:7]
	v_pk_mul_f32 v[92:93], v[92:93], v[140:141]
	v_pk_mul_f32 v[94:95], v[94:95], v[142:143]
	v_ashrrev_i32_e32 v97, 31, v96
	v_pk_mul_f32 v[102:103], v[88:89], v[136:137]
	v_cvt_pk_bf16_f32 v88, v92, v93
	v_cvt_pk_bf16_f32 v89, v94, v95
	v_lshl_add_u64 v[92:93], s[48:49], 0, v[98:99]
	v_lshlrev_b64 v[94:95], 7, v[96:97]
	v_pk_mul_f32 v[104:105], v[90:91], v[138:139]
	v_lshl_add_u64 v[92:93], v[92:93], 0, v[94:95]
	v_cvt_pk_bf16_f32 v90, v102, v103
	v_cvt_pk_bf16_f32 v91, v104, v105
	v_lshl_add_u64 v[92:93], v[92:93], 0, v[152:153]
	global_store_dwordx4 v[92:93], v[88:91], off nt
	s_and_saveexec_b64 s[6:7], vcc
	s_xor_b64 s[6:7], exec, s[6:7]
	v_and_or_b32 v88, v189, s33, v100
	s_or_saveexec_b64 s[6:7], s[6:7]
	v_mov_b64_e32 v[90:91], 0x9600000
	s_xor_b64 exec, exec, s[6:7]
	v_and_or_b32 v88, v190, s34, v101
	v_mov_b64_e32 v[90:91], 0x5600000
	s_or_b64 exec, exec, s[6:7]
	v_pk_mul_f32 v[84:85], v[84:85], v[122:123]
	v_pk_mul_f32 v[86:87], v[86:87], v[120:121]
	v_ashrrev_i32_e32 v89, 31, v88
	v_pk_mul_f32 v[92:93], v[80:81], v[126:127]
	v_cvt_pk_bf16_f32 v80, v84, v85
	v_cvt_pk_bf16_f32 v81, v86, v87
	v_lshl_add_u64 v[84:85], s[48:49], 0, v[90:91]
	v_lshlrev_b64 v[86:87], 7, v[88:89]
	v_pk_mul_f32 v[94:95], v[82:83], v[124:125]
	v_lshl_add_u64 v[84:85], v[84:85], 0, v[86:87]
	v_cvt_pk_bf16_f32 v82, v92, v93
	v_cvt_pk_bf16_f32 v83, v94, v95
	v_lshl_add_u64 v[84:85], v[84:85], 0, v[152:153]
	global_store_dwordx4 v[84:85], v[80:83], off nt
	v_or_b32_e32 v84, s36, v181
	s_nop 0
	v_or_b32_e32 v80, 48, v167
	v_cmp_lt_i32_e32 vcc, s29, v80
	s_and_saveexec_b64 s[6:7], vcc
	s_xor_b64 s[6:7], exec, s[6:7]
	v_and_or_b32 v80, v166, s30, v84
	s_or_saveexec_b64 s[6:7], s[6:7]
	s_movk_i32 s36, 0x7f
	v_bitop3_b32 v81, v167, s36, 48 bitop3:0xc8
	v_or_b32_e32 v85, s37, v81
	v_mov_b64_e32 v[82:83], 0x9600000
	s_xor_b64 exec, exec, s[6:7]
	v_and_or_b32 v80, v188, s31, v85
	v_mov_b64_e32 v[82:83], 0x5600000
	s_or_b64 exec, exec, s[6:7]
	v_pk_mul_f32 v[76:77], v[76:77], v[140:141]
	v_pk_mul_f32 v[78:79], v[78:79], v[142:143]
	v_ashrrev_i32_e32 v81, 31, v80
	v_pk_mul_f32 v[86:87], v[72:73], v[136:137]
	v_cvt_pk_bf16_f32 v72, v76, v77
	v_cvt_pk_bf16_f32 v73, v78, v79
	v_lshl_add_u64 v[76:77], s[48:49], 0, v[82:83]
	v_lshlrev_b64 v[78:79], 7, v[80:81]
	v_pk_mul_f32 v[88:89], v[74:75], v[138:139]
	v_lshl_add_u64 v[76:77], v[76:77], 0, v[78:79]
	v_cvt_pk_bf16_f32 v74, v86, v87
	v_cvt_pk_bf16_f32 v75, v88, v89
	v_lshl_add_u64 v[76:77], v[76:77], 0, v[152:153]
	global_store_dwordx4 v[76:77], v[72:75], off nt
	s_and_saveexec_b64 s[6:7], vcc
	s_xor_b64 s[6:7], exec, s[6:7]
	v_and_or_b32 v72, v189, s33, v84
	s_or_saveexec_b64 s[6:7], s[6:7]
	v_mov_b64_e32 v[74:75], 0x9600000
	s_xor_b64 exec, exec, s[6:7]
	v_and_or_b32 v72, v190, s34, v85
	v_mov_b64_e32 v[74:75], 0x5600000
	s_or_b64 exec, exec, s[6:7]
	v_pk_mul_f32 v[68:69], v[68:69], v[122:123]
	v_pk_mul_f32 v[70:71], v[70:71], v[120:121]
	v_ashrrev_i32_e32 v73, 31, v72
	v_pk_mul_f32 v[76:77], v[64:65], v[126:127]
	v_cvt_pk_bf16_f32 v64, v68, v69
	v_cvt_pk_bf16_f32 v65, v70, v71
	v_lshl_add_u64 v[68:69], s[48:49], 0, v[74:75]
	v_lshlrev_b64 v[70:71], 7, v[72:73]
	v_pk_mul_f32 v[78:79], v[66:67], v[124:125]
	v_lshl_add_u64 v[68:69], v[68:69], 0, v[70:71]
	v_cvt_pk_bf16_f32 v66, v76, v77
	v_cvt_pk_bf16_f32 v67, v78, v79
	v_lshl_add_u64 v[68:69], v[68:69], 0, v[152:153]
	global_store_dwordx4 v[68:69], v[64:67], off nt
	s_movk_i32 s6, 0x37f
	v_cmp_lt_i32_e32 vcc, s6, v167
	v_add_u32_e32 v65, 0x80, v167
	v_lshlrev_b32_e32 v64, 5, v65
	v_and_b32_e32 v64, 0xfffff800, v64
	v_add_u32_e32 v68, s15, v64
	v_or_b32_e32 v70, v68, v155
	s_and_saveexec_b64 s[6:7], vcc
	s_xor_b64 s[6:7], exec, s[6:7]
	v_and_or_b32 v64, v166, s30, v70
	s_or_saveexec_b64 s[6:7], s[6:7]
	v_lshrrev_b32_e32 v65, 7, v65
	v_add_u32_e32 v65, s35, v65
	v_lshl_or_b32 v69, v65, 12, v191
	v_mov_b64_e32 v[66:67], 0x9600000
	s_xor_b64 exec, exec, s[6:7]
	v_and_or_b32 v64, v188, s31, v69
	v_mov_b64_e32 v[66:67], 0x5600000
	s_or_b64 exec, exec, s[6:7]
	v_pk_mul_f32 v[60:61], v[60:61], v[140:141]
	v_pk_mul_f32 v[62:63], v[62:63], v[142:143]
	v_ashrrev_i32_e32 v65, 31, v64
	v_pk_mul_f32 v[72:73], v[56:57], v[136:137]
	v_cvt_pk_bf16_f32 v56, v60, v61
	v_cvt_pk_bf16_f32 v57, v62, v63
	v_lshl_add_u64 v[60:61], s[48:49], 0, v[66:67]
	v_lshlrev_b64 v[62:63], 7, v[64:65]
	v_pk_mul_f32 v[74:75], v[58:59], v[138:139]
	v_lshl_add_u64 v[60:61], v[60:61], 0, v[62:63]
	v_cvt_pk_bf16_f32 v58, v72, v73
	v_cvt_pk_bf16_f32 v59, v74, v75
	v_lshl_add_u64 v[60:61], v[60:61], 0, v[152:153]
	global_store_dwordx4 v[60:61], v[56:59], off nt
	s_and_saveexec_b64 s[6:7], vcc
	s_xor_b64 s[6:7], exec, s[6:7]
	v_and_or_b32 v56, v189, s33, v70
	s_or_saveexec_b64 s[6:7], s[6:7]
	v_mov_b64_e32 v[58:59], 0x9600000
; __device__ __forceinline__ unsigned cvt_pk_bf16(float lo, float hi) { f32x2_t v = {lo, hi}; bf16x2_t b = __builtin_convertvector(v, bf16x2_t); return __builtin_bit_cast(unsigned, b); }
; #define PG8_BAR __builtin_amdgcn_s_barrier()
; template <class Epi>
; __device__ __forceinline__ void gemm_phase(LAS unsigned char* lds, const Gemm g, const StaticOrder& S, const Epi& E) {
;     ...
;         if (wr == 0) PG8_BAR;
;         E(acc, cur, wr, wc, fr, fq);
;     __device__ __forceinline__ void operator()(const Acc& acc, const Unit& u, int wr, int wc, int fr, int fq) const {
;     ...
;             for (int m = 0; m < 4; ++m) {
;                 const int row = row0 + ai * HALF + m * 16;
; #pragma unroll
;                 for (int bj = 0; bj < 2; ++bj) {
;                     float o[8];
; #pragma unroll
;                     for (int n = 0; n < 2; ++n)
; #pragma unroll
;                         for (int e = 0; e < 4; ++e) o[4 * n + e] = acc[ai][bj][m][n][e] * rs[bj][4 * n + e];
;                     u32x4 w; w.x = cvt_pk_bf16(o[0], o[1]); w.y = cvt_pk_bf16(o[2], o[3]); w.z = cvt_pk_bf16(o[4], o[5]); w.w = cvt_pk_bf16(o[6], o[7]);
;                     const int tok = col0 + bj * HALF, b = tok >> 11, t = tok & (SEQ - 1);
;                     bf16_t* dst;
;                     if (row < 1024) dst = VT + ((size_t)(((b * 8 + (row >> 7)) * 32 + (t >> 6)) * 128 + (row & 127))) * 64 + (t & 63);
;                     else { const int f = row - 1024; dst = VTS + ((size_t)(((b * 4 + (f >> 6)) * 32 + (t >> 6)) * 64 + (f & 63))) * 64 + (t & 63); }
;                     *(u32x4*)dst = w;
	s_xor_b64 exec, exec, s[6:7]
	v_and_or_b32 v56, v190, s34, v69
	v_mov_b64_e32 v[58:59], 0x5600000
	s_or_b64 exec, exec, s[6:7]
	v_pk_mul_f32 v[52:53], v[52:53], v[122:123]
	v_pk_mul_f32 v[54:55], v[54:55], v[120:121]
	v_ashrrev_i32_e32 v57, 31, v56
	v_pk_mul_f32 v[60:61], v[48:49], v[126:127]
	v_cvt_pk_bf16_f32 v48, v52, v53
	v_cvt_pk_bf16_f32 v49, v54, v55
	v_lshl_add_u64 v[52:53], s[48:49], 0, v[58:59]
	v_lshlrev_b64 v[54:55], 7, v[56:57]
	v_pk_mul_f32 v[62:63], v[50:51], v[124:125]
	v_lshl_add_u64 v[52:53], v[52:53], 0, v[54:55]
	v_cvt_pk_bf16_f32 v50, v60, v61
	v_cvt_pk_bf16_f32 v51, v62, v63
	v_lshl_add_u64 v[52:53], v[52:53], 0, v[152:153]
	s_movk_i32 s6, 0x36f
	global_store_dwordx4 v[52:53], v[48:51], off nt
	v_cmp_lt_i32_e32 vcc, s6, v167
	v_or_b32_e32 v52, v68, v178
	s_and_saveexec_b64 s[6:7], vcc
	s_xor_b64 s[6:7], exec, s[6:7]
	v_and_or_b32 v48, v166, s30, v52
	s_or_saveexec_b64 s[6:7], s[6:7]
	v_or_b32_e32 v53, 16, v69
	v_mov_b64_e32 v[50:51], 0x9600000
	s_xor_b64 exec, exec, s[6:7]
	v_and_or_b32 v48, v188, s31, v53
	v_mov_b64_e32 v[50:51], 0x5600000
	s_or_b64 exec, exec, s[6:7]
	v_pk_mul_f32 v[44:45], v[44:45], v[140:141]
	v_pk_mul_f32 v[46:47], v[46:47], v[142:143]
	v_ashrrev_i32_e32 v49, 31, v48
	v_pk_mul_f32 v[54:55], v[40:41], v[136:137]
	v_cvt_pk_bf16_f32 v40, v44, v45
	v_cvt_pk_bf16_f32 v41, v46, v47
	v_lshl_add_u64 v[44:45], s[48:49], 0, v[50:51]
	v_lshlrev_b64 v[46:47], 7, v[48:49]
	v_pk_mul_f32 v[56:57], v[42:43], v[138:139]
	v_lshl_add_u64 v[44:45], v[44:45], 0, v[46:47]
	v_cvt_pk_bf16_f32 v42, v54, v55
	v_cvt_pk_bf16_f32 v43, v56, v57
	v_lshl_add_u64 v[44:45], v[44:45], 0, v[152:153]
	global_store_dwordx4 v[44:45], v[40:43], off nt
	s_and_saveexec_b64 s[6:7], vcc
	s_xor_b64 s[6:7], exec, s[6:7]
	v_and_or_b32 v40, v189, s33, v52
	s_or_saveexec_b64 s[6:7], s[6:7]
	v_mov_b64_e32 v[42:43], 0x9600000
	s_xor_b64 exec, exec, s[6:7]
	v_and_or_b32 v40, v190, s34, v53
	v_mov_b64_e32 v[42:43], 0x5600000
	s_or_b64 exec, exec, s[6:7]
	v_pk_mul_f32 v[36:37], v[36:37], v[122:123]
	v_pk_mul_f32 v[38:39], v[38:39], v[120:121]
	v_ashrrev_i32_e32 v41, 31, v40
	v_pk_mul_f32 v[44:45], v[32:33], v[126:127]
	v_cvt_pk_bf16_f32 v32, v36, v37
	v_cvt_pk_bf16_f32 v33, v38, v39
	v_lshl_add_u64 v[36:37], s[48:49], 0, v[42:43]
	v_lshlrev_b64 v[38:39], 7, v[40:41]
	v_pk_mul_f32 v[46:47], v[34:35], v[124:125]
	v_lshl_add_u64 v[36:37], v[36:37], 0, v[38:39]
	v_cvt_pk_bf16_f32 v34, v44, v45
	v_cvt_pk_bf16_f32 v35, v46, v47
	v_lshl_add_u64 v[36:37], v[36:37], 0, v[152:153]
	s_movk_i32 s6, 0x35f
	global_store_dwordx4 v[36:37], v[32:35], off nt
	v_cmp_lt_i32_e32 vcc, s6, v167
	v_or_b32_e32 v36, v68, v180
	s_and_saveexec_b64 s[6:7], vcc
	s_xor_b64 s[6:7], exec, s[6:7]
	v_and_or_b32 v32, v166, s30, v36
	s_or_saveexec_b64 s[6:7], s[6:7]
	v_or_b32_e32 v37, 32, v69
	v_mov_b64_e32 v[34:35], 0x9600000
	s_xor_b64 exec, exec, s[6:7]
	v_and_or_b32 v32, v188, s31, v37
	v_mov_b64_e32 v[34:35], 0x5600000
	s_or_b64 exec, exec, s[6:7]
	v_pk_mul_f32 v[28:29], v[28:29], v[140:141]
	v_pk_mul_f32 v[30:31], v[30:31], v[142:143]
	v_ashrrev_i32_e32 v33, 31, v32
	v_pk_mul_f32 v[38:39], v[24:25], v[136:137]
	v_cvt_pk_bf16_f32 v24, v28, v29
	v_cvt_pk_bf16_f32 v25, v30, v31
	v_lshl_add_u64 v[28:29], s[48:49], 0, v[34:35]
	v_lshlrev_b64 v[30:31], 7, v[32:33]
	v_pk_mul_f32 v[40:41], v[26:27], v[138:139]
	v_lshl_add_u64 v[28:29], v[28:29], 0, v[30:31]
	v_cvt_pk_bf16_f32 v26, v38, v39
	v_cvt_pk_bf16_f32 v27, v40, v41
	v_lshl_add_u64 v[28:29], v[28:29], 0, v[152:153]
	global_store_dwordx4 v[28:29], v[24:27], off nt
	s_and_saveexec_b64 s[6:7], vcc
	s_xor_b64 s[6:7], exec, s[6:7]
	v_and_or_b32 v24, v189, s33, v36
	s_or_saveexec_b64 s[6:7], s[6:7]
	v_mov_b64_e32 v[26:27], 0x9600000
	s_xor_b64 exec, exec, s[6:7]
	v_and_or_b32 v24, v190, s34, v37
	v_mov_b64_e32 v[26:27], 0x5600000
	s_or_b64 exec, exec, s[6:7]
	v_pk_mul_f32 v[20:21], v[20:21], v[122:123]
	v_pk_mul_f32 v[22:23], v[22:23], v[120:121]
	v_ashrrev_i32_e32 v25, 31, v24
	v_pk_mul_f32 v[28:29], v[16:17], v[126:127]
	v_cvt_pk_bf16_f32 v16, v20, v21
	v_cvt_pk_bf16_f32 v17, v22, v23
	v_lshl_add_u64 v[20:21], s[48:49], 0, v[26:27]
	v_lshlrev_b64 v[22:23], 7, v[24:25]
	v_pk_mul_f32 v[30:31], v[18:19], v[124:125]
	v_lshl_add_u64 v[20:21], v[20:21], 0, v[22:23]
	v_cvt_pk_bf16_f32 v18, v28, v29
	v_cvt_pk_bf16_f32 v19, v30, v31
	v_lshl_add_u64 v[20:21], v[20:21], 0, v[152:153]
	s_movk_i32 s6, 0x34f
	global_store_dwordx4 v[20:21], v[16:19], off nt
	v_cmp_lt_i32_e32 vcc, s6, v167
	v_or_b32_e32 v20, v68, v181
	s_and_saveexec_b64 s[6:7], vcc
	s_xor_b64 s[6:7], exec, s[6:7]
	v_and_or_b32 v16, v166, s30, v20
	s_or_saveexec_b64 s[6:7], s[6:7]
	v_or_b32_e32 v21, 48, v69
	v_mov_b64_e32 v[18:19], 0x9600000
	s_xor_b64 exec, exec, s[6:7]
	v_and_or_b32 v16, v188, s31, v21
	v_mov_b64_e32 v[18:19], 0x5600000
	s_or_b64 exec, exec, s[6:7]
	v_pk_mul_f32 v[12:13], v[12:13], v[140:141]
	v_pk_mul_f32 v[14:15], v[14:15], v[142:143]
	v_ashrrev_i32_e32 v17, 31, v16
	v_pk_mul_f32 v[22:23], v[8:9], v[136:137]
	v_cvt_pk_bf16_f32 v8, v12, v13
	v_cvt_pk_bf16_f32 v9, v14, v15
	v_lshl_add_u64 v[12:13], s[48:49], 0, v[18:19]
	v_lshlrev_b64 v[14:15], 7, v[16:17]
	v_pk_mul_f32 v[24:25], v[10:11], v[138:139]
	v_lshl_add_u64 v[12:13], v[12:13], 0, v[14:15]
	v_cvt_pk_bf16_f32 v10, v22, v23
	v_cvt_pk_bf16_f32 v11, v24, v25
	v_lshl_add_u64 v[12:13], v[12:13], 0, v[152:153]
	global_store_dwordx4 v[12:13], v[8:11], off nt
	s_and_saveexec_b64 s[6:7], vcc
	s_xor_b64 s[6:7], exec, s[6:7]
	v_and_or_b32 v8, v189, s33, v20
	s_or_saveexec_b64 s[6:7], s[6:7]
	v_mov_b64_e32 v[10:11], 0x9600000
	s_xor_b64 exec, exec, s[6:7]
	v_and_or_b32 v8, v190, s34, v21
	v_mov_b64_e32 v[10:11], 0x5600000
	s_or_b64 exec, exec, s[6:7]
	v_ashrrev_i32_e32 v9, 31, v8
	v_lshl_add_u64 v[10:11], s[48:49], 0, v[10:11]
	v_lshlrev_b64 v[8:9], 7, v[8:9]
	v_pk_mul_f32 v[4:5], v[4:5], v[122:123]
	v_pk_mul_f32 v[6:7], v[6:7], v[120:121]
	v_pk_mul_f32 v[0:1], v[0:1], v[126:127]
	v_lshl_add_u64 v[8:9], v[10:11], 0, v[8:9]
	v_cvt_pk_bf16_f32 v4, v4, v5
	v_cvt_pk_bf16_f32 v5, v6, v7
	v_cvt_pk_bf16_f32 v6, v0, v1
	v_pk_mul_f32 v[0:1], v[2:3], v[124:125]
	v_lshl_add_u64 v[8:9], v[8:9], 0, v[152:153]
	v_cvt_pk_bf16_f32 v7, v0, v1
	s_andn2_b64 vcc, exec, s[8:9]
	s_mov_b64 s[6:7], -1
	global_store_dwordx4 v[8:9], v[4:7], off nt
	s_cbranch_vccnz .LBB0_716
	s_andn2_b64 vcc, exec, s[0:1]
	s_cbranch_vccnz .LBB0_715
	s_barrier
	s_branch .LBB0_715

; __device__ __forceinline__ unsigned cvt_pk_bf16(float lo, float hi) { f32x2_t v = {lo, hi}; bf16x2_t b = __builtin_convertvector(v, bf16x2_t); return __builtin_bit_cast(unsigned, b); }
; __device__ __forceinline__ float rstd_of(const float* ss, int row) { return __builtin_amdgcn_rsqf(ss[row] * (1.0f / 1024.0f) + RMS_EPS); }
; __device__ __forceinline__ float sigmoidf_(float v) { return __builtin_amdgcn_rcpf(1.0f + __builtin_amdgcn_exp2f(-v * LOG2E)); }
;     __device__ __forceinline__ void operator()(const Acc& acc, const Unit& u, int wr, int wc, int fr, int fq) const {
;         const int row0 = u.pm * BM + wr * 64 + fr, col0 = u.pn * 128 + wc * 32 + 8 * fq;
; #pragma unroll
;         for (int ai = 0; ai < 2; ++ai)
; #pragma unroll
;             for (int m = 0; m < 4; ++m) {
;                 const int row = row0 + ai * HALF + m * 16; const float rs = rstd_of(ss, row);
;                 float o[8];
; #pragma unroll
;                 for (int n = 0; n < 2; ++n)
; #pragma unroll
;                     for (int e = 0; e < 4; ++e) { const float gv = acc[ai][0][m][n][e] * rs, uv = acc[ai][1][m][n][e] * rs; o[4 * n + e] = gv * sigmoidf_(gv) * uv; }
;                 u32x4 w; w.x = cvt_pk_bf16(o[0], o[1]); w.y = cvt_pk_bf16(o[2], o[3]); w.z = cvt_pk_bf16(o[4], o[5]); w.w = cvt_pk_bf16(o[6], o[7]);
;                 *(u32x4*)(H + (size_t)row * FF + col0) = w;
.LBB0_1353:
	v_lshl_add_u32 v144, s36, 8, v152
	v_ashrrev_i32_e32 v145, 31, v144
	v_lshl_add_u64 v[150:151], v[144:145], 2, s[2:3]
	global_load_dword v145, v[150:151], off
	v_or_b32_e32 v164, 16, v144
	v_ashrrev_i32_e32 v165, 31, v164
	v_lshl_add_u64 v[166:167], v[164:165], 2, s[2:3]
	v_lshl_or_b32 v148, s37, 7, v154
	v_mov_b64_e32 v[146:147], s[20:21]
	v_ashrrev_i32_e32 v149, 31, v148
	v_mad_i64_i32 v[162:163], s[36:37], v144, s33, v[146:147]
	v_lshlrev_b64 v[148:149], 1, v[148:149]
	v_lshl_add_u64 v[162:163], v[162:163], 0, v[148:149]
	v_readlane_b32 s48, v255, 6
	s_andn2_b64 vcc, exec, s[6:7]
	s_mov_b64 s[6:7], -1
	v_readlane_b32 s49, v255, 7
	v_readlane_b32 s50, v255, 8
	v_readlane_b32 s51, v255, 9
	s_waitcnt vmcnt(0)
	v_fmamk_f32 v145, v145, 0x3a800000, v158
	v_rsq_f32_e32 v160, v145
	s_nop 0
	v_pk_mul_f32 v[124:125], v[124:125], v[160:161] op_sel_hi:[1,0]
	v_pk_mul_f32 v[126:127], v[126:127], v[160:161] op_sel_hi:[1,0]
	v_pk_mul_f32 v[120:121], v[120:121], v[160:161] op_sel_hi:[1,0]
	v_pk_mul_f32 v[122:123], v[122:123], v[160:161] op_sel_hi:[1,0]
	v_pk_mul_f32 v[116:117], v[116:117], v[160:161] op_sel_hi:[1,0]
	v_pk_mul_f32 v[118:119], v[118:119], v[160:161] op_sel_hi:[1,0]
	v_pk_mul_f32 v[112:113], v[112:113], v[160:161] op_sel_hi:[1,0]
	v_pk_mul_f32 v[114:115], v[114:115], v[160:161] op_sel_hi:[1,0]
	v_mul_f32_e32 v145, 0xbfb8aa3b, v124
	v_mul_f32_e32 v159, 0xbfb8aa3b, v125
	v_mul_f32_e32 v160, 0xbfb8aa3b, v126
	v_mul_f32_e32 v165, 0xbfb8aa3b, v127
	v_mul_f32_e32 v168, 0xbfb8aa3b, v120
	v_mul_f32_e32 v169, 0xbfb8aa3b, v121
	v_mul_f32_e32 v170, 0xbfb8aa3b, v122
	v_mul_f32_e32 v171, 0xbfb8aa3b, v123
	v_exp_f32_e32 v145, v145
	v_exp_f32_e32 v159, v159
	v_exp_f32_e32 v160, v160
	v_exp_f32_e32 v165, v165
	v_exp_f32_e32 v168, v168
	v_exp_f32_e32 v169, v169
	v_exp_f32_e32 v170, v170
	v_exp_f32_e32 v171, v171
	v_add_f32_e32 v145, 1.0, v145
	v_add_f32_e32 v159, 1.0, v159
	v_add_f32_e32 v160, 1.0, v160
	v_add_f32_e32 v165, 1.0, v165
	v_add_f32_e32 v172, 1.0, v168
	v_add_f32_e32 v173, 1.0, v169
	v_add_f32_e32 v174, 1.0, v170
	v_add_f32_e32 v175, 1.0, v171
	v_rcp_f32_e32 v168, v145
	v_rcp_f32_e32 v169, v159
	v_rcp_f32_e32 v170, v160
	v_rcp_f32_e32 v171, v165
	v_rcp_f32_e32 v172, v172
	v_rcp_f32_e32 v173, v173
	v_rcp_f32_e32 v174, v174
	v_rcp_f32_e32 v175, v175
	v_pk_mul_f32 v[124:125], v[124:125], v[168:169]
	v_pk_mul_f32 v[126:127], v[126:127], v[170:171]
	v_pk_mul_f32 v[120:121], v[120:121], v[172:173]
	v_pk_mul_f32 v[122:123], v[122:123], v[174:175]
	v_pk_mul_f32 v[116:117], v[116:117], v[124:125]
	v_pk_mul_f32 v[118:119], v[118:119], v[126:127]
	v_pk_mul_f32 v[120:121], v[112:113], v[120:121]
	v_pk_mul_f32 v[122:123], v[114:115], v[122:123]
	v_cvt_pk_bf16_f32 v112, v116, v117
	v_cvt_pk_bf16_f32 v113, v118, v119
	v_cvt_pk_bf16_f32 v114, v120, v121
	v_cvt_pk_bf16_f32 v115, v122, v123
	global_store_dwordx4 v[162:163], v[112:115], off nt
	global_load_dword v113, v[166:167], off
	s_nop 0
	v_or_b32_e32 v112, 32, v144
	v_mad_i64_i32 v[114:115], s[36:37], v164, s33, v[146:147]
	v_lshl_add_u64 v[114:115], v[114:115], 0, v[148:149]
	s_waitcnt vmcnt(0)
	v_fmamk_f32 v113, v113, 0x3a800000, v158
	v_rsq_f32_e32 v116, v113
	v_ashrrev_i32_e32 v113, 31, v112
	v_lshl_add_u64 v[118:119], v[112:113], 2, s[2:3]
	v_pk_mul_f32 v[108:109], v[108:109], v[116:117] op_sel_hi:[1,0]
	v_pk_mul_f32 v[110:111], v[110:111], v[116:117] op_sel_hi:[1,0]
	v_pk_mul_f32 v[104:105], v[104:105], v[116:117] op_sel_hi:[1,0]
	v_pk_mul_f32 v[106:107], v[106:107], v[116:117] op_sel_hi:[1,0]
	v_pk_mul_f32 v[100:101], v[100:101], v[116:117] op_sel_hi:[1,0]
	v_pk_mul_f32 v[102:103], v[102:103], v[116:117] op_sel_hi:[1,0]
	v_pk_mul_f32 v[96:97], v[96:97], v[116:117] op_sel_hi:[1,0]
	v_pk_mul_f32 v[98:99], v[98:99], v[116:117] op_sel_hi:[1,0]
	v_mul_f32_e32 v113, 0xbfb8aa3b, v108
	v_mul_f32_e32 v116, 0xbfb8aa3b, v109
	v_mul_f32_e32 v117, 0xbfb8aa3b, v110
	v_mul_f32_e32 v120, 0xbfb8aa3b, v111
	v_mul_f32_e32 v121, 0xbfb8aa3b, v104
	v_mul_f32_e32 v122, 0xbfb8aa3b, v105
	v_mul_f32_e32 v123, 0xbfb8aa3b, v106
	v_mul_f32_e32 v124, 0xbfb8aa3b, v107
	v_exp_f32_e32 v113, v113
	v_exp_f32_e32 v116, v116
	v_exp_f32_e32 v117, v117
	v_exp_f32_e32 v120, v120
	v_exp_f32_e32 v121, v121
	v_exp_f32_e32 v122, v122
	v_exp_f32_e32 v123, v123
	v_exp_f32_e32 v124, v124
	v_add_f32_e32 v113, 1.0, v113
	v_add_f32_e32 v125, 1.0, v116
	v_add_f32_e32 v126, 1.0, v117
	v_add_f32_e32 v127, 1.0, v120
	v_add_f32_e32 v145, 1.0, v121
	v_add_f32_e32 v159, 1.0, v122
	v_add_f32_e32 v160, 1.0, v123
	v_add_f32_e32 v162, 1.0, v124
	v_rcp_f32_e32 v116, v113
	v_rcp_f32_e32 v117, v125
	v_rcp_f32_e32 v120, v126
	v_rcp_f32_e32 v121, v127
	v_rcp_f32_e32 v122, v145
	v_rcp_f32_e32 v123, v159
	v_rcp_f32_e32 v124, v160
	v_rcp_f32_e32 v125, v162
	v_pk_mul_f32 v[108:109], v[108:109], v[116:117]
	v_pk_mul_f32 v[110:111], v[110:111], v[120:121]
	v_pk_mul_f32 v[104:105], v[104:105], v[122:123]
	v_pk_mul_f32 v[106:107], v[106:107], v[124:125]
	v_pk_mul_f32 v[100:101], v[100:101], v[108:109]
	v_pk_mul_f32 v[102:103], v[102:103], v[110:111]
	v_pk_mul_f32 v[104:105], v[96:97], v[104:105]
	v_pk_mul_f32 v[106:107], v[98:99], v[106:107]
	v_cvt_pk_bf16_f32 v96, v100, v101
	v_cvt_pk_bf16_f32 v97, v102, v103
	v_cvt_pk_bf16_f32 v98, v104, v105
	v_cvt_pk_bf16_f32 v99, v106, v107
	global_store_dwordx4 v[114:115], v[96:99], off nt
	global_load_dword v97, v[118:119], off
	s_nop 0
	v_or_b32_e32 v96, 48, v144
	v_mad_i64_i32 v[98:99], s[36:37], v112, s33, v[146:147]
	v_lshl_add_u64 v[98:99], v[98:99], 0, v[148:149]
	s_waitcnt vmcnt(0)
; __device__ __forceinline__ unsigned cvt_pk_bf16(float lo, float hi) { f32x2_t v = {lo, hi}; bf16x2_t b = __builtin_convertvector(v, bf16x2_t); return __builtin_bit_cast(unsigned, b); }
; __device__ __forceinline__ float rstd_of(const float* ss, int row) { return __builtin_amdgcn_rsqf(ss[row] * (1.0f / 1024.0f) + RMS_EPS); }
; __device__ __forceinline__ float sigmoidf_(float v) { return __builtin_amdgcn_rcpf(1.0f + __builtin_amdgcn_exp2f(-v * LOG2E)); }
;     __device__ __forceinline__ void operator()(const Acc& acc, const Unit& u, int wr, int wc, int fr, int fq) const {
;         const int row0 = u.pm * BM + wr * 64 + fr, col0 = u.pn * 128 + wc * 32 + 8 * fq;
; #pragma unroll
;         for (int ai = 0; ai < 2; ++ai)
; #pragma unroll
;             for (int m = 0; m < 4; ++m) {
;                 const int row = row0 + ai * HALF + m * 16; const float rs = rstd_of(ss, row);
;                 float o[8];
; #pragma unroll
;                 for (int n = 0; n < 2; ++n)
; #pragma unroll
;                     for (int e = 0; e < 4; ++e) { const float gv = acc[ai][0][m][n][e] * rs, uv = acc[ai][1][m][n][e] * rs; o[4 * n + e] = gv * sigmoidf_(gv) * uv; }
;                 u32x4 w; w.x = cvt_pk_bf16(o[0], o[1]); w.y = cvt_pk_bf16(o[2], o[3]); w.z = cvt_pk_bf16(o[4], o[5]); w.w = cvt_pk_bf16(o[6], o[7]);
;                 *(u32x4*)(H + (size_t)row * FF + col0) = w;
	v_fmamk_f32 v97, v97, 0x3a800000, v158
	v_rsq_f32_e32 v100, v97
	v_ashrrev_i32_e32 v97, 31, v96
	v_lshl_add_u64 v[102:103], v[96:97], 2, s[2:3]
	v_pk_mul_f32 v[92:93], v[92:93], v[100:101] op_sel_hi:[1,0]
	v_pk_mul_f32 v[94:95], v[94:95], v[100:101] op_sel_hi:[1,0]
	v_pk_mul_f32 v[88:89], v[88:89], v[100:101] op_sel_hi:[1,0]
	v_pk_mul_f32 v[90:91], v[90:91], v[100:101] op_sel_hi:[1,0]
	v_pk_mul_f32 v[84:85], v[84:85], v[100:101] op_sel_hi:[1,0]
	v_pk_mul_f32 v[86:87], v[86:87], v[100:101] op_sel_hi:[1,0]
	v_pk_mul_f32 v[80:81], v[80:81], v[100:101] op_sel_hi:[1,0]
	v_pk_mul_f32 v[82:83], v[82:83], v[100:101] op_sel_hi:[1,0]
	v_mul_f32_e32 v97, 0xbfb8aa3b, v92
	v_mul_f32_e32 v100, 0xbfb8aa3b, v93
	v_mul_f32_e32 v101, 0xbfb8aa3b, v94
	v_mul_f32_e32 v104, 0xbfb8aa3b, v95
	v_mul_f32_e32 v105, 0xbfb8aa3b, v88
	v_mul_f32_e32 v106, 0xbfb8aa3b, v89
	v_mul_f32_e32 v107, 0xbfb8aa3b, v90
	v_mul_f32_e32 v108, 0xbfb8aa3b, v91
	v_exp_f32_e32 v97, v97
	v_exp_f32_e32 v100, v100
	v_exp_f32_e32 v101, v101
	v_exp_f32_e32 v104, v104
	v_exp_f32_e32 v105, v105
	v_exp_f32_e32 v106, v106
	v_exp_f32_e32 v107, v107
	v_exp_f32_e32 v108, v108
	v_add_f32_e32 v97, 1.0, v97
	v_add_f32_e32 v109, 1.0, v100
	v_add_f32_e32 v110, 1.0, v101
	v_add_f32_e32 v111, 1.0, v104
	v_add_f32_e32 v112, 1.0, v105
	v_add_f32_e32 v113, 1.0, v106
	v_add_f32_e32 v114, 1.0, v107
	v_add_f32_e32 v115, 1.0, v108
	v_rcp_f32_e32 v100, v97
	v_rcp_f32_e32 v101, v109
	v_rcp_f32_e32 v104, v110
	v_rcp_f32_e32 v105, v111
	v_rcp_f32_e32 v106, v112
	v_rcp_f32_e32 v107, v113
	v_rcp_f32_e32 v108, v114
	v_rcp_f32_e32 v109, v115
	v_pk_mul_f32 v[92:93], v[92:93], v[100:101]
	v_pk_mul_f32 v[94:95], v[94:95], v[104:105]
	v_pk_mul_f32 v[88:89], v[88:89], v[106:107]
	v_pk_mul_f32 v[90:91], v[90:91], v[108:109]
	v_pk_mul_f32 v[84:85], v[84:85], v[92:93]
	v_pk_mul_f32 v[86:87], v[86:87], v[94:95]
	v_pk_mul_f32 v[88:89], v[80:81], v[88:89]
	v_pk_mul_f32 v[90:91], v[82:83], v[90:91]
	v_cvt_pk_bf16_f32 v80, v84, v85
	v_cvt_pk_bf16_f32 v81, v86, v87
	v_cvt_pk_bf16_f32 v82, v88, v89
	v_cvt_pk_bf16_f32 v83, v90, v91
	global_store_dwordx4 v[98:99], v[80:83], off nt
	global_load_dword v80, v[102:103], off
	s_nop 0
	v_mad_i64_i32 v[82:83], s[36:37], v96, s33, v[146:147]
	v_lshl_add_u64 v[82:83], v[82:83], 0, v[148:149]
	s_waitcnt vmcnt(0)
	v_fmamk_f32 v80, v80, 0x3a800000, v158
	v_rsq_f32_e32 v80, v80
	s_nop 0
	v_pk_mul_f32 v[76:77], v[76:77], v[80:81] op_sel_hi:[1,0]
	v_pk_mul_f32 v[78:79], v[78:79], v[80:81] op_sel_hi:[1,0]
	v_pk_mul_f32 v[72:73], v[72:73], v[80:81] op_sel_hi:[1,0]
	v_pk_mul_f32 v[74:75], v[74:75], v[80:81] op_sel_hi:[1,0]
	v_pk_mul_f32 v[68:69], v[68:69], v[80:81] op_sel_hi:[1,0]
	v_pk_mul_f32 v[70:71], v[70:71], v[80:81] op_sel_hi:[1,0]
	v_pk_mul_f32 v[64:65], v[64:65], v[80:81] op_sel_hi:[1,0]
	v_pk_mul_f32 v[66:67], v[66:67], v[80:81] op_sel_hi:[1,0]
	v_mul_f32_e32 v80, 0xbfb8aa3b, v76
	v_mul_f32_e32 v81, 0xbfb8aa3b, v77
	v_mul_f32_e32 v84, 0xbfb8aa3b, v78
	v_mul_f32_e32 v85, 0xbfb8aa3b, v79
	v_mul_f32_e32 v86, 0xbfb8aa3b, v72
	v_mul_f32_e32 v87, 0xbfb8aa3b, v73
	v_mul_f32_e32 v88, 0xbfb8aa3b, v74
	v_mul_f32_e32 v89, 0xbfb8aa3b, v75
	v_exp_f32_e32 v80, v80
	v_exp_f32_e32 v81, v81
	v_exp_f32_e32 v84, v84
	v_exp_f32_e32 v85, v85
	v_exp_f32_e32 v86, v86
	v_exp_f32_e32 v87, v87
	v_exp_f32_e32 v88, v88
	v_exp_f32_e32 v89, v89
	v_add_f32_e32 v80, 1.0, v80
	v_add_f32_e32 v81, 1.0, v81
	v_add_f32_e32 v84, 1.0, v84
	v_add_f32_e32 v85, 1.0, v85
	v_add_f32_e32 v86, 1.0, v86
	v_add_f32_e32 v87, 1.0, v87
	v_add_f32_e32 v88, 1.0, v88
	v_add_f32_e32 v89, 1.0, v89
	v_rcp_f32_e32 v80, v80
	v_rcp_f32_e32 v81, v81
	v_rcp_f32_e32 v84, v84
	v_rcp_f32_e32 v85, v85
	v_rcp_f32_e32 v86, v86
	v_rcp_f32_e32 v87, v87
	v_rcp_f32_e32 v88, v88
	v_rcp_f32_e32 v89, v89
	v_pk_mul_f32 v[76:77], v[76:77], v[80:81]
	v_pk_mul_f32 v[78:79], v[78:79], v[84:85]
	v_pk_mul_f32 v[72:73], v[72:73], v[86:87]
	v_pk_mul_f32 v[74:75], v[74:75], v[88:89]
	v_pk_mul_f32 v[68:69], v[68:69], v[76:77]
	v_pk_mul_f32 v[70:71], v[70:71], v[78:79]
	v_pk_mul_f32 v[72:73], v[64:65], v[72:73]
	v_pk_mul_f32 v[74:75], v[66:67], v[74:75]
	v_cvt_pk_bf16_f32 v64, v68, v69
	v_cvt_pk_bf16_f32 v65, v70, v71
	v_cvt_pk_bf16_f32 v66, v72, v73
	v_cvt_pk_bf16_f32 v67, v74, v75
	global_store_dwordx4 v[82:83], v[64:67], off nt
	global_load_dword v64, v[150:151], off offset:512
	s_nop 0
	v_add_u32_e32 v65, 0x80, v144
	v_mad_i64_i32 v[66:67], s[36:37], v65, s33, v[146:147]
	v_lshl_add_u64 v[66:67], v[66:67], 0, v[148:149]
	s_waitcnt vmcnt(0)
	v_fmamk_f32 v64, v64, 0x3a800000, v158
	v_rsq_f32_e32 v64, v64
	s_nop 0
	v_pk_mul_f32 v[60:61], v[60:61], v[64:65] op_sel_hi:[1,0]
	v_pk_mul_f32 v[62:63], v[62:63], v[64:65] op_sel_hi:[1,0]
	v_pk_mul_f32 v[56:57], v[56:57], v[64:65] op_sel_hi:[1,0]
	v_pk_mul_f32 v[58:59], v[58:59], v[64:65] op_sel_hi:[1,0]
	v_pk_mul_f32 v[52:53], v[52:53], v[64:65] op_sel_hi:[1,0]
	v_pk_mul_f32 v[54:55], v[54:55], v[64:65] op_sel_hi:[1,0]
	v_pk_mul_f32 v[48:49], v[48:49], v[64:65] op_sel_hi:[1,0]
	v_pk_mul_f32 v[50:51], v[50:51], v[64:65] op_sel_hi:[1,0]
	v_mul_f32_e32 v64, 0xbfb8aa3b, v60
	v_mul_f32_e32 v65, 0xbfb8aa3b, v61
	v_mul_f32_e32 v68, 0xbfb8aa3b, v62
	v_mul_f32_e32 v69, 0xbfb8aa3b, v63
	v_mul_f32_e32 v70, 0xbfb8aa3b, v56
	v_mul_f32_e32 v71, 0xbfb8aa3b, v57
	v_mul_f32_e32 v72, 0xbfb8aa3b, v58
	v_mul_f32_e32 v73, 0xbfb8aa3b, v59
	v_exp_f32_e32 v64, v64
	v_exp_f32_e32 v65, v65
	v_exp_f32_e32 v68, v68
	v_exp_f32_e32 v69, v69
	v_exp_f32_e32 v70, v70
	v_exp_f32_e32 v71, v71
	v_exp_f32_e32 v72, v72
	v_exp_f32_e32 v73, v73
	v_add_f32_e32 v64, 1.0, v64
	v_add_f32_e32 v65, 1.0, v65
	v_add_f32_e32 v68, 1.0, v68
	v_add_f32_e32 v69, 1.0, v69
	v_add_f32_e32 v70, 1.0, v70
	v_add_f32_e32 v71, 1.0, v71
	v_add_f32_e32 v72, 1.0, v72
	v_add_f32_e32 v73, 1.0, v73
	v_rcp_f32_e32 v64, v64
	v_rcp_f32_e32 v65, v65
	v_rcp_f32_e32 v68, v68
	v_rcp_f32_e32 v69, v69
	v_rcp_f32_e32 v70, v70
	v_rcp_f32_e32 v71, v71
	v_rcp_f32_e32 v72, v72
	v_rcp_f32_e32 v73, v73
	v_pk_mul_f32 v[60:61], v[60:61], v[64:65]
	v_pk_mul_f32 v[62:63], v[62:63], v[68:69]
	v_pk_mul_f32 v[56:57], v[56:57], v[70:71]
	v_pk_mul_f32 v[58:59], v[58:59], v[72:73]
	v_pk_mul_f32 v[52:53], v[52:53], v[60:61]
	v_pk_mul_f32 v[54:55], v[54:55], v[62:63]
	v_pk_mul_f32 v[56:57], v[48:49], v[56:57]
	v_pk_mul_f32 v[58:59], v[50:51], v[58:59]
	v_cvt_pk_bf16_f32 v48, v52, v53
	v_cvt_pk_bf16_f32 v49, v54, v55
	v_cvt_pk_bf16_f32 v50, v56, v57
	v_cvt_pk_bf16_f32 v51, v58, v59
	global_store_dwordx4 v[66:67], v[48:51], off nt
	global_load_dword v48, v[150:151], off offset:576
	s_nop 0
	v_add_u32_e32 v49, 0x90, v144
	v_mad_i64_i32 v[50:51], s[36:37], v49, s33, v[146:147]
	v_lshl_add_u64 v[50:51], v[50:51], 0, v[148:149]
	s_waitcnt vmcnt(0)
; __device__ __forceinline__ unsigned cvt_pk_bf16(float lo, float hi) { f32x2_t v = {lo, hi}; bf16x2_t b = __builtin_convertvector(v, bf16x2_t); return __builtin_bit_cast(unsigned, b); }
; __device__ __forceinline__ float rstd_of(const float* ss, int row) { return __builtin_amdgcn_rsqf(ss[row] * (1.0f / 1024.0f) + RMS_EPS); }
; __device__ __forceinline__ float sigmoidf_(float v) { return __builtin_amdgcn_rcpf(1.0f + __builtin_amdgcn_exp2f(-v * LOG2E)); }
; #define PG8_BAR __builtin_amdgcn_s_barrier()
; template <class Epi>
; __device__ __forceinline__ void gemm_phase(LAS unsigned char* lds, const Gemm g, const StaticOrder& S, const Epi& E) {
;     ...
;         if (wr == 0) PG8_BAR;
;         E(acc, cur, wr, wc, fr, fq);
;     __device__ __forceinline__ void operator()(const Acc& acc, const Unit& u, int wr, int wc, int fr, int fq) const {
;         const int row0 = u.pm * BM + wr * 64 + fr, col0 = u.pn * 128 + wc * 32 + 8 * fq;
; #pragma unroll
;         for (int ai = 0; ai < 2; ++ai)
; #pragma unroll
;             for (int m = 0; m < 4; ++m) {
;                 const int row = row0 + ai * HALF + m * 16; const float rs = rstd_of(ss, row);
;                 float o[8];
; #pragma unroll
;                 for (int n = 0; n < 2; ++n)
; #pragma unroll
;                     for (int e = 0; e < 4; ++e) { const float gv = acc[ai][0][m][n][e] * rs, uv = acc[ai][1][m][n][e] * rs; o[4 * n + e] = gv * sigmoidf_(gv) * uv; }
;                 u32x4 w; w.x = cvt_pk_bf16(o[0], o[1]); w.y = cvt_pk_bf16(o[2], o[3]); w.z = cvt_pk_bf16(o[4], o[5]); w.w = cvt_pk_bf16(o[6], o[7]);
;                 *(u32x4*)(H + (size_t)row * FF + col0) = w;
	v_fmamk_f32 v48, v48, 0x3a800000, v158
	v_rsq_f32_e32 v48, v48
	s_nop 0
	v_pk_mul_f32 v[44:45], v[44:45], v[48:49] op_sel_hi:[1,0]
	v_pk_mul_f32 v[46:47], v[46:47], v[48:49] op_sel_hi:[1,0]
	v_pk_mul_f32 v[40:41], v[40:41], v[48:49] op_sel_hi:[1,0]
	v_pk_mul_f32 v[42:43], v[42:43], v[48:49] op_sel_hi:[1,0]
	v_pk_mul_f32 v[36:37], v[36:37], v[48:49] op_sel_hi:[1,0]
	v_pk_mul_f32 v[38:39], v[38:39], v[48:49] op_sel_hi:[1,0]
	v_pk_mul_f32 v[32:33], v[32:33], v[48:49] op_sel_hi:[1,0]
	v_pk_mul_f32 v[34:35], v[34:35], v[48:49] op_sel_hi:[1,0]
	v_mul_f32_e32 v48, 0xbfb8aa3b, v44
	v_mul_f32_e32 v49, 0xbfb8aa3b, v45
	v_mul_f32_e32 v52, 0xbfb8aa3b, v46
	v_mul_f32_e32 v53, 0xbfb8aa3b, v47
	v_mul_f32_e32 v54, 0xbfb8aa3b, v40
	v_mul_f32_e32 v55, 0xbfb8aa3b, v41
	v_mul_f32_e32 v56, 0xbfb8aa3b, v42
	v_mul_f32_e32 v57, 0xbfb8aa3b, v43
	v_exp_f32_e32 v48, v48
	v_exp_f32_e32 v49, v49
	v_exp_f32_e32 v52, v52
	v_exp_f32_e32 v53, v53
	v_exp_f32_e32 v54, v54
	v_exp_f32_e32 v55, v55
	v_exp_f32_e32 v56, v56
	v_exp_f32_e32 v57, v57
	v_add_f32_e32 v48, 1.0, v48
	v_add_f32_e32 v49, 1.0, v49
	v_add_f32_e32 v52, 1.0, v52
	v_add_f32_e32 v53, 1.0, v53
	v_add_f32_e32 v54, 1.0, v54
	v_add_f32_e32 v55, 1.0, v55
	v_add_f32_e32 v56, 1.0, v56
	v_add_f32_e32 v57, 1.0, v57
	v_rcp_f32_e32 v48, v48
	v_rcp_f32_e32 v49, v49
	v_rcp_f32_e32 v52, v52
	v_rcp_f32_e32 v53, v53
	v_rcp_f32_e32 v54, v54
	v_rcp_f32_e32 v55, v55
	v_rcp_f32_e32 v56, v56
	v_rcp_f32_e32 v57, v57
	v_pk_mul_f32 v[44:45], v[44:45], v[48:49]
	v_pk_mul_f32 v[46:47], v[46:47], v[52:53]
	v_pk_mul_f32 v[40:41], v[40:41], v[54:55]
	v_pk_mul_f32 v[42:43], v[42:43], v[56:57]
	v_pk_mul_f32 v[36:37], v[36:37], v[44:45]
	v_pk_mul_f32 v[38:39], v[38:39], v[46:47]
	v_pk_mul_f32 v[40:41], v[32:33], v[40:41]
	v_pk_mul_f32 v[42:43], v[34:35], v[42:43]
	v_cvt_pk_bf16_f32 v32, v36, v37
	v_cvt_pk_bf16_f32 v33, v38, v39
	v_cvt_pk_bf16_f32 v34, v40, v41
	v_cvt_pk_bf16_f32 v35, v42, v43
	global_store_dwordx4 v[50:51], v[32:35], off nt
	global_load_dword v32, v[150:151], off offset:640
	s_nop 0
	v_add_u32_e32 v33, 0xa0, v144
	v_mad_i64_i32 v[34:35], s[36:37], v33, s33, v[146:147]
	v_lshl_add_u64 v[34:35], v[34:35], 0, v[148:149]
	s_waitcnt vmcnt(0)
	v_fmamk_f32 v32, v32, 0x3a800000, v158
	v_rsq_f32_e32 v32, v32
	s_nop 0
	v_pk_mul_f32 v[28:29], v[28:29], v[32:33] op_sel_hi:[1,0]
	v_pk_mul_f32 v[30:31], v[30:31], v[32:33] op_sel_hi:[1,0]
	v_pk_mul_f32 v[24:25], v[24:25], v[32:33] op_sel_hi:[1,0]
	v_pk_mul_f32 v[26:27], v[26:27], v[32:33] op_sel_hi:[1,0]
	v_pk_mul_f32 v[20:21], v[20:21], v[32:33] op_sel_hi:[1,0]
	v_pk_mul_f32 v[22:23], v[22:23], v[32:33] op_sel_hi:[1,0]
	v_pk_mul_f32 v[16:17], v[16:17], v[32:33] op_sel_hi:[1,0]
	v_pk_mul_f32 v[18:19], v[18:19], v[32:33] op_sel_hi:[1,0]
	v_mul_f32_e32 v32, 0xbfb8aa3b, v28
	v_mul_f32_e32 v33, 0xbfb8aa3b, v29
	v_mul_f32_e32 v36, 0xbfb8aa3b, v30
	v_mul_f32_e32 v37, 0xbfb8aa3b, v31
	v_mul_f32_e32 v38, 0xbfb8aa3b, v24
	v_mul_f32_e32 v39, 0xbfb8aa3b, v25
	v_mul_f32_e32 v40, 0xbfb8aa3b, v26
	v_mul_f32_e32 v41, 0xbfb8aa3b, v27
	v_exp_f32_e32 v32, v32
	v_exp_f32_e32 v33, v33
	v_exp_f32_e32 v36, v36
	v_exp_f32_e32 v37, v37
	v_exp_f32_e32 v38, v38
	v_exp_f32_e32 v39, v39
	v_exp_f32_e32 v40, v40
	v_exp_f32_e32 v41, v41
	v_add_f32_e32 v32, 1.0, v32
	v_add_f32_e32 v33, 1.0, v33
	v_add_f32_e32 v36, 1.0, v36
	v_add_f32_e32 v37, 1.0, v37
	v_add_f32_e32 v38, 1.0, v38
	v_add_f32_e32 v39, 1.0, v39
	v_add_f32_e32 v40, 1.0, v40
	v_add_f32_e32 v41, 1.0, v41
	v_rcp_f32_e32 v32, v32
	v_rcp_f32_e32 v33, v33
	v_rcp_f32_e32 v36, v36
	v_rcp_f32_e32 v37, v37
	v_rcp_f32_e32 v38, v38
	v_rcp_f32_e32 v39, v39
	v_rcp_f32_e32 v40, v40
	v_rcp_f32_e32 v41, v41
	v_pk_mul_f32 v[28:29], v[28:29], v[32:33]
	v_pk_mul_f32 v[30:31], v[30:31], v[36:37]
	v_pk_mul_f32 v[24:25], v[24:25], v[38:39]
	v_pk_mul_f32 v[26:27], v[26:27], v[40:41]
	v_pk_mul_f32 v[20:21], v[20:21], v[28:29]
	v_pk_mul_f32 v[22:23], v[22:23], v[30:31]
	v_pk_mul_f32 v[24:25], v[16:17], v[24:25]
	v_pk_mul_f32 v[26:27], v[18:19], v[26:27]
	v_cvt_pk_bf16_f32 v16, v20, v21
	v_cvt_pk_bf16_f32 v17, v22, v23
	v_cvt_pk_bf16_f32 v18, v24, v25
	v_cvt_pk_bf16_f32 v19, v26, v27
	global_store_dwordx4 v[34:35], v[16:19], off nt
	global_load_dword v16, v[150:151], off offset:704
	s_nop 0
	v_add_u32_e32 v17, 0xb0, v144
	v_mad_i64_i32 v[18:19], s[36:37], v17, s33, v[146:147]
	v_lshl_add_u64 v[18:19], v[18:19], 0, v[148:149]
	s_waitcnt vmcnt(0)
	v_fmamk_f32 v16, v16, 0x3a800000, v158
	v_rsq_f32_e32 v16, v16
	s_nop 0
	v_pk_mul_f32 v[12:13], v[12:13], v[16:17] op_sel_hi:[1,0]
	v_pk_mul_f32 v[14:15], v[14:15], v[16:17] op_sel_hi:[1,0]
	v_pk_mul_f32 v[8:9], v[8:9], v[16:17] op_sel_hi:[1,0]
	v_pk_mul_f32 v[10:11], v[10:11], v[16:17] op_sel_hi:[1,0]
	v_pk_mul_f32 v[4:5], v[4:5], v[16:17] op_sel_hi:[1,0]
	v_pk_mul_f32 v[6:7], v[6:7], v[16:17] op_sel_hi:[1,0]
	v_pk_mul_f32 v[0:1], v[0:1], v[16:17] op_sel_hi:[1,0]
	v_pk_mul_f32 v[2:3], v[2:3], v[16:17] op_sel_hi:[1,0]
	v_mul_f32_e32 v16, 0xbfb8aa3b, v12
	v_mul_f32_e32 v17, 0xbfb8aa3b, v13
	v_mul_f32_e32 v20, 0xbfb8aa3b, v14
	v_mul_f32_e32 v21, 0xbfb8aa3b, v15
	v_mul_f32_e32 v22, 0xbfb8aa3b, v8
	v_mul_f32_e32 v23, 0xbfb8aa3b, v9
	v_mul_f32_e32 v24, 0xbfb8aa3b, v10
	v_mul_f32_e32 v25, 0xbfb8aa3b, v11
	v_exp_f32_e32 v16, v16
	v_exp_f32_e32 v17, v17
	v_exp_f32_e32 v20, v20
	v_exp_f32_e32 v21, v21
	v_exp_f32_e32 v22, v22
	v_exp_f32_e32 v23, v23
	v_exp_f32_e32 v24, v24
	v_exp_f32_e32 v25, v25
	v_add_f32_e32 v16, 1.0, v16
	v_add_f32_e32 v17, 1.0, v17
	v_add_f32_e32 v20, 1.0, v20
	v_add_f32_e32 v21, 1.0, v21
	v_add_f32_e32 v22, 1.0, v22
	v_add_f32_e32 v23, 1.0, v23
	v_add_f32_e32 v24, 1.0, v24
	v_add_f32_e32 v25, 1.0, v25
	v_rcp_f32_e32 v16, v16
	v_rcp_f32_e32 v17, v17
	v_rcp_f32_e32 v20, v20
	v_rcp_f32_e32 v21, v21
	v_rcp_f32_e32 v22, v22
	v_rcp_f32_e32 v23, v23
	v_rcp_f32_e32 v24, v24
	v_rcp_f32_e32 v25, v25
	v_pk_mul_f32 v[12:13], v[12:13], v[16:17]
	v_pk_mul_f32 v[14:15], v[14:15], v[20:21]
	v_pk_mul_f32 v[8:9], v[8:9], v[22:23]
	v_pk_mul_f32 v[10:11], v[10:11], v[24:25]
	v_pk_mul_f32 v[4:5], v[4:5], v[12:13]
	v_pk_mul_f32 v[6:7], v[6:7], v[14:15]
	v_pk_mul_f32 v[8:9], v[0:1], v[8:9]
	v_pk_mul_f32 v[10:11], v[2:3], v[10:11]
	v_cvt_pk_bf16_f32 v0, v4, v5
	v_cvt_pk_bf16_f32 v1, v6, v7
	v_cvt_pk_bf16_f32 v2, v8, v9
	v_cvt_pk_bf16_f32 v3, v10, v11
	global_store_dwordx4 v[18:19], v[0:3], off nt
	s_cbranch_vccnz .LBB0_1346
	s_andn2_b64 vcc, exec, s[8:9]
	s_cbranch_vccnz .LBB0_1345
	s_barrier
	s_branch .LBB0_1345
